# mid_sgu: 16 spatial-gating weight fragment loads issued together before the MFMA K loop (was 8 serialized load/wait round trips), loop unrolled
# baseline (speedup 1.0000x reference)
.LBB0_277:
	s_lshl_b32 s11, s10, 7
	v_add_u32_e32 v4, s11, v102
	v_mad_i64_i32 v[2:3], s[14:15], v4, s55, v[76:77]
	global_load_dwordx4 v[62:65], v[2:3], off offset:1536 nt
	global_load_dwordx4 v[58:61], v[2:3], off offset:2048 nt
	v_add_u32_e32 v2, 16, v4
	v_mad_i64_i32 v[2:3], s[14:15], v2, s55, v[76:77]
	global_load_dwordx4 v[54:57], v[2:3], off offset:1536 nt
	global_load_dwordx4 v[50:53], v[2:3], off offset:2048 nt
	v_add_u32_e32 v2, 32, v4
	v_mad_i64_i32 v[2:3], s[14:15], v2, s55, v[76:77]
	global_load_dwordx4 v[46:49], v[2:3], off offset:1536 nt
	global_load_dwordx4 v[42:45], v[2:3], off offset:2048 nt
	v_add_u32_e32 v2, 48, v4
	v_mad_i64_i32 v[2:3], s[14:15], v2, s55, v[76:77]
	global_load_dwordx4 v[38:41], v[2:3], off offset:1536 nt
	global_load_dwordx4 v[34:37], v[2:3], off offset:2048 nt
	v_add_u32_e32 v2, 64, v4
	v_mad_i64_i32 v[2:3], s[14:15], v2, s55, v[76:77]
	global_load_dwordx4 v[30:33], v[2:3], off offset:1536 nt
	global_load_dwordx4 v[26:29], v[2:3], off offset:2048 nt
	v_add_u32_e32 v2, 0x50, v4
	v_mad_i64_i32 v[2:3], s[14:15], v2, s55, v[76:77]
	global_load_dwordx4 v[22:25], v[2:3], off offset:1536 nt
	global_load_dwordx4 v[18:21], v[2:3], off offset:2048 nt
	v_add_u32_e32 v2, 0x60, v4
	v_mad_i64_i32 v[2:3], s[14:15], v2, s55, v[76:77]
	global_load_dwordx4 v[14:17], v[2:3], off offset:1536 nt
	global_load_dwordx4 v[10:13], v[2:3], off offset:2048 nt
	v_add_u32_e32 v2, 0x70, v4
	v_mad_i64_i32 v[2:3], s[14:15], v2, s55, v[76:77]
	global_load_dwordx4 v[6:9], v[2:3], off offset:1536 nt
	s_nop 0
	global_load_dwordx4 v[2:5], v[2:3], off offset:2048 nt
	s_mov_b32 s5, 0
	s_waitcnt vmcnt(0)
	v_lshlrev_b32_e32 v98, 16, v62
	v_mul_f32_e32 v99, 0x3d372713, v98
	v_mul_f32_e32 v99, v99, v98
	v_fma_f32 v99, v99, v98, v98
	v_mul_f32_e32 v99, 0x3f4c422a, v99
	v_add_f32_e32 v99, v99, v99
	v_mul_f32_e32 v99, 0x3fb8aa3b, v99
	v_exp_f32_e32 v99, v99
	v_mul_f32_e32 v98, 0.5, v98
	v_and_b32_e32 v62, 0xffff0000, v62
	v_add_f32_e32 v99, 1.0, v99
	v_div_scale_f32 v100, s[14:15], v99, v99, 2.0
	v_rcp_f32_e32 v101, v100
	s_nop 0
	v_fma_f32 v115, -v100, v101, 1.0
	v_fmac_f32_e32 v101, v115, v101
	v_div_scale_f32 v115, vcc, 2.0, v99, 2.0
	v_mul_f32_e32 v116, v115, v101
	v_fma_f32 v117, -v100, v116, v115
	v_fmac_f32_e32 v116, v117, v101
	v_fma_f32 v100, -v100, v116, v115
	v_div_fmas_f32 v100, v100, v101, v116
	v_div_fixup_f32 v99, v100, v99, 2.0
	v_sub_f32_e32 v99, 1.0, v99
	v_add_f32_e32 v99, 1.0, v99
	v_mul_f32_e32 v98, v98, v99
	v_mul_f32_e32 v99, 0x3d372713, v62
	v_mul_f32_e32 v99, v99, v62
	v_fma_f32 v99, v99, v62, v62
	v_mul_f32_e32 v99, 0x3f4c422a, v99
	v_add_f32_e32 v99, v99, v99
	v_mul_f32_e32 v99, 0x3fb8aa3b, v99
	v_exp_f32_e32 v99, v99
	v_mul_f32_e32 v62, 0.5, v62
	v_add_f32_e32 v99, 1.0, v99
	v_div_scale_f32 v100, s[14:15], v99, v99, 2.0
	v_rcp_f32_e32 v101, v100
	s_nop 0
	v_fma_f32 v115, -v100, v101, 1.0
	v_fmac_f32_e32 v101, v115, v101
	v_div_scale_f32 v115, vcc, 2.0, v99, 2.0
	v_mul_f32_e32 v116, v115, v101
	v_fma_f32 v117, -v100, v116, v115
	v_fmac_f32_e32 v116, v117, v101
	v_fma_f32 v100, -v100, v116, v115
	v_div_fmas_f32 v100, v100, v101, v116
	v_div_fixup_f32 v99, v100, v99, 2.0
	v_sub_f32_e32 v99, 1.0, v99
	v_add_f32_e32 v99, 1.0, v99
	v_mul_f32_e32 v99, v62, v99
	v_lshlrev_b32_e32 v62, 16, v58
	v_mul_f32_e32 v100, 0x3d372713, v62
	v_mul_f32_e32 v100, v100, v62
	v_fma_f32 v100, v100, v62, v62
	v_mul_f32_e32 v100, 0x3f4c422a, v100
	v_add_f32_e32 v100, v100, v100
	v_mul_f32_e32 v100, 0x3fb8aa3b, v100
	v_exp_f32_e32 v100, v100
	v_mul_f32_e32 v62, 0.5, v62
	v_and_b32_e32 v58, 0xffff0000, v58
	v_cvt_pk_bf16_f32 v98, v98, v99
	v_add_f32_e32 v100, 1.0, v100
	v_div_scale_f32 v101, s[14:15], v100, v100, 2.0
	v_rcp_f32_e32 v115, v101
	s_nop 0
	v_fma_f32 v116, -v101, v115, 1.0
	v_fmac_f32_e32 v115, v116, v115
	v_div_scale_f32 v116, vcc, 2.0, v100, 2.0
	v_mul_f32_e32 v117, v116, v115
	v_fma_f32 v118, -v101, v117, v116
	v_fmac_f32_e32 v117, v118, v115
	v_fma_f32 v101, -v101, v117, v116
	v_div_fmas_f32 v101, v101, v115, v117
	v_div_fixup_f32 v100, v101, v100, 2.0
	v_sub_f32_e32 v100, 1.0, v100
	v_add_f32_e32 v100, 1.0, v100
	v_mul_f32_e32 v100, v62, v100
	v_mul_f32_e32 v62, 0x3d372713, v58
	v_mul_f32_e32 v62, v62, v58
	v_fma_f32 v62, v62, v58, v58
	v_mul_f32_e32 v62, 0x3f4c422a, v62
	v_add_f32_e32 v62, v62, v62
	v_mul_f32_e32 v62, 0x3fb8aa3b, v62
	v_exp_f32_e32 v62, v62
	v_mul_f32_e32 v58, 0.5, v58
	v_add_f32_e32 v62, 1.0, v62
	v_div_scale_f32 v101, s[14:15], v62, v62, 2.0
	v_rcp_f32_e32 v115, v101
	s_nop 0
	v_fma_f32 v116, -v101, v115, 1.0
	v_fmac_f32_e32 v115, v116, v115
	v_div_scale_f32 v116, vcc, 2.0, v62, 2.0
	v_mul_f32_e32 v117, v116, v115
	v_fma_f32 v118, -v101, v117, v116
	v_fmac_f32_e32 v117, v118, v115
	v_fma_f32 v101, -v101, v117, v116
	v_div_fmas_f32 v101, v101, v115, v117
	v_div_fixup_f32 v62, v101, v62, 2.0
	v_sub_f32_e32 v62, 1.0, v62
	v_add_f32_e32 v62, 1.0, v62
	v_mul_f32_e32 v101, v58, v62
	v_lshlrev_b32_e32 v58, 16, v63
	v_mul_f32_e32 v62, 0x3d372713, v58
	v_mul_f32_e32 v62, v62, v58
	v_fma_f32 v62, v62, v58, v58
	v_mul_f32_e32 v62, 0x3f4c422a, v62
	v_add_f32_e32 v62, v62, v62
	v_mul_f32_e32 v62, 0x3fb8aa3b, v62
	v_exp_f32_e32 v62, v62
	v_mul_f32_e32 v58, 0.5, v58
	v_add_f32_e32 v62, 1.0, v62
	v_div_scale_f32 v115, s[14:15], v62, v62, 2.0
	v_rcp_f32_e32 v116, v115
	s_nop 0
	v_fma_f32 v117, -v115, v116, 1.0
	v_fmac_f32_e32 v116, v117, v116
	v_div_scale_f32 v117, vcc, 2.0, v62, 2.0
	v_mul_f32_e32 v118, v117, v116
	v_fma_f32 v119, -v115, v118, v117
	v_fmac_f32_e32 v118, v119, v116
	v_fma_f32 v115, -v115, v118, v117
	v_div_fmas_f32 v115, v115, v116, v118
	v_div_fixup_f32 v62, v115, v62, 2.0
	v_sub_f32_e32 v62, 1.0, v62
	v_add_f32_e32 v62, 1.0, v62
	v_mul_f32_e32 v115, v58, v62
	v_and_b32_e32 v58, 0xffff0000, v63
	v_mul_f32_e32 v62, 0x3d372713, v58
	v_mul_f32_e32 v62, v62, v58
	v_fma_f32 v62, v62, v58, v58
	v_mul_f32_e32 v62, 0x3f4c422a, v62
	v_add_f32_e32 v62, v62, v62
	v_mul_f32_e32 v62, 0x3fb8aa3b, v62
	v_exp_f32_e32 v62, v62
	v_mul_f32_e32 v58, 0.5, v58
	v_add_f32_e32 v62, 1.0, v62
	v_div_scale_f32 v63, s[14:15], v62, v62, 2.0
	v_rcp_f32_e32 v116, v63
	s_nop 0
	v_fma_f32 v117, -v63, v116, 1.0
	v_fmac_f32_e32 v116, v117, v116
	v_div_scale_f32 v117, vcc, 2.0, v62, 2.0
	v_mul_f32_e32 v118, v117, v116
	v_fma_f32 v119, -v63, v118, v117
	v_fmac_f32_e32 v118, v119, v116
	v_fma_f32 v63, -v63, v118, v117
	v_div_fmas_f32 v63, v63, v116, v118
	v_div_fixup_f32 v62, v63, v62, 2.0
	v_sub_f32_e32 v62, 1.0, v62
	v_add_f32_e32 v62, 1.0, v62
	v_mul_f32_e32 v116, v58, v62
	v_lshlrev_b32_e32 v58, 16, v64
	v_mul_f32_e32 v62, 0x3d372713, v58
	v_mul_f32_e32 v62, v62, v58
	v_fma_f32 v62, v62, v58, v58
	v_mul_f32_e32 v62, 0x3f4c422a, v62
	v_add_f32_e32 v62, v62, v62
	v_mul_f32_e32 v62, 0x3fb8aa3b, v62
	v_exp_f32_e32 v62, v62
	v_mul_f32_e32 v58, 0.5, v58
	v_add_f32_e32 v62, 1.0, v62
	v_div_scale_f32 v63, s[14:15], v62, v62, 2.0
	v_rcp_f32_e32 v117, v63
	s_nop 0
	v_fma_f32 v118, -v63, v117, 1.0
	v_fmac_f32_e32 v117, v118, v117
	v_div_scale_f32 v118, vcc, 2.0, v62, 2.0
	v_mul_f32_e32 v119, v118, v117
	v_fma_f32 v120, -v63, v119, v118
	v_fmac_f32_e32 v119, v120, v117
	v_fma_f32 v63, -v63, v119, v118
	v_div_fmas_f32 v63, v63, v117, v119
	v_div_fixup_f32 v62, v63, v62, 2.0
	v_sub_f32_e32 v62, 1.0, v62
	v_add_f32_e32 v62, 1.0, v62
	v_mul_f32_e32 v117, v58, v62
	v_and_b32_e32 v58, 0xffff0000, v64
	v_mul_f32_e32 v62, 0x3d372713, v58
	v_mul_f32_e32 v62, v62, v58
	v_fma_f32 v62, v62, v58, v58
	v_mul_f32_e32 v62, 0x3f4c422a, v62
	v_add_f32_e32 v62, v62, v62
	v_mul_f32_e32 v62, 0x3fb8aa3b, v62
	v_exp_f32_e32 v62, v62
	v_mul_f32_e32 v58, 0.5, v58
	v_add_f32_e32 v62, 1.0, v62
	v_div_scale_f32 v63, s[14:15], v62, v62, 2.0
	v_rcp_f32_e32 v64, v63
	s_nop 0
	v_fma_f32 v118, -v63, v64, 1.0
	v_fmac_f32_e32 v64, v118, v64
	v_div_scale_f32 v118, vcc, 2.0, v62, 2.0
	v_mul_f32_e32 v119, v118, v64
	v_fma_f32 v120, -v63, v119, v118
	v_fmac_f32_e32 v119, v120, v64
	v_fma_f32 v63, -v63, v119, v118
	v_div_fmas_f32 v63, v63, v64, v119
	v_div_fixup_f32 v62, v63, v62, 2.0
	v_sub_f32_e32 v62, 1.0, v62
	v_add_f32_e32 v62, 1.0, v62
	v_mul_f32_e32 v64, v58, v62
	v_lshlrev_b32_e32 v58, 16, v65
	v_mul_f32_e32 v62, 0x3d372713, v58
	v_mul_f32_e32 v62, v62, v58
	v_fma_f32 v62, v62, v58, v58
	v_mul_f32_e32 v62, 0x3f4c422a, v62
	v_add_f32_e32 v62, v62, v62
	v_mul_f32_e32 v62, 0x3fb8aa3b, v62
	v_exp_f32_e32 v62, v62
	v_mul_f32_e32 v58, 0.5, v58
	v_add_f32_e32 v62, 1.0, v62
	v_div_scale_f32 v63, s[14:15], v62, v62, 2.0
	v_rcp_f32_e32 v118, v63
	s_nop 0
	v_fma_f32 v119, -v63, v118, 1.0
	v_fmac_f32_e32 v118, v119, v118
	v_div_scale_f32 v119, vcc, 2.0, v62, 2.0
	v_mul_f32_e32 v120, v119, v118
	v_fma_f32 v121, -v63, v120, v119
	v_fmac_f32_e32 v120, v121, v118
	v_fma_f32 v63, -v63, v120, v119
	v_div_fmas_f32 v63, v63, v118, v120
	v_div_fixup_f32 v62, v63, v62, 2.0
	v_sub_f32_e32 v62, 1.0, v62
	v_add_f32_e32 v62, 1.0, v62
	v_mul_f32_e32 v118, v58, v62
	v_and_b32_e32 v58, 0xffff0000, v65
	v_mul_f32_e32 v62, 0x3d372713, v58
	v_mul_f32_e32 v62, v62, v58
	v_fma_f32 v62, v62, v58, v58
	v_mul_f32_e32 v62, 0x3f4c422a, v62
	v_add_f32_e32 v62, v62, v62
	v_mul_f32_e32 v62, 0x3fb8aa3b, v62
	v_exp_f32_e32 v62, v62
	v_mul_f32_e32 v58, 0.5, v58
	v_add_f32_e32 v62, 1.0, v62
	v_div_scale_f32 v63, s[14:15], v62, v62, 2.0
	v_rcp_f32_e32 v65, v63
	s_nop 0
	v_fma_f32 v119, -v63, v65, 1.0
	v_fmac_f32_e32 v65, v119, v65
	v_div_scale_f32 v119, vcc, 2.0, v62, 2.0
	v_mul_f32_e32 v120, v119, v65
	v_fma_f32 v121, -v63, v120, v119
	v_fmac_f32_e32 v120, v121, v65
	v_fma_f32 v63, -v63, v120, v119
	v_div_fmas_f32 v63, v63, v65, v120
	v_div_fixup_f32 v62, v63, v62, 2.0
	v_sub_f32_e32 v62, 1.0, v62
	v_add_f32_e32 v62, 1.0, v62
	v_mul_f32_e32 v65, v58, v62
	v_and_b32_e32 v58, 0xffff0000, v59
	v_lshlrev_b32_e32 v59, 16, v59
	v_mul_f32_e32 v62, 0x3d372713, v59
	v_mul_f32_e32 v62, v62, v59
	v_mov_b32_e32 v63, v59
	v_fmac_f32_e32 v63, v62, v63
	v_mul_f32_e32 v62, 0x3f4c422a, v63
	v_add_f32_e32 v62, v62, v62
	v_mul_f32_e32 v62, 0x3fb8aa3b, v62
	v_exp_f32_e32 v63, v62
	v_mul_f32_e32 v62, 0x3d372713, v58
	v_mul_f32_e32 v62, v62, v58
	v_mov_b32_e32 v120, v58
	v_fmac_f32_e32 v120, v62, v120
	v_mul_f32_e32 v62, 0x3f4c422a, v120
	v_add_f32_e32 v62, v62, v62
	v_mul_f32_e32 v62, 0x3fb8aa3b, v62
	v_exp_f32_e32 v62, v62
	v_pk_mul_f32 v[58:59], v[58:59], 0.5 op_sel_hi:[1,0]
	v_mul_f32_e32 v119, v101, v101
	v_fmac_f32_e32 v119, v100, v100
	v_pk_add_f32 v[62:63], v[62:63], 1.0 op_sel_hi:[1,0]
	s_nop 0
	v_div_scale_f32 v120, s[14:15], v63, v63, 2.0
	v_rcp_f32_e32 v121, v120
	s_nop 0
	v_fma_f32 v122, -v120, v121, 1.0
	v_fmac_f32_e32 v121, v122, v121
	v_div_scale_f32 v122, vcc, 2.0, v63, 2.0
	v_mul_f32_e32 v123, v122, v121
	v_fma_f32 v124, -v120, v123, v122
	v_fmac_f32_e32 v123, v124, v121
	v_fma_f32 v120, -v120, v123, v122
	v_div_fmas_f32 v120, v120, v121, v123
	v_div_fixup_f32 v63, v120, v63, 2.0
	v_div_scale_f32 v120, s[14:15], v62, v62, 2.0
	v_rcp_f32_e32 v121, v120
	s_nop 0
	v_fma_f32 v122, -v120, v121, 1.0
	v_fmac_f32_e32 v121, v122, v121
	v_div_scale_f32 v122, vcc, 2.0, v62, 2.0
	v_mul_f32_e32 v123, v122, v121
	v_fma_f32 v124, -v120, v123, v122
	v_fmac_f32_e32 v123, v124, v121
	v_fma_f32 v120, -v120, v123, v122
	v_div_fmas_f32 v120, v120, v121, v123
	v_div_fixup_f32 v62, v120, v62, 2.0
	v_pk_add_f32 v[62:63], v[62:63], 1.0 op_sel_hi:[1,0] neg_lo:[1,0] neg_hi:[1,0]
	s_nop 0
	v_pk_add_f32 v[62:63], v[62:63], 1.0 op_sel_hi:[1,0]
	s_nop 0
	v_pk_mul_f32 v[58:59], v[58:59], v[62:63]
	s_nop 0
	v_pk_mul_f32 v[62:63], v[58:59], v[58:59]
	s_nop 0
	v_add_f32_e32 v63, v63, v119
	v_add_f32_e32 v119, v62, v63
	v_lshlrev_b32_e32 v63, 16, v60
	v_and_b32_e32 v62, 0xffff0000, v60
	v_mul_f32_e32 v60, 0x3d372713, v63
	v_mul_f32_e32 v60, v60, v63
	v_mov_b32_e32 v120, v63
	v_fmac_f32_e32 v120, v60, v120
	v_mul_f32_e32 v60, 0x3f4c422a, v120
	v_add_f32_e32 v60, v60, v60
	v_mul_f32_e32 v60, 0x3fb8aa3b, v60
	v_exp_f32_e32 v121, v60
	v_mul_f32_e32 v60, 0x3d372713, v62
	v_mul_f32_e32 v60, v60, v62
	v_mov_b32_e32 v120, v62
	v_fmac_f32_e32 v120, v60, v120
	v_mul_f32_e32 v60, 0x3f4c422a, v120
	v_add_f32_e32 v60, v60, v60
	v_mul_f32_e32 v60, 0x3fb8aa3b, v60
	v_exp_f32_e32 v120, v60
	v_pk_mul_f32 v[62:63], v[62:63], 0.5 op_sel_hi:[1,0]
	v_pk_add_f32 v[120:121], v[120:121], 1.0 op_sel_hi:[1,0]
	s_nop 0
	v_div_scale_f32 v60, s[14:15], v121, v121, 2.0
	v_rcp_f32_e32 v122, v60
	s_nop 0
	v_fma_f32 v123, -v60, v122, 1.0
	v_fmac_f32_e32 v122, v123, v122
	v_div_scale_f32 v123, vcc, 2.0, v121, 2.0
	v_mul_f32_e32 v124, v123, v122
	v_fma_f32 v125, -v60, v124, v123
	v_fmac_f32_e32 v124, v125, v122
	v_fma_f32 v60, -v60, v124, v123
	v_div_fmas_f32 v60, v60, v122, v124
	v_div_fixup_f32 v121, v60, v121, 2.0
	v_div_scale_f32 v60, s[14:15], v120, v120, 2.0
	v_rcp_f32_e32 v122, v60
	s_nop 0
	v_fma_f32 v123, -v60, v122, 1.0
	v_fmac_f32_e32 v122, v123, v122
	v_div_scale_f32 v123, vcc, 2.0, v120, 2.0
	v_mul_f32_e32 v124, v123, v122
	v_fma_f32 v125, -v60, v124, v123
	v_fmac_f32_e32 v124, v125, v122
	v_fma_f32 v60, -v60, v124, v123
	v_div_fmas_f32 v60, v60, v122, v124
	v_div_fixup_f32 v120, v60, v120, 2.0
	v_pk_add_f32 v[120:121], v[120:121], 1.0 op_sel_hi:[1,0] neg_lo:[1,0] neg_hi:[1,0]
	s_nop 0
	v_pk_add_f32 v[120:121], v[120:121], 1.0 op_sel_hi:[1,0]
	s_nop 0
	v_pk_mul_f32 v[62:63], v[62:63], v[120:121]
	s_nop 0
	v_pk_mul_f32 v[120:121], v[62:63], v[62:63]
	s_nop 0
	v_add_f32_e32 v60, v121, v119
	v_add_f32_e32 v119, v120, v60
	v_and_b32_e32 v60, 0xffff0000, v61
	v_lshlrev_b32_e32 v61, 16, v61
	v_mul_f32_e32 v120, 0x3d372713, v61
	v_mul_f32_e32 v120, v120, v61
	v_mov_b32_e32 v121, v61
	v_fmac_f32_e32 v121, v120, v121
	v_mul_f32_e32 v120, 0x3f4c422a, v121
	v_add_f32_e32 v120, v120, v120
	v_mul_f32_e32 v120, 0x3fb8aa3b, v120
	v_exp_f32_e32 v121, v120
	v_mul_f32_e32 v120, 0x3d372713, v60
	v_mul_f32_e32 v120, v120, v60
	v_mov_b32_e32 v122, v60
	v_fmac_f32_e32 v122, v120, v122
	v_mul_f32_e32 v120, 0x3f4c422a, v122
	v_add_f32_e32 v120, v120, v120
	v_mul_f32_e32 v120, 0x3fb8aa3b, v120
	v_exp_f32_e32 v120, v120
	v_pk_mul_f32 v[60:61], v[60:61], 0.5 op_sel_hi:[1,0]
	v_pk_add_f32 v[120:121], v[120:121], 1.0 op_sel_hi:[1,0]
	s_nop 0
	v_div_scale_f32 v122, s[14:15], v121, v121, 2.0
	v_rcp_f32_e32 v123, v122
	s_nop 0
	v_fma_f32 v124, -v122, v123, 1.0
	v_fmac_f32_e32 v123, v124, v123
	v_div_scale_f32 v124, vcc, 2.0, v121, 2.0
	v_mul_f32_e32 v125, v124, v123
	v_fma_f32 v126, -v122, v125, v124
	v_fmac_f32_e32 v125, v126, v123
	v_fma_f32 v122, -v122, v125, v124
	v_div_fmas_f32 v122, v122, v123, v125
	v_div_fixup_f32 v121, v122, v121, 2.0
	v_div_scale_f32 v122, s[14:15], v120, v120, 2.0
	v_rcp_f32_e32 v123, v122
	s_nop 0
	v_fma_f32 v124, -v122, v123, 1.0
	v_fmac_f32_e32 v123, v124, v123
	v_div_scale_f32 v124, vcc, 2.0, v120, 2.0
	v_mul_f32_e32 v125, v124, v123
	v_fma_f32 v126, -v122, v125, v124
	v_fmac_f32_e32 v125, v126, v123
	v_fma_f32 v122, -v122, v125, v124
	v_div_fmas_f32 v122, v122, v123, v125
	v_div_fixup_f32 v120, v122, v120, 2.0
	v_pk_add_f32 v[120:121], v[120:121], 1.0 op_sel_hi:[1,0] neg_lo:[1,0] neg_hi:[1,0]
	s_nop 0
	v_pk_add_f32 v[120:121], v[120:121], 1.0 op_sel_hi:[1,0]
	s_nop 0
	v_pk_mul_f32 v[120:121], v[60:61], v[120:121]
	s_nop 0
	v_pk_mul_f32 v[60:61], v[120:121], v[120:121]
	s_nop 0
	v_add_f32_e32 v61, v61, v119
	v_add_f32_e32 v60, v60, v61
	ds_bpermute_b32 v61, v106, v60
	s_waitcnt lgkmcnt(0)
	v_add_f32_e32 v60, v60, v61
	ds_bpermute_b32 v61, v107, v60
	s_waitcnt lgkmcnt(0)
	v_add_f32_e32 v60, v60, v61
	ds_bpermute_b32 v61, v108, v60
	s_waitcnt lgkmcnt(0)
	v_add_f32_e32 v60, v60, v61
	ds_bpermute_b32 v61, v109, v60
	s_waitcnt lgkmcnt(0)
	v_add_f32_e32 v60, v60, v61
	ds_bpermute_b32 v61, v110, v60
	s_waitcnt lgkmcnt(0)
	v_add_f32_e32 v60, v60, v61
	v_fmamk_f32 v60, v60, 0x3b800000, v243
	v_cmp_gt_f32_e32 vcc, s3, v60
	v_mul_f32_e32 v61, 0x4b800000, v60
	s_nop 0
	v_cndmask_b32_e32 v60, v60, v61, vcc
	v_rsq_f32_e32 v60, v60
	s_nop 0
	v_mul_f32_e32 v61, 0x45800000, v60
	v_cndmask_b32_e32 v119, v60, v61, vcc
	v_mul_f32_e32 v60, v100, v119
	v_mul_f32_e32 v61, v101, v119
	v_mul_f32_e32 v58, v58, v119
	v_mul_f32_e32 v60, v70, v60
	v_mul_f32_e32 v61, v71, v61
	v_mul_f32_e32 v59, v59, v119
	v_mul_f32_e32 v58, v73, v58
	v_cvt_pk_bf16_f32 v60, v60, v61
	v_cvt_pk_bf16_f32 v99, v115, v116
	v_mul_f32_e32 v59, v72, v59
	v_cvt_pk_bf16_f32 v61, v59, v58
	v_mul_f32_e32 v58, v63, v119
	v_mul_f32_e32 v58, v66, v58
	v_mul_f32_e32 v59, v62, v119
	v_cvt_pk_bf16_f32 v100, v117, v64
	v_mul_f32_e32 v59, v67, v59
	v_cvt_pk_bf16_f32 v62, v58, v59
	v_mul_f32_e32 v58, v121, v119
	v_mul_f32_e32 v58, v68, v58
	v_mul_f32_e32 v59, v120, v119
	v_cvt_pk_bf16_f32 v101, v118, v65
	v_mul_f32_e32 v59, v69, v59
	v_cvt_pk_bf16_f32 v63, v58, v59
	v_lshlrev_b32_e32 v58, 16, v54
	v_mul_f32_e32 v59, 0x3d372713, v58
	v_mul_f32_e32 v59, v59, v58
	v_fma_f32 v59, v59, v58, v58
	v_mul_f32_e32 v59, 0x3f4c422a, v59
	v_add_f32_e32 v59, v59, v59
	v_mul_f32_e32 v59, 0x3fb8aa3b, v59
	v_exp_f32_e32 v59, v59
	ds_write_b128 v111, v[98:101]
	ds_write_b128 v112, v[60:63]
	v_mul_f32_e32 v58, 0.5, v58
	v_and_b32_e32 v54, 0xffff0000, v54
	v_add_f32_e32 v59, 1.0, v59
	v_div_scale_f32 v60, s[14:15], v59, v59, 2.0
	v_rcp_f32_e32 v61, v60
	s_nop 0
	v_fma_f32 v62, -v60, v61, 1.0
	v_fmac_f32_e32 v61, v62, v61
	v_div_scale_f32 v62, vcc, 2.0, v59, 2.0
	v_mul_f32_e32 v63, v62, v61
	v_fma_f32 v64, -v60, v63, v62
	v_fmac_f32_e32 v63, v64, v61
	v_fma_f32 v60, -v60, v63, v62
	v_div_fmas_f32 v60, v60, v61, v63
	v_div_fixup_f32 v59, v60, v59, 2.0
	v_sub_f32_e32 v59, 1.0, v59
	v_add_f32_e32 v59, 1.0, v59
	v_mul_f32_e32 v58, v58, v59
	v_mul_f32_e32 v59, 0x3d372713, v54
	v_mul_f32_e32 v59, v59, v54
	v_fma_f32 v59, v59, v54, v54
	v_mul_f32_e32 v59, 0x3f4c422a, v59
	v_add_f32_e32 v59, v59, v59
	v_mul_f32_e32 v59, 0x3fb8aa3b, v59
	v_exp_f32_e32 v59, v59
	v_mul_f32_e32 v54, 0.5, v54
	v_add_f32_e32 v59, 1.0, v59
	v_div_scale_f32 v60, s[14:15], v59, v59, 2.0
	v_rcp_f32_e32 v61, v60
	s_nop 0
	v_fma_f32 v62, -v60, v61, 1.0
	v_fmac_f32_e32 v61, v62, v61
	v_div_scale_f32 v62, vcc, 2.0, v59, 2.0
	v_mul_f32_e32 v63, v62, v61
	v_fma_f32 v64, -v60, v63, v62
	v_fmac_f32_e32 v63, v64, v61
	v_fma_f32 v60, -v60, v63, v62
	v_div_fmas_f32 v60, v60, v61, v63
	v_div_fixup_f32 v59, v60, v59, 2.0
	v_sub_f32_e32 v59, 1.0, v59
	v_add_f32_e32 v59, 1.0, v59
	v_mul_f32_e32 v59, v54, v59
	v_lshlrev_b32_e32 v54, 16, v50
	v_mul_f32_e32 v60, 0x3d372713, v54
	v_mul_f32_e32 v60, v60, v54
	v_fma_f32 v60, v60, v54, v54
	v_mul_f32_e32 v60, 0x3f4c422a, v60
	v_add_f32_e32 v60, v60, v60
	v_mul_f32_e32 v60, 0x3fb8aa3b, v60
	v_exp_f32_e32 v60, v60
	v_mul_f32_e32 v54, 0.5, v54
	v_and_b32_e32 v50, 0xffff0000, v50
	v_cvt_pk_bf16_f32 v58, v58, v59
	v_add_f32_e32 v60, 1.0, v60
	v_div_scale_f32 v61, s[14:15], v60, v60, 2.0
	v_rcp_f32_e32 v62, v61
	s_nop 0
	v_fma_f32 v63, -v61, v62, 1.0
	v_fmac_f32_e32 v62, v63, v62
	v_div_scale_f32 v63, vcc, 2.0, v60, 2.0
	v_mul_f32_e32 v64, v63, v62
	v_fma_f32 v65, -v61, v64, v63
	v_fmac_f32_e32 v64, v65, v62
	v_fma_f32 v61, -v61, v64, v63
	v_div_fmas_f32 v61, v61, v62, v64
	v_div_fixup_f32 v60, v61, v60, 2.0
	v_sub_f32_e32 v60, 1.0, v60
	v_add_f32_e32 v60, 1.0, v60
	v_mul_f32_e32 v60, v54, v60
	v_mul_f32_e32 v54, 0x3d372713, v50
	v_mul_f32_e32 v54, v54, v50
	v_fma_f32 v54, v54, v50, v50
	v_mul_f32_e32 v54, 0x3f4c422a, v54
	v_add_f32_e32 v54, v54, v54
	v_mul_f32_e32 v54, 0x3fb8aa3b, v54
	v_exp_f32_e32 v54, v54
	v_mul_f32_e32 v50, 0.5, v50
	v_add_f32_e32 v54, 1.0, v54
	v_div_scale_f32 v61, s[14:15], v54, v54, 2.0
	v_rcp_f32_e32 v62, v61
	s_nop 0
	v_fma_f32 v63, -v61, v62, 1.0
	v_fmac_f32_e32 v62, v63, v62
	v_div_scale_f32 v63, vcc, 2.0, v54, 2.0
	v_mul_f32_e32 v64, v63, v62
	v_fma_f32 v65, -v61, v64, v63
	v_fmac_f32_e32 v64, v65, v62
	v_fma_f32 v61, -v61, v64, v63
	v_div_fmas_f32 v61, v61, v62, v64
	v_div_fixup_f32 v54, v61, v54, 2.0
	v_sub_f32_e32 v54, 1.0, v54
	v_add_f32_e32 v54, 1.0, v54
	v_mul_f32_e32 v61, v50, v54
	v_lshlrev_b32_e32 v50, 16, v55
	v_mul_f32_e32 v54, 0x3d372713, v50
	v_mul_f32_e32 v54, v54, v50
	v_fma_f32 v54, v54, v50, v50
	v_mul_f32_e32 v54, 0x3f4c422a, v54
	v_add_f32_e32 v54, v54, v54
	v_mul_f32_e32 v54, 0x3fb8aa3b, v54
	v_exp_f32_e32 v54, v54
	v_mul_f32_e32 v50, 0.5, v50
	v_add_f32_e32 v54, 1.0, v54
	v_div_scale_f32 v62, s[14:15], v54, v54, 2.0
	v_rcp_f32_e32 v63, v62
	s_nop 0
	v_fma_f32 v64, -v62, v63, 1.0
	v_fmac_f32_e32 v63, v64, v63
	v_div_scale_f32 v64, vcc, 2.0, v54, 2.0
	v_mul_f32_e32 v65, v64, v63
	v_fma_f32 v98, -v62, v65, v64
	v_fmac_f32_e32 v65, v98, v63
	v_fma_f32 v62, -v62, v65, v64
	v_div_fmas_f32 v62, v62, v63, v65
	v_div_fixup_f32 v54, v62, v54, 2.0
	v_sub_f32_e32 v54, 1.0, v54
	v_add_f32_e32 v54, 1.0, v54
	v_mul_f32_e32 v62, v50, v54
	v_and_b32_e32 v50, 0xffff0000, v55
	v_mul_f32_e32 v54, 0x3d372713, v50
	v_mul_f32_e32 v54, v54, v50
	v_fma_f32 v54, v54, v50, v50
	v_mul_f32_e32 v54, 0x3f4c422a, v54
	v_add_f32_e32 v54, v54, v54
	v_mul_f32_e32 v54, 0x3fb8aa3b, v54
	v_exp_f32_e32 v54, v54
	v_mul_f32_e32 v50, 0.5, v50
	v_add_f32_e32 v54, 1.0, v54
	v_div_scale_f32 v55, s[14:15], v54, v54, 2.0
	v_rcp_f32_e32 v63, v55
	s_nop 0
	v_fma_f32 v64, -v55, v63, 1.0
	v_fmac_f32_e32 v63, v64, v63
	v_div_scale_f32 v64, vcc, 2.0, v54, 2.0
	v_mul_f32_e32 v65, v64, v63
	v_fma_f32 v98, -v55, v65, v64
	v_fmac_f32_e32 v65, v98, v63
	v_fma_f32 v55, -v55, v65, v64
	v_div_fmas_f32 v55, v55, v63, v65
	v_div_fixup_f32 v54, v55, v54, 2.0
	v_sub_f32_e32 v54, 1.0, v54
	v_add_f32_e32 v54, 1.0, v54
	v_mul_f32_e32 v63, v50, v54
	v_lshlrev_b32_e32 v50, 16, v56
	v_mul_f32_e32 v54, 0x3d372713, v50
	v_mul_f32_e32 v54, v54, v50
	v_fma_f32 v54, v54, v50, v50
	v_mul_f32_e32 v54, 0x3f4c422a, v54
	v_add_f32_e32 v54, v54, v54
	v_mul_f32_e32 v54, 0x3fb8aa3b, v54
	v_exp_f32_e32 v54, v54
	v_mul_f32_e32 v50, 0.5, v50
	v_add_f32_e32 v54, 1.0, v54
	v_div_scale_f32 v55, s[14:15], v54, v54, 2.0
	v_rcp_f32_e32 v64, v55
	s_nop 0
	v_fma_f32 v65, -v55, v64, 1.0
	v_fmac_f32_e32 v64, v65, v64
	v_div_scale_f32 v65, vcc, 2.0, v54, 2.0
	v_mul_f32_e32 v98, v65, v64
	v_fma_f32 v99, -v55, v98, v65
	v_fmac_f32_e32 v98, v99, v64
	v_fma_f32 v55, -v55, v98, v65
	v_div_fmas_f32 v55, v55, v64, v98
	v_div_fixup_f32 v54, v55, v54, 2.0
	v_sub_f32_e32 v54, 1.0, v54
	v_add_f32_e32 v54, 1.0, v54
	v_mul_f32_e32 v64, v50, v54
	v_and_b32_e32 v50, 0xffff0000, v56
	v_mul_f32_e32 v54, 0x3d372713, v50
	v_mul_f32_e32 v54, v54, v50
	v_fma_f32 v54, v54, v50, v50
	v_mul_f32_e32 v54, 0x3f4c422a, v54
	v_add_f32_e32 v54, v54, v54
	v_mul_f32_e32 v54, 0x3fb8aa3b, v54
	v_exp_f32_e32 v54, v54
	v_mul_f32_e32 v50, 0.5, v50
	v_add_f32_e32 v54, 1.0, v54
	v_div_scale_f32 v55, s[14:15], v54, v54, 2.0
	v_rcp_f32_e32 v56, v55
	s_nop 0
	v_fma_f32 v65, -v55, v56, 1.0
	v_fmac_f32_e32 v56, v65, v56
	v_div_scale_f32 v65, vcc, 2.0, v54, 2.0
	v_mul_f32_e32 v98, v65, v56
	v_fma_f32 v99, -v55, v98, v65
	v_fmac_f32_e32 v98, v99, v56
	v_fma_f32 v55, -v55, v98, v65
	v_div_fmas_f32 v55, v55, v56, v98
	v_div_fixup_f32 v54, v55, v54, 2.0
	v_sub_f32_e32 v54, 1.0, v54
	v_add_f32_e32 v54, 1.0, v54
	v_mul_f32_e32 v56, v50, v54
	v_lshlrev_b32_e32 v50, 16, v57
	v_mul_f32_e32 v54, 0x3d372713, v50
	v_mul_f32_e32 v54, v54, v50
	v_fma_f32 v54, v54, v50, v50
	v_mul_f32_e32 v54, 0x3f4c422a, v54
	v_add_f32_e32 v54, v54, v54
	v_mul_f32_e32 v54, 0x3fb8aa3b, v54
	v_exp_f32_e32 v54, v54
	v_mul_f32_e32 v50, 0.5, v50
	v_add_f32_e32 v54, 1.0, v54
	v_div_scale_f32 v55, s[14:15], v54, v54, 2.0
	v_rcp_f32_e32 v65, v55
	s_nop 0
	v_fma_f32 v98, -v55, v65, 1.0
	v_fmac_f32_e32 v65, v98, v65
	v_div_scale_f32 v98, vcc, 2.0, v54, 2.0
	v_mul_f32_e32 v99, v98, v65
	v_fma_f32 v100, -v55, v99, v98
	v_fmac_f32_e32 v99, v100, v65
	v_fma_f32 v55, -v55, v99, v98
	v_div_fmas_f32 v55, v55, v65, v99
	v_div_fixup_f32 v54, v55, v54, 2.0
	v_sub_f32_e32 v54, 1.0, v54
	v_add_f32_e32 v54, 1.0, v54
	v_mul_f32_e32 v65, v50, v54
	v_and_b32_e32 v50, 0xffff0000, v57
	v_mul_f32_e32 v54, 0x3d372713, v50
	v_mul_f32_e32 v54, v54, v50
	v_fma_f32 v54, v54, v50, v50
	v_mul_f32_e32 v54, 0x3f4c422a, v54
	v_add_f32_e32 v54, v54, v54
	v_mul_f32_e32 v54, 0x3fb8aa3b, v54
	v_exp_f32_e32 v54, v54
	v_mul_f32_e32 v50, 0.5, v50
	v_add_f32_e32 v54, 1.0, v54
	v_div_scale_f32 v55, s[14:15], v54, v54, 2.0
	v_rcp_f32_e32 v57, v55
	s_nop 0
	v_fma_f32 v98, -v55, v57, 1.0
	v_fmac_f32_e32 v57, v98, v57
	v_div_scale_f32 v98, vcc, 2.0, v54, 2.0
	v_mul_f32_e32 v99, v98, v57
	v_fma_f32 v100, -v55, v99, v98
	v_fmac_f32_e32 v99, v100, v57
	v_fma_f32 v55, -v55, v99, v98
	v_div_fmas_f32 v55, v55, v57, v99
	v_div_fixup_f32 v54, v55, v54, 2.0
	v_sub_f32_e32 v54, 1.0, v54
	v_add_f32_e32 v54, 1.0, v54
	v_mul_f32_e32 v57, v50, v54
	v_and_b32_e32 v50, 0xffff0000, v51
	v_lshlrev_b32_e32 v51, 16, v51
	v_mul_f32_e32 v54, 0x3d372713, v51
	v_mul_f32_e32 v54, v54, v51
	v_mov_b32_e32 v55, v51
	v_fmac_f32_e32 v55, v54, v55
	v_mul_f32_e32 v54, 0x3f4c422a, v55
	v_add_f32_e32 v54, v54, v54
	v_mul_f32_e32 v54, 0x3fb8aa3b, v54
	v_exp_f32_e32 v55, v54
	v_mul_f32_e32 v54, 0x3d372713, v50
	v_mul_f32_e32 v54, v54, v50
	v_mov_b32_e32 v99, v50
	v_fmac_f32_e32 v99, v54, v99
	v_mul_f32_e32 v54, 0x3f4c422a, v99
	v_add_f32_e32 v54, v54, v54
	v_mul_f32_e32 v54, 0x3fb8aa3b, v54
	v_exp_f32_e32 v54, v54
	v_pk_mul_f32 v[50:51], v[50:51], 0.5 op_sel_hi:[1,0]
	v_mul_f32_e32 v98, v61, v61
	v_fmac_f32_e32 v98, v60, v60
	v_pk_add_f32 v[54:55], v[54:55], 1.0 op_sel_hi:[1,0]
	s_nop 0
	v_div_scale_f32 v99, s[14:15], v55, v55, 2.0
	v_rcp_f32_e32 v100, v99
	s_nop 0
	v_fma_f32 v101, -v99, v100, 1.0
	v_fmac_f32_e32 v100, v101, v100
	v_div_scale_f32 v101, vcc, 2.0, v55, 2.0
	v_mul_f32_e32 v115, v101, v100
	v_fma_f32 v116, -v99, v115, v101
	v_fmac_f32_e32 v115, v116, v100
	v_fma_f32 v99, -v99, v115, v101
	v_div_fmas_f32 v99, v99, v100, v115
	v_div_fixup_f32 v55, v99, v55, 2.0
	v_div_scale_f32 v99, s[14:15], v54, v54, 2.0
	v_rcp_f32_e32 v100, v99
	s_nop 0
	v_fma_f32 v101, -v99, v100, 1.0
	v_fmac_f32_e32 v100, v101, v100
	v_div_scale_f32 v101, vcc, 2.0, v54, 2.0
	v_mul_f32_e32 v115, v101, v100
	v_fma_f32 v116, -v99, v115, v101
	v_fmac_f32_e32 v115, v116, v100
	v_fma_f32 v99, -v99, v115, v101
	v_div_fmas_f32 v99, v99, v100, v115
	v_div_fixup_f32 v54, v99, v54, 2.0
	v_pk_add_f32 v[54:55], v[54:55], 1.0 op_sel_hi:[1,0] neg_lo:[1,0] neg_hi:[1,0]
	s_nop 0
	v_pk_add_f32 v[54:55], v[54:55], 1.0 op_sel_hi:[1,0]
	s_nop 0
	v_pk_mul_f32 v[50:51], v[50:51], v[54:55]
	s_nop 0
	v_pk_mul_f32 v[54:55], v[50:51], v[50:51]
	s_nop 0
	v_add_f32_e32 v55, v55, v98
	v_add_f32_e32 v100, v54, v55
	v_lshlrev_b32_e32 v55, 16, v52
	v_and_b32_e32 v54, 0xffff0000, v52
	v_mul_f32_e32 v52, 0x3d372713, v55
	v_mul_f32_e32 v52, v52, v55
	v_mov_b32_e32 v98, v55
	v_fmac_f32_e32 v98, v52, v98
	v_mul_f32_e32 v52, 0x3f4c422a, v98
	v_add_f32_e32 v52, v52, v52
	v_mul_f32_e32 v52, 0x3fb8aa3b, v52
	v_exp_f32_e32 v99, v52
	v_mul_f32_e32 v52, 0x3d372713, v54
	v_mul_f32_e32 v52, v52, v54
	v_mov_b32_e32 v98, v54
	v_fmac_f32_e32 v98, v52, v98
	v_mul_f32_e32 v52, 0x3f4c422a, v98
	v_add_f32_e32 v52, v52, v52
	v_mul_f32_e32 v52, 0x3fb8aa3b, v52
	v_exp_f32_e32 v98, v52
	v_pk_mul_f32 v[54:55], v[54:55], 0.5 op_sel_hi:[1,0]
	v_pk_add_f32 v[98:99], v[98:99], 1.0 op_sel_hi:[1,0]
	s_nop 0
	v_div_scale_f32 v52, s[14:15], v99, v99, 2.0
	v_rcp_f32_e32 v101, v52
	s_nop 0
	v_fma_f32 v115, -v52, v101, 1.0
	v_fmac_f32_e32 v101, v115, v101
	v_div_scale_f32 v115, vcc, 2.0, v99, 2.0
	v_mul_f32_e32 v116, v115, v101
	v_fma_f32 v117, -v52, v116, v115
	v_fmac_f32_e32 v116, v117, v101
	v_fma_f32 v52, -v52, v116, v115
	v_div_fmas_f32 v52, v52, v101, v116
	v_div_fixup_f32 v99, v52, v99, 2.0
	v_div_scale_f32 v52, s[14:15], v98, v98, 2.0
	v_rcp_f32_e32 v101, v52
	s_nop 0
	v_fma_f32 v115, -v52, v101, 1.0
	v_fmac_f32_e32 v101, v115, v101
	v_div_scale_f32 v115, vcc, 2.0, v98, 2.0
	v_mul_f32_e32 v116, v115, v101
	v_fma_f32 v117, -v52, v116, v115
	v_fmac_f32_e32 v116, v117, v101
	v_fma_f32 v52, -v52, v116, v115
	v_div_fmas_f32 v52, v52, v101, v116
	v_div_fixup_f32 v98, v52, v98, 2.0
	v_pk_add_f32 v[98:99], v[98:99], 1.0 op_sel_hi:[1,0] neg_lo:[1,0] neg_hi:[1,0]
	s_nop 0
	v_pk_add_f32 v[98:99], v[98:99], 1.0 op_sel_hi:[1,0]
	s_nop 0
	v_pk_mul_f32 v[54:55], v[54:55], v[98:99]
	s_nop 0
	v_pk_mul_f32 v[98:99], v[54:55], v[54:55]
	s_nop 0
	v_add_f32_e32 v52, v99, v100
	v_add_f32_e32 v100, v98, v52
	v_and_b32_e32 v52, 0xffff0000, v53
	v_lshlrev_b32_e32 v53, 16, v53
	v_mul_f32_e32 v98, 0x3d372713, v53
	v_mul_f32_e32 v98, v98, v53
	v_mov_b32_e32 v99, v53
	v_fmac_f32_e32 v99, v98, v99
	v_mul_f32_e32 v98, 0x3f4c422a, v99
	v_add_f32_e32 v98, v98, v98
	v_mul_f32_e32 v98, 0x3fb8aa3b, v98
	v_exp_f32_e32 v99, v98
	v_mul_f32_e32 v98, 0x3d372713, v52
	v_mul_f32_e32 v98, v98, v52
	v_mov_b32_e32 v101, v52
	v_fmac_f32_e32 v101, v98, v101
	v_mul_f32_e32 v98, 0x3f4c422a, v101
	v_add_f32_e32 v98, v98, v98
	v_mul_f32_e32 v98, 0x3fb8aa3b, v98
	v_exp_f32_e32 v98, v98
	v_pk_mul_f32 v[52:53], v[52:53], 0.5 op_sel_hi:[1,0]
	v_pk_add_f32 v[98:99], v[98:99], 1.0 op_sel_hi:[1,0]
	s_nop 0
	v_div_scale_f32 v101, s[14:15], v99, v99, 2.0
	v_rcp_f32_e32 v115, v101
	s_nop 0
	v_fma_f32 v116, -v101, v115, 1.0
	v_fmac_f32_e32 v115, v116, v115
	v_div_scale_f32 v116, vcc, 2.0, v99, 2.0
	v_mul_f32_e32 v117, v116, v115
	v_fma_f32 v118, -v101, v117, v116
	v_fmac_f32_e32 v117, v118, v115
	v_fma_f32 v101, -v101, v117, v116
	v_div_fmas_f32 v101, v101, v115, v117
	v_div_fixup_f32 v99, v101, v99, 2.0
	v_div_scale_f32 v101, s[14:15], v98, v98, 2.0
	v_rcp_f32_e32 v115, v101
	s_nop 0
	v_fma_f32 v116, -v101, v115, 1.0
	v_fmac_f32_e32 v115, v116, v115
	v_div_scale_f32 v116, vcc, 2.0, v98, 2.0
	v_mul_f32_e32 v117, v116, v115
	v_fma_f32 v118, -v101, v117, v116
	v_fmac_f32_e32 v117, v118, v115
	v_fma_f32 v101, -v101, v117, v116
	v_div_fmas_f32 v101, v101, v115, v117
	v_div_fixup_f32 v98, v101, v98, 2.0
	v_pk_add_f32 v[98:99], v[98:99], 1.0 op_sel_hi:[1,0] neg_lo:[1,0] neg_hi:[1,0]
	s_nop 0
	v_pk_add_f32 v[98:99], v[98:99], 1.0 op_sel_hi:[1,0]
	s_nop 0
	v_pk_mul_f32 v[98:99], v[52:53], v[98:99]
	s_nop 0
	v_pk_mul_f32 v[52:53], v[98:99], v[98:99]
	s_nop 0
	v_add_f32_e32 v53, v53, v100
	v_add_f32_e32 v52, v52, v53
	ds_bpermute_b32 v53, v106, v52
	s_waitcnt lgkmcnt(0)
	v_add_f32_e32 v52, v52, v53
	ds_bpermute_b32 v53, v107, v52
	s_waitcnt lgkmcnt(0)
	v_add_f32_e32 v52, v52, v53
	ds_bpermute_b32 v53, v108, v52
	s_waitcnt lgkmcnt(0)
	v_add_f32_e32 v52, v52, v53
	ds_bpermute_b32 v53, v109, v52
	s_waitcnt lgkmcnt(0)
	v_add_f32_e32 v52, v52, v53
	ds_bpermute_b32 v53, v110, v52
	s_waitcnt lgkmcnt(0)
	v_add_f32_e32 v52, v52, v53
	v_fmamk_f32 v52, v52, 0x3b800000, v243
	v_cmp_gt_f32_e32 vcc, s3, v52
	v_mul_f32_e32 v53, 0x4b800000, v52
	s_nop 0
	v_cndmask_b32_e32 v52, v52, v53, vcc
	v_rsq_f32_e32 v52, v52
	s_nop 0
	v_mul_f32_e32 v53, 0x45800000, v52
	v_cndmask_b32_e32 v100, v52, v53, vcc
	v_mul_f32_e32 v52, v60, v100
	v_mul_f32_e32 v53, v61, v100
	v_mul_f32_e32 v50, v50, v100
	v_mul_f32_e32 v52, v70, v52
	v_mul_f32_e32 v53, v71, v53
	v_mul_f32_e32 v51, v51, v100
	v_mul_f32_e32 v50, v73, v50
	v_cvt_pk_bf16_f32 v52, v52, v53
	v_cvt_pk_bf16_f32 v59, v62, v63
	v_mul_f32_e32 v51, v72, v51
	v_cvt_pk_bf16_f32 v53, v51, v50
	v_mul_f32_e32 v50, v55, v100
	v_mul_f32_e32 v50, v66, v50
	v_mul_f32_e32 v51, v54, v100
	v_cvt_pk_bf16_f32 v60, v64, v56
	v_mul_f32_e32 v51, v67, v51
	v_cvt_pk_bf16_f32 v54, v50, v51
	v_mul_f32_e32 v50, v99, v100
	v_mul_f32_e32 v50, v68, v50
	v_mul_f32_e32 v51, v98, v100
	v_cvt_pk_bf16_f32 v61, v65, v57
	v_mul_f32_e32 v51, v69, v51
	v_cvt_pk_bf16_f32 v55, v50, v51
	v_lshlrev_b32_e32 v50, 16, v46
	v_mul_f32_e32 v51, 0x3d372713, v50
	v_mul_f32_e32 v51, v51, v50
	v_fma_f32 v51, v51, v50, v50
	v_mul_f32_e32 v51, 0x3f4c422a, v51
	v_add_f32_e32 v51, v51, v51
	v_mul_f32_e32 v51, 0x3fb8aa3b, v51
	v_exp_f32_e32 v51, v51
	ds_write_b128 v111, v[58:61] offset:8704
	ds_write_b128 v112, v[52:55] offset:8704
	v_mul_f32_e32 v50, 0.5, v50
	v_and_b32_e32 v46, 0xffff0000, v46
	v_add_f32_e32 v51, 1.0, v51
	v_div_scale_f32 v52, s[14:15], v51, v51, 2.0
	v_rcp_f32_e32 v53, v52
	v_mov_b64_e32 v[98:99], v[80:81]
	v_mov_b64_e32 v[100:101], v[78:79]
	v_fma_f32 v54, -v52, v53, 1.0
	v_fmac_f32_e32 v53, v54, v53
	v_div_scale_f32 v54, vcc, 2.0, v51, 2.0
	v_mul_f32_e32 v55, v54, v53
	v_fma_f32 v56, -v52, v55, v54
	v_fmac_f32_e32 v55, v56, v53
	v_fma_f32 v52, -v52, v55, v54
	v_div_fmas_f32 v52, v52, v53, v55
	v_div_fixup_f32 v51, v52, v51, 2.0
	v_sub_f32_e32 v51, 1.0, v51
	v_add_f32_e32 v51, 1.0, v51
	v_mul_f32_e32 v50, v50, v51
	v_mul_f32_e32 v51, 0x3d372713, v46
	v_mul_f32_e32 v51, v51, v46
	v_fma_f32 v51, v51, v46, v46
	v_mul_f32_e32 v51, 0x3f4c422a, v51
	v_add_f32_e32 v51, v51, v51
	v_mul_f32_e32 v51, 0x3fb8aa3b, v51
	v_exp_f32_e32 v51, v51
	v_mul_f32_e32 v46, 0.5, v46
	v_add_f32_e32 v51, 1.0, v51
	v_div_scale_f32 v52, s[14:15], v51, v51, 2.0
	v_rcp_f32_e32 v53, v52
	s_nop 0
	v_fma_f32 v54, -v52, v53, 1.0
	v_fmac_f32_e32 v53, v54, v53
	v_div_scale_f32 v54, vcc, 2.0, v51, 2.0
	v_mul_f32_e32 v55, v54, v53
	v_fma_f32 v56, -v52, v55, v54
	v_fmac_f32_e32 v55, v56, v53
	v_fma_f32 v52, -v52, v55, v54
	v_div_fmas_f32 v52, v52, v53, v55
	v_div_fixup_f32 v51, v52, v51, 2.0
	v_sub_f32_e32 v51, 1.0, v51
	v_add_f32_e32 v51, 1.0, v51
	v_mul_f32_e32 v51, v46, v51
	v_lshlrev_b32_e32 v46, 16, v42
	v_mul_f32_e32 v52, 0x3d372713, v46
	v_mul_f32_e32 v52, v52, v46
	v_fma_f32 v52, v52, v46, v46
	v_mul_f32_e32 v52, 0x3f4c422a, v52
	v_add_f32_e32 v52, v52, v52
	v_mul_f32_e32 v52, 0x3fb8aa3b, v52
	v_exp_f32_e32 v52, v52
	v_mul_f32_e32 v46, 0.5, v46
	v_and_b32_e32 v42, 0xffff0000, v42
	v_cvt_pk_bf16_f32 v50, v50, v51
	v_add_f32_e32 v52, 1.0, v52
	v_div_scale_f32 v53, s[14:15], v52, v52, 2.0
	v_rcp_f32_e32 v54, v53
	s_nop 0
	v_fma_f32 v55, -v53, v54, 1.0
	v_fmac_f32_e32 v54, v55, v54
	v_div_scale_f32 v55, vcc, 2.0, v52, 2.0
	v_mul_f32_e32 v56, v55, v54
	v_fma_f32 v57, -v53, v56, v55
	v_fmac_f32_e32 v56, v57, v54
	v_fma_f32 v53, -v53, v56, v55
	v_div_fmas_f32 v53, v53, v54, v56
	v_div_fixup_f32 v52, v53, v52, 2.0
	v_sub_f32_e32 v52, 1.0, v52
	v_add_f32_e32 v52, 1.0, v52
	v_mul_f32_e32 v52, v46, v52
	v_mul_f32_e32 v46, 0x3d372713, v42
	v_mul_f32_e32 v46, v46, v42
	v_fma_f32 v46, v46, v42, v42
	v_mul_f32_e32 v46, 0x3f4c422a, v46
	v_add_f32_e32 v46, v46, v46
	v_mul_f32_e32 v46, 0x3fb8aa3b, v46
	v_exp_f32_e32 v46, v46
	v_mul_f32_e32 v42, 0.5, v42
	v_add_f32_e32 v46, 1.0, v46
	v_div_scale_f32 v53, s[14:15], v46, v46, 2.0
	v_rcp_f32_e32 v54, v53
	s_nop 0
	v_fma_f32 v55, -v53, v54, 1.0
	v_fmac_f32_e32 v54, v55, v54
	v_div_scale_f32 v55, vcc, 2.0, v46, 2.0
	v_mul_f32_e32 v56, v55, v54
	v_fma_f32 v57, -v53, v56, v55
	v_fmac_f32_e32 v56, v57, v54
	v_fma_f32 v53, -v53, v56, v55
	v_div_fmas_f32 v53, v53, v54, v56
	v_div_fixup_f32 v46, v53, v46, 2.0
	v_sub_f32_e32 v46, 1.0, v46
	v_add_f32_e32 v46, 1.0, v46
	v_mul_f32_e32 v53, v42, v46
	v_lshlrev_b32_e32 v42, 16, v47
	v_mul_f32_e32 v46, 0x3d372713, v42
	v_mul_f32_e32 v46, v46, v42
	v_fma_f32 v46, v46, v42, v42
	v_mul_f32_e32 v46, 0x3f4c422a, v46
	v_add_f32_e32 v46, v46, v46
	v_mul_f32_e32 v46, 0x3fb8aa3b, v46
	v_exp_f32_e32 v46, v46
	v_mul_f32_e32 v42, 0.5, v42
	v_add_f32_e32 v46, 1.0, v46
	v_div_scale_f32 v54, s[14:15], v46, v46, 2.0
	v_rcp_f32_e32 v55, v54
	s_nop 0
	v_fma_f32 v56, -v54, v55, 1.0
	v_fmac_f32_e32 v55, v56, v55
	v_div_scale_f32 v56, vcc, 2.0, v46, 2.0
	v_mul_f32_e32 v57, v56, v55
	v_fma_f32 v58, -v54, v57, v56
	v_fmac_f32_e32 v57, v58, v55
	v_fma_f32 v54, -v54, v57, v56
	v_div_fmas_f32 v54, v54, v55, v57
	v_div_fixup_f32 v46, v54, v46, 2.0
	v_sub_f32_e32 v46, 1.0, v46
	v_add_f32_e32 v46, 1.0, v46
	v_mul_f32_e32 v54, v42, v46
	v_and_b32_e32 v42, 0xffff0000, v47
	v_mul_f32_e32 v46, 0x3d372713, v42
	v_mul_f32_e32 v46, v46, v42
	v_fma_f32 v46, v46, v42, v42
	v_mul_f32_e32 v46, 0x3f4c422a, v46
	v_add_f32_e32 v46, v46, v46
	v_mul_f32_e32 v46, 0x3fb8aa3b, v46
	v_exp_f32_e32 v46, v46
	v_mul_f32_e32 v42, 0.5, v42
	v_add_f32_e32 v46, 1.0, v46
	v_div_scale_f32 v47, s[14:15], v46, v46, 2.0
	v_rcp_f32_e32 v55, v47
	s_nop 0
	v_fma_f32 v56, -v47, v55, 1.0
	v_fmac_f32_e32 v55, v56, v55
	v_div_scale_f32 v56, vcc, 2.0, v46, 2.0
	v_mul_f32_e32 v57, v56, v55
	v_fma_f32 v58, -v47, v57, v56
	v_fmac_f32_e32 v57, v58, v55
	v_fma_f32 v47, -v47, v57, v56
	v_div_fmas_f32 v47, v47, v55, v57
	v_div_fixup_f32 v46, v47, v46, 2.0
	v_sub_f32_e32 v46, 1.0, v46
	v_add_f32_e32 v46, 1.0, v46
	v_mul_f32_e32 v55, v42, v46
	v_lshlrev_b32_e32 v42, 16, v48
	v_mul_f32_e32 v46, 0x3d372713, v42
	v_mul_f32_e32 v46, v46, v42
	v_fma_f32 v46, v46, v42, v42
	v_mul_f32_e32 v46, 0x3f4c422a, v46
	v_add_f32_e32 v46, v46, v46
	v_mul_f32_e32 v46, 0x3fb8aa3b, v46
	v_exp_f32_e32 v46, v46
	v_mul_f32_e32 v42, 0.5, v42
	v_add_f32_e32 v46, 1.0, v46
	v_div_scale_f32 v47, s[14:15], v46, v46, 2.0
	v_rcp_f32_e32 v56, v47
	s_nop 0
	v_fma_f32 v57, -v47, v56, 1.0
	v_fmac_f32_e32 v56, v57, v56
	v_div_scale_f32 v57, vcc, 2.0, v46, 2.0
	v_mul_f32_e32 v58, v57, v56
	v_fma_f32 v59, -v47, v58, v57
	v_fmac_f32_e32 v58, v59, v56
	v_fma_f32 v47, -v47, v58, v57
	v_div_fmas_f32 v47, v47, v56, v58
	v_div_fixup_f32 v46, v47, v46, 2.0
	v_sub_f32_e32 v46, 1.0, v46
	v_add_f32_e32 v46, 1.0, v46
	v_mul_f32_e32 v56, v42, v46
	v_and_b32_e32 v42, 0xffff0000, v48
	v_mul_f32_e32 v46, 0x3d372713, v42
	v_mul_f32_e32 v46, v46, v42
	v_fma_f32 v46, v46, v42, v42
	v_mul_f32_e32 v46, 0x3f4c422a, v46
	v_add_f32_e32 v46, v46, v46
	v_mul_f32_e32 v46, 0x3fb8aa3b, v46
	v_exp_f32_e32 v46, v46
	v_mul_f32_e32 v42, 0.5, v42
	v_add_f32_e32 v46, 1.0, v46
	v_div_scale_f32 v47, s[14:15], v46, v46, 2.0
	v_rcp_f32_e32 v48, v47
	s_nop 0
	v_fma_f32 v57, -v47, v48, 1.0
	v_fmac_f32_e32 v48, v57, v48
	v_div_scale_f32 v57, vcc, 2.0, v46, 2.0
	v_mul_f32_e32 v58, v57, v48
	v_fma_f32 v59, -v47, v58, v57
	v_fmac_f32_e32 v58, v59, v48
	v_fma_f32 v47, -v47, v58, v57
	v_div_fmas_f32 v47, v47, v48, v58
	v_div_fixup_f32 v46, v47, v46, 2.0
	v_sub_f32_e32 v46, 1.0, v46
	v_add_f32_e32 v46, 1.0, v46
	v_mul_f32_e32 v48, v42, v46
	v_lshlrev_b32_e32 v42, 16, v49
	v_mul_f32_e32 v46, 0x3d372713, v42
	v_mul_f32_e32 v46, v46, v42
	v_fma_f32 v46, v46, v42, v42
	v_mul_f32_e32 v46, 0x3f4c422a, v46
	v_add_f32_e32 v46, v46, v46
	v_mul_f32_e32 v46, 0x3fb8aa3b, v46
	v_exp_f32_e32 v46, v46
	v_mul_f32_e32 v42, 0.5, v42
	v_add_f32_e32 v46, 1.0, v46
	v_div_scale_f32 v47, s[14:15], v46, v46, 2.0
	v_rcp_f32_e32 v57, v47
	s_nop 0
	v_fma_f32 v58, -v47, v57, 1.0
	v_fmac_f32_e32 v57, v58, v57
	v_div_scale_f32 v58, vcc, 2.0, v46, 2.0
	v_mul_f32_e32 v59, v58, v57
	v_fma_f32 v60, -v47, v59, v58
	v_fmac_f32_e32 v59, v60, v57
	v_fma_f32 v47, -v47, v59, v58
	v_div_fmas_f32 v47, v47, v57, v59
	v_div_fixup_f32 v46, v47, v46, 2.0
	v_sub_f32_e32 v46, 1.0, v46
	v_add_f32_e32 v46, 1.0, v46
	v_mul_f32_e32 v57, v42, v46
	v_and_b32_e32 v42, 0xffff0000, v49
	v_mul_f32_e32 v46, 0x3d372713, v42
	v_mul_f32_e32 v46, v46, v42
	v_fma_f32 v46, v46, v42, v42
	v_mul_f32_e32 v46, 0x3f4c422a, v46
	v_add_f32_e32 v46, v46, v46
	v_mul_f32_e32 v46, 0x3fb8aa3b, v46
	v_exp_f32_e32 v46, v46
	v_mul_f32_e32 v42, 0.5, v42
	v_add_f32_e32 v46, 1.0, v46
	v_div_scale_f32 v47, s[14:15], v46, v46, 2.0
	v_rcp_f32_e32 v49, v47
	s_nop 0
	v_fma_f32 v58, -v47, v49, 1.0
	v_fmac_f32_e32 v49, v58, v49
	v_div_scale_f32 v58, vcc, 2.0, v46, 2.0
	v_mul_f32_e32 v59, v58, v49
	v_fma_f32 v60, -v47, v59, v58
	v_fmac_f32_e32 v59, v60, v49
	v_fma_f32 v47, -v47, v59, v58
	v_div_fmas_f32 v47, v47, v49, v59
	v_div_fixup_f32 v46, v47, v46, 2.0
	v_sub_f32_e32 v46, 1.0, v46
	v_add_f32_e32 v46, 1.0, v46
	v_mul_f32_e32 v49, v42, v46
	v_and_b32_e32 v42, 0xffff0000, v43
	v_lshlrev_b32_e32 v43, 16, v43
	v_mul_f32_e32 v46, 0x3d372713, v43
	v_mul_f32_e32 v46, v46, v43
	v_mov_b32_e32 v47, v43
	v_fmac_f32_e32 v47, v46, v47
	v_mul_f32_e32 v46, 0x3f4c422a, v47
	v_add_f32_e32 v46, v46, v46
	v_mul_f32_e32 v46, 0x3fb8aa3b, v46
	v_exp_f32_e32 v47, v46
	v_mul_f32_e32 v46, 0x3d372713, v42
	v_mul_f32_e32 v46, v46, v42
	v_mov_b32_e32 v59, v42
	v_fmac_f32_e32 v59, v46, v59
	v_mul_f32_e32 v46, 0x3f4c422a, v59
	v_add_f32_e32 v46, v46, v46
	v_mul_f32_e32 v46, 0x3fb8aa3b, v46
	v_exp_f32_e32 v46, v46
	v_pk_mul_f32 v[42:43], v[42:43], 0.5 op_sel_hi:[1,0]
	v_mul_f32_e32 v58, v53, v53
	v_fmac_f32_e32 v58, v52, v52
	v_pk_add_f32 v[46:47], v[46:47], 1.0 op_sel_hi:[1,0]
	s_nop 0
	v_div_scale_f32 v59, s[14:15], v47, v47, 2.0
	v_rcp_f32_e32 v60, v59
	s_nop 0
	v_fma_f32 v61, -v59, v60, 1.0
	v_fmac_f32_e32 v60, v61, v60
	v_div_scale_f32 v61, vcc, 2.0, v47, 2.0
	v_mul_f32_e32 v62, v61, v60
	v_fma_f32 v63, -v59, v62, v61
	v_fmac_f32_e32 v62, v63, v60
	v_fma_f32 v59, -v59, v62, v61
	v_div_fmas_f32 v59, v59, v60, v62
	v_div_fixup_f32 v47, v59, v47, 2.0
	v_div_scale_f32 v59, s[14:15], v46, v46, 2.0
	v_rcp_f32_e32 v60, v59
	s_nop 0
	v_fma_f32 v61, -v59, v60, 1.0
	v_fmac_f32_e32 v60, v61, v60
	v_div_scale_f32 v61, vcc, 2.0, v46, 2.0
	v_mul_f32_e32 v62, v61, v60
	v_fma_f32 v63, -v59, v62, v61
	v_fmac_f32_e32 v62, v63, v60
	v_fma_f32 v59, -v59, v62, v61
	v_div_fmas_f32 v59, v59, v60, v62
	v_div_fixup_f32 v46, v59, v46, 2.0
	v_pk_add_f32 v[46:47], v[46:47], 1.0 op_sel_hi:[1,0] neg_lo:[1,0] neg_hi:[1,0]
	s_nop 0
	v_pk_add_f32 v[46:47], v[46:47], 1.0 op_sel_hi:[1,0]
	s_nop 0
	v_pk_mul_f32 v[42:43], v[42:43], v[46:47]
	s_nop 0
	v_pk_mul_f32 v[46:47], v[42:43], v[42:43]
	s_nop 0
	v_add_f32_e32 v47, v47, v58
	v_add_f32_e32 v60, v46, v47
	v_lshlrev_b32_e32 v47, 16, v44
	v_and_b32_e32 v46, 0xffff0000, v44
	v_mul_f32_e32 v44, 0x3d372713, v47
	v_mul_f32_e32 v44, v44, v47
	v_mov_b32_e32 v58, v47
	v_fmac_f32_e32 v58, v44, v58
	v_mul_f32_e32 v44, 0x3f4c422a, v58
	v_add_f32_e32 v44, v44, v44
	v_mul_f32_e32 v44, 0x3fb8aa3b, v44
	v_exp_f32_e32 v59, v44
	v_mul_f32_e32 v44, 0x3d372713, v46
	v_mul_f32_e32 v44, v44, v46
	v_mov_b32_e32 v58, v46
	v_fmac_f32_e32 v58, v44, v58
	v_mul_f32_e32 v44, 0x3f4c422a, v58
	v_add_f32_e32 v44, v44, v44
	v_mul_f32_e32 v44, 0x3fb8aa3b, v44
	v_exp_f32_e32 v58, v44
	v_pk_mul_f32 v[46:47], v[46:47], 0.5 op_sel_hi:[1,0]
	v_pk_add_f32 v[58:59], v[58:59], 1.0 op_sel_hi:[1,0]
	s_nop 0
	v_div_scale_f32 v44, s[14:15], v59, v59, 2.0
	v_rcp_f32_e32 v61, v44
	s_nop 0
	v_fma_f32 v62, -v44, v61, 1.0
	v_fmac_f32_e32 v61, v62, v61
	v_div_scale_f32 v62, vcc, 2.0, v59, 2.0
	v_mul_f32_e32 v63, v62, v61
	v_fma_f32 v64, -v44, v63, v62
	v_fmac_f32_e32 v63, v64, v61
	v_fma_f32 v44, -v44, v63, v62
	v_div_fmas_f32 v44, v44, v61, v63
	v_div_fixup_f32 v59, v44, v59, 2.0
	v_div_scale_f32 v44, s[14:15], v58, v58, 2.0
	v_rcp_f32_e32 v61, v44
	s_nop 0
	v_fma_f32 v62, -v44, v61, 1.0
	v_fmac_f32_e32 v61, v62, v61
	v_div_scale_f32 v62, vcc, 2.0, v58, 2.0
	v_mul_f32_e32 v63, v62, v61
	v_fma_f32 v64, -v44, v63, v62
	v_fmac_f32_e32 v63, v64, v61
	v_fma_f32 v44, -v44, v63, v62
	v_div_fmas_f32 v44, v44, v61, v63
	v_div_fixup_f32 v58, v44, v58, 2.0
	v_pk_add_f32 v[58:59], v[58:59], 1.0 op_sel_hi:[1,0] neg_lo:[1,0] neg_hi:[1,0]
	s_nop 0
	v_pk_add_f32 v[58:59], v[58:59], 1.0 op_sel_hi:[1,0]
	s_nop 0
	v_pk_mul_f32 v[46:47], v[46:47], v[58:59]
	s_nop 0
	v_pk_mul_f32 v[58:59], v[46:47], v[46:47]
	s_nop 0
	v_add_f32_e32 v44, v59, v60
	v_add_f32_e32 v60, v58, v44
	v_and_b32_e32 v44, 0xffff0000, v45
	v_lshlrev_b32_e32 v45, 16, v45
	v_mul_f32_e32 v58, 0x3d372713, v45
	v_mul_f32_e32 v58, v58, v45
	v_mov_b32_e32 v59, v45
	v_fmac_f32_e32 v59, v58, v59
	v_mul_f32_e32 v58, 0x3f4c422a, v59
	v_add_f32_e32 v58, v58, v58
	v_mul_f32_e32 v58, 0x3fb8aa3b, v58
	v_exp_f32_e32 v59, v58
	v_mul_f32_e32 v58, 0x3d372713, v44
	v_mul_f32_e32 v58, v58, v44
	v_mov_b32_e32 v61, v44
	v_fmac_f32_e32 v61, v58, v61
	v_mul_f32_e32 v58, 0x3f4c422a, v61
	v_add_f32_e32 v58, v58, v58
	v_mul_f32_e32 v58, 0x3fb8aa3b, v58
	v_exp_f32_e32 v58, v58
	v_pk_mul_f32 v[44:45], v[44:45], 0.5 op_sel_hi:[1,0]
	v_pk_add_f32 v[58:59], v[58:59], 1.0 op_sel_hi:[1,0]
	s_nop 0
	v_div_scale_f32 v61, s[14:15], v59, v59, 2.0
	v_rcp_f32_e32 v62, v61
	s_nop 0
	v_fma_f32 v63, -v61, v62, 1.0
	v_fmac_f32_e32 v62, v63, v62
	v_div_scale_f32 v63, vcc, 2.0, v59, 2.0
	v_mul_f32_e32 v64, v63, v62
	v_fma_f32 v65, -v61, v64, v63
	v_fmac_f32_e32 v64, v65, v62
	v_fma_f32 v61, -v61, v64, v63
	v_div_fmas_f32 v61, v61, v62, v64
	v_div_fixup_f32 v59, v61, v59, 2.0
	v_div_scale_f32 v61, s[14:15], v58, v58, 2.0
	v_rcp_f32_e32 v62, v61
	s_nop 0
	v_fma_f32 v63, -v61, v62, 1.0
	v_fmac_f32_e32 v62, v63, v62
	v_div_scale_f32 v63, vcc, 2.0, v58, 2.0
	v_mul_f32_e32 v64, v63, v62
	v_fma_f32 v65, -v61, v64, v63
	v_fmac_f32_e32 v64, v65, v62
	v_fma_f32 v61, -v61, v64, v63
	v_div_fmas_f32 v61, v61, v62, v64
	v_div_fixup_f32 v58, v61, v58, 2.0
	v_pk_add_f32 v[58:59], v[58:59], 1.0 op_sel_hi:[1,0] neg_lo:[1,0] neg_hi:[1,0]
	s_nop 0
	v_pk_add_f32 v[58:59], v[58:59], 1.0 op_sel_hi:[1,0]
	s_nop 0
	v_pk_mul_f32 v[58:59], v[44:45], v[58:59]
	s_nop 0
	v_pk_mul_f32 v[44:45], v[58:59], v[58:59]
	s_nop 0
	v_add_f32_e32 v45, v45, v60
	v_add_f32_e32 v44, v44, v45
	ds_bpermute_b32 v45, v106, v44
	s_waitcnt lgkmcnt(0)
	v_add_f32_e32 v44, v44, v45
	ds_bpermute_b32 v45, v107, v44
	s_waitcnt lgkmcnt(0)
	v_add_f32_e32 v44, v44, v45
	ds_bpermute_b32 v45, v108, v44
	s_waitcnt lgkmcnt(0)
	v_add_f32_e32 v44, v44, v45
	ds_bpermute_b32 v45, v109, v44
	s_waitcnt lgkmcnt(0)
	v_add_f32_e32 v44, v44, v45
	ds_bpermute_b32 v45, v110, v44
	s_waitcnt lgkmcnt(0)
	v_add_f32_e32 v44, v44, v45
	v_fmamk_f32 v44, v44, 0x3b800000, v243
	v_cmp_gt_f32_e32 vcc, s3, v44
	v_mul_f32_e32 v45, 0x4b800000, v44
	s_nop 0
	v_cndmask_b32_e32 v44, v44, v45, vcc
	v_rsq_f32_e32 v44, v44
	s_nop 0
	v_mul_f32_e32 v45, 0x45800000, v44
	v_cndmask_b32_e32 v60, v44, v45, vcc
	v_mul_f32_e32 v44, v52, v60
	v_mul_f32_e32 v45, v53, v60
	v_mul_f32_e32 v42, v42, v60
	v_mul_f32_e32 v44, v70, v44
	v_mul_f32_e32 v45, v71, v45
	v_mul_f32_e32 v43, v43, v60
	v_mul_f32_e32 v42, v73, v42
	v_cvt_pk_bf16_f32 v44, v44, v45
	v_cvt_pk_bf16_f32 v51, v54, v55
	v_mul_f32_e32 v43, v72, v43
	v_cvt_pk_bf16_f32 v45, v43, v42
	v_mul_f32_e32 v42, v47, v60
	v_mul_f32_e32 v42, v66, v42
	v_mul_f32_e32 v43, v46, v60
	v_cvt_pk_bf16_f32 v52, v56, v48
	v_mul_f32_e32 v43, v67, v43
	v_cvt_pk_bf16_f32 v46, v42, v43
	v_mul_f32_e32 v42, v59, v60
	v_mul_f32_e32 v42, v68, v42
	v_mul_f32_e32 v43, v58, v60
	v_cvt_pk_bf16_f32 v53, v57, v49
	v_mul_f32_e32 v43, v69, v43
	v_cvt_pk_bf16_f32 v47, v42, v43
	v_lshlrev_b32_e32 v42, 16, v38
	v_mul_f32_e32 v43, 0x3d372713, v42
	v_mul_f32_e32 v43, v43, v42
	v_fma_f32 v43, v43, v42, v42
	v_mul_f32_e32 v43, 0x3f4c422a, v43
	v_add_f32_e32 v43, v43, v43
	v_mul_f32_e32 v43, 0x3fb8aa3b, v43
	v_exp_f32_e32 v43, v43
	ds_write_b128 v111, v[50:53] offset:17408
	ds_write_b128 v112, v[44:47] offset:17408
	v_mul_f32_e32 v42, 0.5, v42
	v_and_b32_e32 v38, 0xffff0000, v38
	v_add_f32_e32 v43, 1.0, v43
	v_div_scale_f32 v44, s[14:15], v43, v43, 2.0
	v_rcp_f32_e32 v45, v44
	s_nop 0
	v_fma_f32 v46, -v44, v45, 1.0
	v_fmac_f32_e32 v45, v46, v45
	v_div_scale_f32 v46, vcc, 2.0, v43, 2.0
	v_mul_f32_e32 v47, v46, v45
	v_fma_f32 v48, -v44, v47, v46
	v_fmac_f32_e32 v47, v48, v45
	v_fma_f32 v44, -v44, v47, v46
	v_div_fmas_f32 v44, v44, v45, v47
	v_div_fixup_f32 v43, v44, v43, 2.0
	v_sub_f32_e32 v43, 1.0, v43
	v_add_f32_e32 v43, 1.0, v43
	v_mul_f32_e32 v42, v42, v43
	v_mul_f32_e32 v43, 0x3d372713, v38
	v_mul_f32_e32 v43, v43, v38
	v_fma_f32 v43, v43, v38, v38
	v_mul_f32_e32 v43, 0x3f4c422a, v43
	v_add_f32_e32 v43, v43, v43
	v_mul_f32_e32 v43, 0x3fb8aa3b, v43
	v_exp_f32_e32 v43, v43
	v_mul_f32_e32 v38, 0.5, v38
	v_add_f32_e32 v43, 1.0, v43
	v_div_scale_f32 v44, s[14:15], v43, v43, 2.0
	v_rcp_f32_e32 v45, v44
	s_nop 0
	v_fma_f32 v46, -v44, v45, 1.0
	v_fmac_f32_e32 v45, v46, v45
	v_div_scale_f32 v46, vcc, 2.0, v43, 2.0
	v_mul_f32_e32 v47, v46, v45
	v_fma_f32 v48, -v44, v47, v46
	v_fmac_f32_e32 v47, v48, v45
	v_fma_f32 v44, -v44, v47, v46
	v_div_fmas_f32 v44, v44, v45, v47
	v_div_fixup_f32 v43, v44, v43, 2.0
	v_sub_f32_e32 v43, 1.0, v43
	v_add_f32_e32 v43, 1.0, v43
	v_mul_f32_e32 v43, v38, v43
	v_lshlrev_b32_e32 v38, 16, v34
	v_mul_f32_e32 v44, 0x3d372713, v38
	v_mul_f32_e32 v44, v44, v38
	v_fma_f32 v44, v44, v38, v38
	v_mul_f32_e32 v44, 0x3f4c422a, v44
	v_add_f32_e32 v44, v44, v44
	v_mul_f32_e32 v44, 0x3fb8aa3b, v44
	v_exp_f32_e32 v44, v44
	v_mul_f32_e32 v38, 0.5, v38
	v_and_b32_e32 v34, 0xffff0000, v34
	v_cvt_pk_bf16_f32 v42, v42, v43
	v_add_f32_e32 v44, 1.0, v44
	v_div_scale_f32 v45, s[14:15], v44, v44, 2.0
	v_rcp_f32_e32 v46, v45
	s_nop 0
	v_fma_f32 v47, -v45, v46, 1.0
	v_fmac_f32_e32 v46, v47, v46
	v_div_scale_f32 v47, vcc, 2.0, v44, 2.0
	v_mul_f32_e32 v48, v47, v46
	v_fma_f32 v49, -v45, v48, v47
	v_fmac_f32_e32 v48, v49, v46
	v_fma_f32 v45, -v45, v48, v47
	v_div_fmas_f32 v45, v45, v46, v48
	v_div_fixup_f32 v44, v45, v44, 2.0
	v_sub_f32_e32 v44, 1.0, v44
	v_add_f32_e32 v44, 1.0, v44
	v_mul_f32_e32 v44, v38, v44
	v_mul_f32_e32 v38, 0x3d372713, v34
	v_mul_f32_e32 v38, v38, v34
	v_fma_f32 v38, v38, v34, v34
	v_mul_f32_e32 v38, 0x3f4c422a, v38
	v_add_f32_e32 v38, v38, v38
	v_mul_f32_e32 v38, 0x3fb8aa3b, v38
	v_exp_f32_e32 v38, v38
	v_mul_f32_e32 v34, 0.5, v34
	v_add_f32_e32 v38, 1.0, v38
	v_div_scale_f32 v45, s[14:15], v38, v38, 2.0
	v_rcp_f32_e32 v46, v45
	s_nop 0
	v_fma_f32 v47, -v45, v46, 1.0
	v_fmac_f32_e32 v46, v47, v46
	v_div_scale_f32 v47, vcc, 2.0, v38, 2.0
	v_mul_f32_e32 v48, v47, v46
	v_fma_f32 v49, -v45, v48, v47
	v_fmac_f32_e32 v48, v49, v46
	v_fma_f32 v45, -v45, v48, v47
	v_div_fmas_f32 v45, v45, v46, v48
	v_div_fixup_f32 v38, v45, v38, 2.0
	v_sub_f32_e32 v38, 1.0, v38
	v_add_f32_e32 v38, 1.0, v38
	v_mul_f32_e32 v45, v34, v38
	v_lshlrev_b32_e32 v34, 16, v39
	v_mul_f32_e32 v38, 0x3d372713, v34
	v_mul_f32_e32 v38, v38, v34
	v_fma_f32 v38, v38, v34, v34
	v_mul_f32_e32 v38, 0x3f4c422a, v38
	v_add_f32_e32 v38, v38, v38
	v_mul_f32_e32 v38, 0x3fb8aa3b, v38
	v_exp_f32_e32 v38, v38
	v_mul_f32_e32 v34, 0.5, v34
	v_add_f32_e32 v38, 1.0, v38
	v_div_scale_f32 v46, s[14:15], v38, v38, 2.0
	v_rcp_f32_e32 v47, v46
	s_nop 0
	v_fma_f32 v48, -v46, v47, 1.0
	v_fmac_f32_e32 v47, v48, v47
	v_div_scale_f32 v48, vcc, 2.0, v38, 2.0
	v_mul_f32_e32 v49, v48, v47
	v_fma_f32 v50, -v46, v49, v48
	v_fmac_f32_e32 v49, v50, v47
	v_fma_f32 v46, -v46, v49, v48
	v_div_fmas_f32 v46, v46, v47, v49
	v_div_fixup_f32 v38, v46, v38, 2.0
	v_sub_f32_e32 v38, 1.0, v38
	v_add_f32_e32 v38, 1.0, v38
	v_mul_f32_e32 v46, v34, v38
	v_and_b32_e32 v34, 0xffff0000, v39
	v_mul_f32_e32 v38, 0x3d372713, v34
	v_mul_f32_e32 v38, v38, v34
	v_fma_f32 v38, v38, v34, v34
	v_mul_f32_e32 v38, 0x3f4c422a, v38
	v_add_f32_e32 v38, v38, v38
	v_mul_f32_e32 v38, 0x3fb8aa3b, v38
	v_exp_f32_e32 v38, v38
	v_mul_f32_e32 v34, 0.5, v34
	v_add_f32_e32 v38, 1.0, v38
	v_div_scale_f32 v39, s[14:15], v38, v38, 2.0
	v_rcp_f32_e32 v47, v39
	s_nop 0
	v_fma_f32 v48, -v39, v47, 1.0
	v_fmac_f32_e32 v47, v48, v47
	v_div_scale_f32 v48, vcc, 2.0, v38, 2.0
	v_mul_f32_e32 v49, v48, v47
	v_fma_f32 v50, -v39, v49, v48
	v_fmac_f32_e32 v49, v50, v47
	v_fma_f32 v39, -v39, v49, v48
	v_div_fmas_f32 v39, v39, v47, v49
	v_div_fixup_f32 v38, v39, v38, 2.0
	v_sub_f32_e32 v38, 1.0, v38
	v_add_f32_e32 v38, 1.0, v38
	v_mul_f32_e32 v47, v34, v38
	v_lshlrev_b32_e32 v34, 16, v40
	v_mul_f32_e32 v38, 0x3d372713, v34
	v_mul_f32_e32 v38, v38, v34
	v_fma_f32 v38, v38, v34, v34
	v_mul_f32_e32 v38, 0x3f4c422a, v38
	v_add_f32_e32 v38, v38, v38
	v_mul_f32_e32 v38, 0x3fb8aa3b, v38
	v_exp_f32_e32 v38, v38
	v_mul_f32_e32 v34, 0.5, v34
	v_add_f32_e32 v38, 1.0, v38
	v_div_scale_f32 v39, s[14:15], v38, v38, 2.0
	v_rcp_f32_e32 v48, v39
	s_nop 0
	v_fma_f32 v49, -v39, v48, 1.0
	v_fmac_f32_e32 v48, v49, v48
	v_div_scale_f32 v49, vcc, 2.0, v38, 2.0
	v_mul_f32_e32 v50, v49, v48
	v_fma_f32 v51, -v39, v50, v49
	v_fmac_f32_e32 v50, v51, v48
	v_fma_f32 v39, -v39, v50, v49
	v_div_fmas_f32 v39, v39, v48, v50
	v_div_fixup_f32 v38, v39, v38, 2.0
	v_sub_f32_e32 v38, 1.0, v38
	v_add_f32_e32 v38, 1.0, v38
	v_mul_f32_e32 v48, v34, v38
	v_and_b32_e32 v34, 0xffff0000, v40
	v_mul_f32_e32 v38, 0x3d372713, v34
	v_mul_f32_e32 v38, v38, v34
	v_fma_f32 v38, v38, v34, v34
	v_mul_f32_e32 v38, 0x3f4c422a, v38
	v_add_f32_e32 v38, v38, v38
	v_mul_f32_e32 v38, 0x3fb8aa3b, v38
	v_exp_f32_e32 v38, v38
	v_mul_f32_e32 v34, 0.5, v34
	v_add_f32_e32 v38, 1.0, v38
	v_div_scale_f32 v39, s[14:15], v38, v38, 2.0
	v_rcp_f32_e32 v40, v39
	s_nop 0
	v_fma_f32 v49, -v39, v40, 1.0
	v_fmac_f32_e32 v40, v49, v40
	v_div_scale_f32 v49, vcc, 2.0, v38, 2.0
	v_mul_f32_e32 v50, v49, v40
	v_fma_f32 v51, -v39, v50, v49
	v_fmac_f32_e32 v50, v51, v40
	v_fma_f32 v39, -v39, v50, v49
	v_div_fmas_f32 v39, v39, v40, v50
	v_div_fixup_f32 v38, v39, v38, 2.0
	v_sub_f32_e32 v38, 1.0, v38
	v_add_f32_e32 v38, 1.0, v38
	v_mul_f32_e32 v40, v34, v38
	v_lshlrev_b32_e32 v34, 16, v41
	v_mul_f32_e32 v38, 0x3d372713, v34
	v_mul_f32_e32 v38, v38, v34
	v_fma_f32 v38, v38, v34, v34
	v_mul_f32_e32 v38, 0x3f4c422a, v38
	v_add_f32_e32 v38, v38, v38
	v_mul_f32_e32 v38, 0x3fb8aa3b, v38
	v_exp_f32_e32 v38, v38
	v_mul_f32_e32 v34, 0.5, v34
	v_add_f32_e32 v38, 1.0, v38
	v_div_scale_f32 v39, s[14:15], v38, v38, 2.0
	v_rcp_f32_e32 v49, v39
	s_nop 0
	v_fma_f32 v50, -v39, v49, 1.0
	v_fmac_f32_e32 v49, v50, v49
	v_div_scale_f32 v50, vcc, 2.0, v38, 2.0
	v_mul_f32_e32 v51, v50, v49
	v_fma_f32 v52, -v39, v51, v50
	v_fmac_f32_e32 v51, v52, v49
	v_fma_f32 v39, -v39, v51, v50
	v_div_fmas_f32 v39, v39, v49, v51
	v_div_fixup_f32 v38, v39, v38, 2.0
	v_sub_f32_e32 v38, 1.0, v38
	v_add_f32_e32 v38, 1.0, v38
	v_mul_f32_e32 v49, v34, v38
	v_and_b32_e32 v34, 0xffff0000, v41
	v_mul_f32_e32 v38, 0x3d372713, v34
	v_mul_f32_e32 v38, v38, v34
	v_fma_f32 v38, v38, v34, v34
	v_mul_f32_e32 v38, 0x3f4c422a, v38
	v_add_f32_e32 v38, v38, v38
	v_mul_f32_e32 v38, 0x3fb8aa3b, v38
	v_exp_f32_e32 v38, v38
	v_mul_f32_e32 v34, 0.5, v34
	v_add_f32_e32 v38, 1.0, v38
	v_div_scale_f32 v39, s[14:15], v38, v38, 2.0
	v_rcp_f32_e32 v41, v39
	s_nop 0
	v_fma_f32 v50, -v39, v41, 1.0
	v_fmac_f32_e32 v41, v50, v41
	v_div_scale_f32 v50, vcc, 2.0, v38, 2.0
	v_mul_f32_e32 v51, v50, v41
	v_fma_f32 v52, -v39, v51, v50
	v_fmac_f32_e32 v51, v52, v41
	v_fma_f32 v39, -v39, v51, v50
	v_div_fmas_f32 v39, v39, v41, v51
	v_div_fixup_f32 v38, v39, v38, 2.0
	v_sub_f32_e32 v38, 1.0, v38
	v_add_f32_e32 v38, 1.0, v38
	v_mul_f32_e32 v41, v34, v38
	v_and_b32_e32 v34, 0xffff0000, v35
	v_lshlrev_b32_e32 v35, 16, v35
	v_mul_f32_e32 v38, 0x3d372713, v35
	v_mul_f32_e32 v38, v38, v35
	v_mov_b32_e32 v39, v35
	v_fmac_f32_e32 v39, v38, v39
	v_mul_f32_e32 v38, 0x3f4c422a, v39
	v_add_f32_e32 v38, v38, v38
	v_mul_f32_e32 v38, 0x3fb8aa3b, v38
	v_exp_f32_e32 v39, v38
	v_mul_f32_e32 v38, 0x3d372713, v34
	v_mul_f32_e32 v38, v38, v34
	v_mov_b32_e32 v51, v34
	v_fmac_f32_e32 v51, v38, v51
	v_mul_f32_e32 v38, 0x3f4c422a, v51
	v_add_f32_e32 v38, v38, v38
	v_mul_f32_e32 v38, 0x3fb8aa3b, v38
	v_exp_f32_e32 v38, v38
	v_pk_mul_f32 v[34:35], v[34:35], 0.5 op_sel_hi:[1,0]
	v_mul_f32_e32 v50, v45, v45
	v_fmac_f32_e32 v50, v44, v44
	v_pk_add_f32 v[38:39], v[38:39], 1.0 op_sel_hi:[1,0]
	s_nop 0
	v_div_scale_f32 v51, s[14:15], v39, v39, 2.0
	v_rcp_f32_e32 v52, v51
	s_nop 0
	v_fma_f32 v53, -v51, v52, 1.0
	v_fmac_f32_e32 v52, v53, v52
	v_div_scale_f32 v53, vcc, 2.0, v39, 2.0
	v_mul_f32_e32 v54, v53, v52
	v_fma_f32 v55, -v51, v54, v53
	v_fmac_f32_e32 v54, v55, v52
	v_fma_f32 v51, -v51, v54, v53
	v_div_fmas_f32 v51, v51, v52, v54
	v_div_fixup_f32 v39, v51, v39, 2.0
	v_div_scale_f32 v51, s[14:15], v38, v38, 2.0
	v_rcp_f32_e32 v52, v51
	s_nop 0
	v_fma_f32 v53, -v51, v52, 1.0
	v_fmac_f32_e32 v52, v53, v52
	v_div_scale_f32 v53, vcc, 2.0, v38, 2.0
	v_mul_f32_e32 v54, v53, v52
	v_fma_f32 v55, -v51, v54, v53
	v_fmac_f32_e32 v54, v55, v52
	v_fma_f32 v51, -v51, v54, v53
	v_div_fmas_f32 v51, v51, v52, v54
	v_div_fixup_f32 v38, v51, v38, 2.0
	v_pk_add_f32 v[38:39], v[38:39], 1.0 op_sel_hi:[1,0] neg_lo:[1,0] neg_hi:[1,0]
	s_nop 0
	v_pk_add_f32 v[38:39], v[38:39], 1.0 op_sel_hi:[1,0]
	s_nop 0
	v_pk_mul_f32 v[34:35], v[34:35], v[38:39]
	s_nop 0
	v_pk_mul_f32 v[38:39], v[34:35], v[34:35]
	s_nop 0
	v_add_f32_e32 v39, v39, v50
	v_add_f32_e32 v52, v38, v39
	v_lshlrev_b32_e32 v39, 16, v36
	v_and_b32_e32 v38, 0xffff0000, v36
	v_mul_f32_e32 v36, 0x3d372713, v39
	v_mul_f32_e32 v36, v36, v39
	v_mov_b32_e32 v50, v39
	v_fmac_f32_e32 v50, v36, v50
	v_mul_f32_e32 v36, 0x3f4c422a, v50
	v_add_f32_e32 v36, v36, v36
	v_mul_f32_e32 v36, 0x3fb8aa3b, v36
	v_exp_f32_e32 v51, v36
	v_mul_f32_e32 v36, 0x3d372713, v38
	v_mul_f32_e32 v36, v36, v38
	v_mov_b32_e32 v50, v38
	v_fmac_f32_e32 v50, v36, v50
	v_mul_f32_e32 v36, 0x3f4c422a, v50
	v_add_f32_e32 v36, v36, v36
	v_mul_f32_e32 v36, 0x3fb8aa3b, v36
	v_exp_f32_e32 v50, v36
	v_pk_mul_f32 v[38:39], v[38:39], 0.5 op_sel_hi:[1,0]
	v_pk_add_f32 v[50:51], v[50:51], 1.0 op_sel_hi:[1,0]
	s_nop 0
	v_div_scale_f32 v36, s[14:15], v51, v51, 2.0
	v_rcp_f32_e32 v53, v36
	s_nop 0
	v_fma_f32 v54, -v36, v53, 1.0
	v_fmac_f32_e32 v53, v54, v53
	v_div_scale_f32 v54, vcc, 2.0, v51, 2.0
	v_mul_f32_e32 v55, v54, v53
	v_fma_f32 v56, -v36, v55, v54
	v_fmac_f32_e32 v55, v56, v53
	v_fma_f32 v36, -v36, v55, v54
	v_div_fmas_f32 v36, v36, v53, v55
	v_div_fixup_f32 v51, v36, v51, 2.0
	v_div_scale_f32 v36, s[14:15], v50, v50, 2.0
	v_rcp_f32_e32 v53, v36
	s_nop 0
	v_fma_f32 v54, -v36, v53, 1.0
	v_fmac_f32_e32 v53, v54, v53
	v_div_scale_f32 v54, vcc, 2.0, v50, 2.0
	v_mul_f32_e32 v55, v54, v53
	v_fma_f32 v56, -v36, v55, v54
	v_fmac_f32_e32 v55, v56, v53
	v_fma_f32 v36, -v36, v55, v54
	v_div_fmas_f32 v36, v36, v53, v55
	v_div_fixup_f32 v50, v36, v50, 2.0
	v_pk_add_f32 v[50:51], v[50:51], 1.0 op_sel_hi:[1,0] neg_lo:[1,0] neg_hi:[1,0]
	s_nop 0
	v_pk_add_f32 v[50:51], v[50:51], 1.0 op_sel_hi:[1,0]
	s_nop 0
	v_pk_mul_f32 v[38:39], v[38:39], v[50:51]
	s_nop 0
	v_pk_mul_f32 v[50:51], v[38:39], v[38:39]
	s_nop 0
	v_add_f32_e32 v36, v51, v52
	v_add_f32_e32 v52, v50, v36
	v_and_b32_e32 v36, 0xffff0000, v37
	v_lshlrev_b32_e32 v37, 16, v37
	v_mul_f32_e32 v50, 0x3d372713, v37
	v_mul_f32_e32 v50, v50, v37
	v_mov_b32_e32 v51, v37
	v_fmac_f32_e32 v51, v50, v51
	v_mul_f32_e32 v50, 0x3f4c422a, v51
	v_add_f32_e32 v50, v50, v50
	v_mul_f32_e32 v50, 0x3fb8aa3b, v50
	v_exp_f32_e32 v51, v50
	v_mul_f32_e32 v50, 0x3d372713, v36
	v_mul_f32_e32 v50, v50, v36
	v_mov_b32_e32 v53, v36
	v_fmac_f32_e32 v53, v50, v53
	v_mul_f32_e32 v50, 0x3f4c422a, v53
	v_add_f32_e32 v50, v50, v50
	v_mul_f32_e32 v50, 0x3fb8aa3b, v50
	v_exp_f32_e32 v50, v50
	v_pk_mul_f32 v[36:37], v[36:37], 0.5 op_sel_hi:[1,0]
	v_pk_add_f32 v[50:51], v[50:51], 1.0 op_sel_hi:[1,0]
	s_nop 0
	v_div_scale_f32 v53, s[14:15], v51, v51, 2.0
	v_rcp_f32_e32 v54, v53
	s_nop 0
	v_fma_f32 v55, -v53, v54, 1.0
	v_fmac_f32_e32 v54, v55, v54
	v_div_scale_f32 v55, vcc, 2.0, v51, 2.0
	v_mul_f32_e32 v56, v55, v54
	v_fma_f32 v57, -v53, v56, v55
	v_fmac_f32_e32 v56, v57, v54
	v_fma_f32 v53, -v53, v56, v55
	v_div_fmas_f32 v53, v53, v54, v56
	v_div_fixup_f32 v51, v53, v51, 2.0
	v_div_scale_f32 v53, s[14:15], v50, v50, 2.0
	v_rcp_f32_e32 v54, v53
	s_nop 0
	v_fma_f32 v55, -v53, v54, 1.0
	v_fmac_f32_e32 v54, v55, v54
	v_div_scale_f32 v55, vcc, 2.0, v50, 2.0
	v_mul_f32_e32 v56, v55, v54
	v_fma_f32 v57, -v53, v56, v55
	v_fmac_f32_e32 v56, v57, v54
	v_fma_f32 v53, -v53, v56, v55
	v_div_fmas_f32 v53, v53, v54, v56
	v_div_fixup_f32 v50, v53, v50, 2.0
	v_pk_add_f32 v[50:51], v[50:51], 1.0 op_sel_hi:[1,0] neg_lo:[1,0] neg_hi:[1,0]
	s_nop 0
	v_pk_add_f32 v[50:51], v[50:51], 1.0 op_sel_hi:[1,0]
	s_nop 0
	v_pk_mul_f32 v[50:51], v[36:37], v[50:51]
	s_nop 0
	v_pk_mul_f32 v[36:37], v[50:51], v[50:51]
	s_nop 0
	v_add_f32_e32 v37, v37, v52
	v_add_f32_e32 v36, v36, v37
	ds_bpermute_b32 v37, v106, v36
	s_waitcnt lgkmcnt(0)
	v_add_f32_e32 v36, v36, v37
	ds_bpermute_b32 v37, v107, v36
	s_waitcnt lgkmcnt(0)
	v_add_f32_e32 v36, v36, v37
	ds_bpermute_b32 v37, v108, v36
	s_waitcnt lgkmcnt(0)
	v_add_f32_e32 v36, v36, v37
	ds_bpermute_b32 v37, v109, v36
	s_waitcnt lgkmcnt(0)
	v_add_f32_e32 v36, v36, v37
	ds_bpermute_b32 v37, v110, v36
	s_waitcnt lgkmcnt(0)
	v_add_f32_e32 v36, v36, v37
	v_fmamk_f32 v36, v36, 0x3b800000, v243
	v_cmp_gt_f32_e32 vcc, s3, v36
	v_mul_f32_e32 v37, 0x4b800000, v36
	s_nop 0
	v_cndmask_b32_e32 v36, v36, v37, vcc
	v_rsq_f32_e32 v36, v36
	s_nop 0
	v_mul_f32_e32 v37, 0x45800000, v36
	v_cndmask_b32_e32 v52, v36, v37, vcc
	v_mul_f32_e32 v36, v44, v52
	v_mul_f32_e32 v37, v45, v52
	v_mul_f32_e32 v34, v34, v52
	v_mul_f32_e32 v36, v70, v36
	v_mul_f32_e32 v37, v71, v37
	v_mul_f32_e32 v35, v35, v52
	v_mul_f32_e32 v34, v73, v34
	v_cvt_pk_bf16_f32 v36, v36, v37
	v_cvt_pk_bf16_f32 v43, v46, v47
	v_mul_f32_e32 v35, v72, v35
	v_cvt_pk_bf16_f32 v37, v35, v34
	v_mul_f32_e32 v34, v39, v52
	v_mul_f32_e32 v34, v66, v34
	v_mul_f32_e32 v35, v38, v52
	v_cvt_pk_bf16_f32 v44, v48, v40
	v_mul_f32_e32 v35, v67, v35
	v_cvt_pk_bf16_f32 v38, v34, v35
	v_mul_f32_e32 v34, v51, v52
	v_mul_f32_e32 v34, v68, v34
	v_mul_f32_e32 v35, v50, v52
	v_cvt_pk_bf16_f32 v45, v49, v41
	v_mul_f32_e32 v35, v69, v35
	v_cvt_pk_bf16_f32 v39, v34, v35
	v_lshlrev_b32_e32 v34, 16, v30
	v_mul_f32_e32 v35, 0x3d372713, v34
	v_mul_f32_e32 v35, v35, v34
	v_fma_f32 v35, v35, v34, v34
	v_mul_f32_e32 v35, 0x3f4c422a, v35
	v_add_f32_e32 v35, v35, v35
	v_mul_f32_e32 v35, 0x3fb8aa3b, v35
	v_exp_f32_e32 v35, v35
	ds_write_b128 v111, v[42:45] offset:26112
	ds_write_b128 v112, v[36:39] offset:26112
	v_mul_f32_e32 v34, 0.5, v34
	v_and_b32_e32 v30, 0xffff0000, v30
	v_add_f32_e32 v35, 1.0, v35
	v_div_scale_f32 v36, s[14:15], v35, v35, 2.0
	v_rcp_f32_e32 v37, v36
	s_nop 0
	v_fma_f32 v38, -v36, v37, 1.0
	v_fmac_f32_e32 v37, v38, v37
	v_div_scale_f32 v38, vcc, 2.0, v35, 2.0
	v_mul_f32_e32 v39, v38, v37
	v_fma_f32 v40, -v36, v39, v38
	v_fmac_f32_e32 v39, v40, v37
	v_fma_f32 v36, -v36, v39, v38
	v_div_fmas_f32 v36, v36, v37, v39
	v_div_fixup_f32 v35, v36, v35, 2.0
	v_sub_f32_e32 v35, 1.0, v35
	v_add_f32_e32 v35, 1.0, v35
	v_mul_f32_e32 v34, v34, v35
	v_mul_f32_e32 v35, 0x3d372713, v30
	v_mul_f32_e32 v35, v35, v30
	v_fma_f32 v35, v35, v30, v30
	v_mul_f32_e32 v35, 0x3f4c422a, v35
	v_add_f32_e32 v35, v35, v35
	v_mul_f32_e32 v35, 0x3fb8aa3b, v35
	v_exp_f32_e32 v35, v35
	v_mul_f32_e32 v30, 0.5, v30
	v_add_f32_e32 v35, 1.0, v35
	v_div_scale_f32 v36, s[14:15], v35, v35, 2.0
	v_rcp_f32_e32 v37, v36
	s_nop 0
	v_fma_f32 v38, -v36, v37, 1.0
	v_fmac_f32_e32 v37, v38, v37
	v_div_scale_f32 v38, vcc, 2.0, v35, 2.0
	v_mul_f32_e32 v39, v38, v37
	v_fma_f32 v40, -v36, v39, v38
	v_fmac_f32_e32 v39, v40, v37
	v_fma_f32 v36, -v36, v39, v38
	v_div_fmas_f32 v36, v36, v37, v39
	v_div_fixup_f32 v35, v36, v35, 2.0
	v_sub_f32_e32 v35, 1.0, v35
	v_add_f32_e32 v35, 1.0, v35
	v_mul_f32_e32 v35, v30, v35
	v_lshlrev_b32_e32 v30, 16, v26
	v_mul_f32_e32 v36, 0x3d372713, v30
	v_mul_f32_e32 v36, v36, v30
	v_fma_f32 v36, v36, v30, v30
	v_mul_f32_e32 v36, 0x3f4c422a, v36
	v_add_f32_e32 v36, v36, v36
	v_mul_f32_e32 v36, 0x3fb8aa3b, v36
	v_exp_f32_e32 v36, v36
	v_mul_f32_e32 v30, 0.5, v30
	v_and_b32_e32 v26, 0xffff0000, v26
	v_cvt_pk_bf16_f32 v34, v34, v35
	v_add_f32_e32 v36, 1.0, v36
	v_div_scale_f32 v37, s[14:15], v36, v36, 2.0
	v_rcp_f32_e32 v38, v37
	s_nop 0
	v_fma_f32 v39, -v37, v38, 1.0
	v_fmac_f32_e32 v38, v39, v38
	v_div_scale_f32 v39, vcc, 2.0, v36, 2.0
	v_mul_f32_e32 v40, v39, v38
	v_fma_f32 v41, -v37, v40, v39
	v_fmac_f32_e32 v40, v41, v38
	v_fma_f32 v37, -v37, v40, v39
	v_div_fmas_f32 v37, v37, v38, v40
	v_div_fixup_f32 v36, v37, v36, 2.0
	v_sub_f32_e32 v36, 1.0, v36
	v_add_f32_e32 v36, 1.0, v36
	v_mul_f32_e32 v36, v30, v36
	v_mul_f32_e32 v30, 0x3d372713, v26
	v_mul_f32_e32 v30, v30, v26
	v_fma_f32 v30, v30, v26, v26
	v_mul_f32_e32 v30, 0x3f4c422a, v30
	v_add_f32_e32 v30, v30, v30
	v_mul_f32_e32 v30, 0x3fb8aa3b, v30
	v_exp_f32_e32 v30, v30
	v_mul_f32_e32 v26, 0.5, v26
	v_add_f32_e32 v30, 1.0, v30
	v_div_scale_f32 v37, s[14:15], v30, v30, 2.0
	v_rcp_f32_e32 v38, v37
	s_nop 0
	v_fma_f32 v39, -v37, v38, 1.0
	v_fmac_f32_e32 v38, v39, v38
	v_div_scale_f32 v39, vcc, 2.0, v30, 2.0
	v_mul_f32_e32 v40, v39, v38
	v_fma_f32 v41, -v37, v40, v39
	v_fmac_f32_e32 v40, v41, v38
	v_fma_f32 v37, -v37, v40, v39
	v_div_fmas_f32 v37, v37, v38, v40
	v_div_fixup_f32 v30, v37, v30, 2.0
	v_sub_f32_e32 v30, 1.0, v30
	v_add_f32_e32 v30, 1.0, v30
	v_mul_f32_e32 v37, v26, v30
	v_lshlrev_b32_e32 v26, 16, v31
	v_mul_f32_e32 v30, 0x3d372713, v26
	v_mul_f32_e32 v30, v30, v26
	v_fma_f32 v30, v30, v26, v26
	v_mul_f32_e32 v30, 0x3f4c422a, v30
	v_add_f32_e32 v30, v30, v30
	v_mul_f32_e32 v30, 0x3fb8aa3b, v30
	v_exp_f32_e32 v30, v30
	v_mul_f32_e32 v26, 0.5, v26
	v_add_f32_e32 v30, 1.0, v30
	v_div_scale_f32 v38, s[14:15], v30, v30, 2.0
	v_rcp_f32_e32 v39, v38
	s_nop 0
	v_fma_f32 v40, -v38, v39, 1.0
	v_fmac_f32_e32 v39, v40, v39
	v_div_scale_f32 v40, vcc, 2.0, v30, 2.0
	v_mul_f32_e32 v41, v40, v39
	v_fma_f32 v42, -v38, v41, v40
	v_fmac_f32_e32 v41, v42, v39
	v_fma_f32 v38, -v38, v41, v40
	v_div_fmas_f32 v38, v38, v39, v41
	v_div_fixup_f32 v30, v38, v30, 2.0
	v_sub_f32_e32 v30, 1.0, v30
	v_add_f32_e32 v30, 1.0, v30
	v_mul_f32_e32 v38, v26, v30
	v_and_b32_e32 v26, 0xffff0000, v31
	v_mul_f32_e32 v30, 0x3d372713, v26
	v_mul_f32_e32 v30, v30, v26
	v_fma_f32 v30, v30, v26, v26
	v_mul_f32_e32 v30, 0x3f4c422a, v30
	v_add_f32_e32 v30, v30, v30
	v_mul_f32_e32 v30, 0x3fb8aa3b, v30
	v_exp_f32_e32 v30, v30
	v_mul_f32_e32 v26, 0.5, v26
	v_add_f32_e32 v30, 1.0, v30
	v_div_scale_f32 v31, s[14:15], v30, v30, 2.0
	v_rcp_f32_e32 v39, v31
	s_nop 0
	v_fma_f32 v40, -v31, v39, 1.0
	v_fmac_f32_e32 v39, v40, v39
	v_div_scale_f32 v40, vcc, 2.0, v30, 2.0
	v_mul_f32_e32 v41, v40, v39
	v_fma_f32 v42, -v31, v41, v40
	v_fmac_f32_e32 v41, v42, v39
	v_fma_f32 v31, -v31, v41, v40
	v_div_fmas_f32 v31, v31, v39, v41
	v_div_fixup_f32 v30, v31, v30, 2.0
	v_sub_f32_e32 v30, 1.0, v30
	v_add_f32_e32 v30, 1.0, v30
	v_mul_f32_e32 v39, v26, v30
	v_lshlrev_b32_e32 v26, 16, v32
	v_mul_f32_e32 v30, 0x3d372713, v26
	v_mul_f32_e32 v30, v30, v26
	v_fma_f32 v30, v30, v26, v26
	v_mul_f32_e32 v30, 0x3f4c422a, v30
	v_add_f32_e32 v30, v30, v30
	v_mul_f32_e32 v30, 0x3fb8aa3b, v30
	v_exp_f32_e32 v30, v30
	v_mul_f32_e32 v26, 0.5, v26
	v_add_f32_e32 v30, 1.0, v30
	v_div_scale_f32 v31, s[14:15], v30, v30, 2.0
	v_rcp_f32_e32 v40, v31
	s_nop 0
	v_fma_f32 v41, -v31, v40, 1.0
	v_fmac_f32_e32 v40, v41, v40
	v_div_scale_f32 v41, vcc, 2.0, v30, 2.0
	v_mul_f32_e32 v42, v41, v40
	v_fma_f32 v43, -v31, v42, v41
	v_fmac_f32_e32 v42, v43, v40
	v_fma_f32 v31, -v31, v42, v41
	v_div_fmas_f32 v31, v31, v40, v42
	v_div_fixup_f32 v30, v31, v30, 2.0
	v_sub_f32_e32 v30, 1.0, v30
	v_add_f32_e32 v30, 1.0, v30
	v_mul_f32_e32 v40, v26, v30
	v_and_b32_e32 v26, 0xffff0000, v32
	v_mul_f32_e32 v30, 0x3d372713, v26
	v_mul_f32_e32 v30, v30, v26
	v_fma_f32 v30, v30, v26, v26
	v_mul_f32_e32 v30, 0x3f4c422a, v30
	v_add_f32_e32 v30, v30, v30
	v_mul_f32_e32 v30, 0x3fb8aa3b, v30
	v_exp_f32_e32 v30, v30
	v_mul_f32_e32 v26, 0.5, v26
	v_add_f32_e32 v30, 1.0, v30
	v_div_scale_f32 v31, s[14:15], v30, v30, 2.0
	v_rcp_f32_e32 v32, v31
	s_nop 0
	v_fma_f32 v41, -v31, v32, 1.0
	v_fmac_f32_e32 v32, v41, v32
	v_div_scale_f32 v41, vcc, 2.0, v30, 2.0
	v_mul_f32_e32 v42, v41, v32
	v_fma_f32 v43, -v31, v42, v41
	v_fmac_f32_e32 v42, v43, v32
	v_fma_f32 v31, -v31, v42, v41
	v_div_fmas_f32 v31, v31, v32, v42
	v_div_fixup_f32 v30, v31, v30, 2.0
	v_sub_f32_e32 v30, 1.0, v30
	v_add_f32_e32 v30, 1.0, v30
	v_mul_f32_e32 v32, v26, v30
	v_lshlrev_b32_e32 v26, 16, v33
	v_mul_f32_e32 v30, 0x3d372713, v26
	v_mul_f32_e32 v30, v30, v26
	v_fma_f32 v30, v30, v26, v26
	v_mul_f32_e32 v30, 0x3f4c422a, v30
	v_add_f32_e32 v30, v30, v30
	v_mul_f32_e32 v30, 0x3fb8aa3b, v30
	v_exp_f32_e32 v30, v30
	v_mul_f32_e32 v26, 0.5, v26
	v_add_f32_e32 v30, 1.0, v30
	v_div_scale_f32 v31, s[14:15], v30, v30, 2.0
	v_rcp_f32_e32 v41, v31
	s_nop 0
	v_fma_f32 v42, -v31, v41, 1.0
	v_fmac_f32_e32 v41, v42, v41
	v_div_scale_f32 v42, vcc, 2.0, v30, 2.0
	v_mul_f32_e32 v43, v42, v41
	v_fma_f32 v44, -v31, v43, v42
	v_fmac_f32_e32 v43, v44, v41
	v_fma_f32 v31, -v31, v43, v42
	v_div_fmas_f32 v31, v31, v41, v43
	v_div_fixup_f32 v30, v31, v30, 2.0
	v_sub_f32_e32 v30, 1.0, v30
	v_add_f32_e32 v30, 1.0, v30
	v_mul_f32_e32 v41, v26, v30
	v_and_b32_e32 v26, 0xffff0000, v33
	v_mul_f32_e32 v30, 0x3d372713, v26
	v_mul_f32_e32 v30, v30, v26
	v_fma_f32 v30, v30, v26, v26
	v_mul_f32_e32 v30, 0x3f4c422a, v30
	v_add_f32_e32 v30, v30, v30
	v_mul_f32_e32 v30, 0x3fb8aa3b, v30
	v_exp_f32_e32 v30, v30
	v_mul_f32_e32 v26, 0.5, v26
	v_add_f32_e32 v30, 1.0, v30
	v_div_scale_f32 v31, s[14:15], v30, v30, 2.0
	v_rcp_f32_e32 v33, v31
	s_nop 0
	v_fma_f32 v42, -v31, v33, 1.0
	v_fmac_f32_e32 v33, v42, v33
	v_div_scale_f32 v42, vcc, 2.0, v30, 2.0
	v_mul_f32_e32 v43, v42, v33
	v_fma_f32 v44, -v31, v43, v42
	v_fmac_f32_e32 v43, v44, v33
	v_fma_f32 v31, -v31, v43, v42
	v_div_fmas_f32 v31, v31, v33, v43
	v_div_fixup_f32 v30, v31, v30, 2.0
	v_sub_f32_e32 v30, 1.0, v30
	v_add_f32_e32 v30, 1.0, v30
	v_mul_f32_e32 v33, v26, v30
	v_and_b32_e32 v26, 0xffff0000, v27
	v_lshlrev_b32_e32 v27, 16, v27
	v_mul_f32_e32 v30, 0x3d372713, v27
	v_mul_f32_e32 v30, v30, v27
	v_mov_b32_e32 v31, v27
	v_fmac_f32_e32 v31, v30, v31
	v_mul_f32_e32 v30, 0x3f4c422a, v31
	v_add_f32_e32 v30, v30, v30
	v_mul_f32_e32 v30, 0x3fb8aa3b, v30
	v_exp_f32_e32 v31, v30
	v_mul_f32_e32 v30, 0x3d372713, v26
	v_mul_f32_e32 v30, v30, v26
	v_mov_b32_e32 v43, v26
	v_fmac_f32_e32 v43, v30, v43
	v_mul_f32_e32 v30, 0x3f4c422a, v43
	v_add_f32_e32 v30, v30, v30
	v_mul_f32_e32 v30, 0x3fb8aa3b, v30
	v_exp_f32_e32 v30, v30
	v_pk_mul_f32 v[26:27], v[26:27], 0.5 op_sel_hi:[1,0]
	v_mul_f32_e32 v42, v37, v37
	v_fmac_f32_e32 v42, v36, v36
	v_pk_add_f32 v[30:31], v[30:31], 1.0 op_sel_hi:[1,0]
	s_nop 0
	v_div_scale_f32 v43, s[14:15], v31, v31, 2.0
	v_rcp_f32_e32 v44, v43
	s_nop 0
	v_fma_f32 v45, -v43, v44, 1.0
	v_fmac_f32_e32 v44, v45, v44
	v_div_scale_f32 v45, vcc, 2.0, v31, 2.0
	v_mul_f32_e32 v46, v45, v44
	v_fma_f32 v47, -v43, v46, v45
	v_fmac_f32_e32 v46, v47, v44
	v_fma_f32 v43, -v43, v46, v45
	v_div_fmas_f32 v43, v43, v44, v46
	v_div_fixup_f32 v31, v43, v31, 2.0
	v_div_scale_f32 v43, s[14:15], v30, v30, 2.0
	v_rcp_f32_e32 v44, v43
	s_nop 0
	v_fma_f32 v45, -v43, v44, 1.0
	v_fmac_f32_e32 v44, v45, v44
	v_div_scale_f32 v45, vcc, 2.0, v30, 2.0
	v_mul_f32_e32 v46, v45, v44
	v_fma_f32 v47, -v43, v46, v45
	v_fmac_f32_e32 v46, v47, v44
	v_fma_f32 v43, -v43, v46, v45
	v_div_fmas_f32 v43, v43, v44, v46
	v_div_fixup_f32 v30, v43, v30, 2.0
	v_pk_add_f32 v[30:31], v[30:31], 1.0 op_sel_hi:[1,0] neg_lo:[1,0] neg_hi:[1,0]
	s_nop 0
	v_pk_add_f32 v[30:31], v[30:31], 1.0 op_sel_hi:[1,0]
	s_nop 0
	v_pk_mul_f32 v[26:27], v[26:27], v[30:31]
	s_nop 0
	v_pk_mul_f32 v[30:31], v[26:27], v[26:27]
	s_nop 0
	v_add_f32_e32 v31, v31, v42
	v_add_f32_e32 v44, v30, v31
	v_lshlrev_b32_e32 v31, 16, v28
	v_and_b32_e32 v30, 0xffff0000, v28
	v_mul_f32_e32 v28, 0x3d372713, v31
	v_mul_f32_e32 v28, v28, v31
	v_mov_b32_e32 v42, v31
	v_fmac_f32_e32 v42, v28, v42
	v_mul_f32_e32 v28, 0x3f4c422a, v42
	v_add_f32_e32 v28, v28, v28
	v_mul_f32_e32 v28, 0x3fb8aa3b, v28
	v_exp_f32_e32 v43, v28
	v_mul_f32_e32 v28, 0x3d372713, v30
	v_mul_f32_e32 v28, v28, v30
	v_mov_b32_e32 v42, v30
	v_fmac_f32_e32 v42, v28, v42
	v_mul_f32_e32 v28, 0x3f4c422a, v42
	v_add_f32_e32 v28, v28, v28
	v_mul_f32_e32 v28, 0x3fb8aa3b, v28
	v_exp_f32_e32 v42, v28
	v_pk_mul_f32 v[30:31], v[30:31], 0.5 op_sel_hi:[1,0]
	v_pk_add_f32 v[42:43], v[42:43], 1.0 op_sel_hi:[1,0]
	s_nop 0
	v_div_scale_f32 v28, s[14:15], v43, v43, 2.0
	v_rcp_f32_e32 v45, v28
	s_nop 0
	v_fma_f32 v46, -v28, v45, 1.0
	v_fmac_f32_e32 v45, v46, v45
	v_div_scale_f32 v46, vcc, 2.0, v43, 2.0
	v_mul_f32_e32 v47, v46, v45
	v_fma_f32 v48, -v28, v47, v46
	v_fmac_f32_e32 v47, v48, v45
	v_fma_f32 v28, -v28, v47, v46
	v_div_fmas_f32 v28, v28, v45, v47
	v_div_fixup_f32 v43, v28, v43, 2.0
	v_div_scale_f32 v28, s[14:15], v42, v42, 2.0
	v_rcp_f32_e32 v45, v28
	s_nop 0
	v_fma_f32 v46, -v28, v45, 1.0
	v_fmac_f32_e32 v45, v46, v45
	v_div_scale_f32 v46, vcc, 2.0, v42, 2.0
	v_mul_f32_e32 v47, v46, v45
	v_fma_f32 v48, -v28, v47, v46
	v_fmac_f32_e32 v47, v48, v45
	v_fma_f32 v28, -v28, v47, v46
	v_div_fmas_f32 v28, v28, v45, v47
	v_div_fixup_f32 v42, v28, v42, 2.0
	v_pk_add_f32 v[42:43], v[42:43], 1.0 op_sel_hi:[1,0] neg_lo:[1,0] neg_hi:[1,0]
	s_nop 0
	v_pk_add_f32 v[42:43], v[42:43], 1.0 op_sel_hi:[1,0]
	s_nop 0
	v_pk_mul_f32 v[30:31], v[30:31], v[42:43]
	s_nop 0
	v_pk_mul_f32 v[42:43], v[30:31], v[30:31]
	s_nop 0
	v_add_f32_e32 v28, v43, v44
	v_add_f32_e32 v44, v42, v28
	v_and_b32_e32 v28, 0xffff0000, v29
	v_lshlrev_b32_e32 v29, 16, v29
	v_mul_f32_e32 v42, 0x3d372713, v29
	v_mul_f32_e32 v42, v42, v29
	v_mov_b32_e32 v43, v29
	v_fmac_f32_e32 v43, v42, v43
	v_mul_f32_e32 v42, 0x3f4c422a, v43
	v_add_f32_e32 v42, v42, v42
	v_mul_f32_e32 v42, 0x3fb8aa3b, v42
	v_exp_f32_e32 v43, v42
	v_mul_f32_e32 v42, 0x3d372713, v28
	v_mul_f32_e32 v42, v42, v28
	v_mov_b32_e32 v45, v28
	v_fmac_f32_e32 v45, v42, v45
	v_mul_f32_e32 v42, 0x3f4c422a, v45
	v_add_f32_e32 v42, v42, v42
	v_mul_f32_e32 v42, 0x3fb8aa3b, v42
	v_exp_f32_e32 v42, v42
	v_pk_mul_f32 v[28:29], v[28:29], 0.5 op_sel_hi:[1,0]
	v_pk_add_f32 v[42:43], v[42:43], 1.0 op_sel_hi:[1,0]
	s_nop 0
	v_div_scale_f32 v45, s[14:15], v43, v43, 2.0
	v_rcp_f32_e32 v46, v45
	s_nop 0
	v_fma_f32 v47, -v45, v46, 1.0
	v_fmac_f32_e32 v46, v47, v46
	v_div_scale_f32 v47, vcc, 2.0, v43, 2.0
	v_mul_f32_e32 v48, v47, v46
	v_fma_f32 v49, -v45, v48, v47
	v_fmac_f32_e32 v48, v49, v46
	v_fma_f32 v45, -v45, v48, v47
	v_div_fmas_f32 v45, v45, v46, v48
	v_div_fixup_f32 v43, v45, v43, 2.0
	v_div_scale_f32 v45, s[14:15], v42, v42, 2.0
	v_rcp_f32_e32 v46, v45
	s_nop 0
	v_fma_f32 v47, -v45, v46, 1.0
	v_fmac_f32_e32 v46, v47, v46
	v_div_scale_f32 v47, vcc, 2.0, v42, 2.0
	v_mul_f32_e32 v48, v47, v46
	v_fma_f32 v49, -v45, v48, v47
	v_fmac_f32_e32 v48, v49, v46
	v_fma_f32 v45, -v45, v48, v47
	v_div_fmas_f32 v45, v45, v46, v48
	v_div_fixup_f32 v42, v45, v42, 2.0
	v_pk_add_f32 v[42:43], v[42:43], 1.0 op_sel_hi:[1,0] neg_lo:[1,0] neg_hi:[1,0]
	s_nop 0
	v_pk_add_f32 v[42:43], v[42:43], 1.0 op_sel_hi:[1,0]
	s_nop 0
	v_pk_mul_f32 v[42:43], v[28:29], v[42:43]
	s_nop 0
	v_pk_mul_f32 v[28:29], v[42:43], v[42:43]
	s_nop 0
	v_add_f32_e32 v29, v29, v44
	v_add_f32_e32 v28, v28, v29
	ds_bpermute_b32 v29, v106, v28
	s_waitcnt lgkmcnt(0)
	v_add_f32_e32 v28, v28, v29
	ds_bpermute_b32 v29, v107, v28
	s_waitcnt lgkmcnt(0)
	v_add_f32_e32 v28, v28, v29
	ds_bpermute_b32 v29, v108, v28
	s_waitcnt lgkmcnt(0)
	v_add_f32_e32 v28, v28, v29
	ds_bpermute_b32 v29, v109, v28
	s_waitcnt lgkmcnt(0)
	v_add_f32_e32 v28, v28, v29
	ds_bpermute_b32 v29, v110, v28
	s_waitcnt lgkmcnt(0)
	v_add_f32_e32 v28, v28, v29
	v_fmamk_f32 v28, v28, 0x3b800000, v243
	v_cmp_gt_f32_e32 vcc, s3, v28
	v_mul_f32_e32 v29, 0x4b800000, v28
	s_nop 0
	v_cndmask_b32_e32 v28, v28, v29, vcc
	v_rsq_f32_e32 v28, v28
	s_nop 0
	v_mul_f32_e32 v29, 0x45800000, v28
	v_cndmask_b32_e32 v44, v28, v29, vcc
	v_mul_f32_e32 v28, v36, v44
	v_mul_f32_e32 v29, v37, v44
	v_mul_f32_e32 v26, v26, v44
	v_mul_f32_e32 v28, v70, v28
	v_mul_f32_e32 v29, v71, v29
	v_mul_f32_e32 v27, v27, v44
	v_mul_f32_e32 v26, v73, v26
	v_cvt_pk_bf16_f32 v28, v28, v29
	v_cvt_pk_bf16_f32 v35, v38, v39
	v_mul_f32_e32 v27, v72, v27
	v_cvt_pk_bf16_f32 v29, v27, v26
	v_mul_f32_e32 v26, v31, v44
	v_mul_f32_e32 v26, v66, v26
	v_mul_f32_e32 v27, v30, v44
	v_cvt_pk_bf16_f32 v36, v40, v32
	v_mul_f32_e32 v27, v67, v27
	v_cvt_pk_bf16_f32 v30, v26, v27
	v_mul_f32_e32 v26, v43, v44
	v_mul_f32_e32 v26, v68, v26
	v_mul_f32_e32 v27, v42, v44
	v_cvt_pk_bf16_f32 v37, v41, v33
	v_mul_f32_e32 v27, v69, v27
	v_cvt_pk_bf16_f32 v31, v26, v27
	v_lshlrev_b32_e32 v26, 16, v22
	v_mul_f32_e32 v27, 0x3d372713, v26
	v_mul_f32_e32 v27, v27, v26
	v_fma_f32 v27, v27, v26, v26
	v_mul_f32_e32 v27, 0x3f4c422a, v27
	v_add_f32_e32 v27, v27, v27
	v_mul_f32_e32 v27, 0x3fb8aa3b, v27
	v_exp_f32_e32 v27, v27
	ds_write_b128 v111, v[34:37] offset:34816
	ds_write_b128 v112, v[28:31] offset:34816
	v_mul_f32_e32 v26, 0.5, v26
	v_and_b32_e32 v22, 0xffff0000, v22
	v_add_f32_e32 v27, 1.0, v27
	v_div_scale_f32 v28, s[14:15], v27, v27, 2.0
	v_rcp_f32_e32 v29, v28
	s_nop 0
	v_fma_f32 v30, -v28, v29, 1.0
	v_fmac_f32_e32 v29, v30, v29
	v_div_scale_f32 v30, vcc, 2.0, v27, 2.0
	v_mul_f32_e32 v31, v30, v29
	v_fma_f32 v32, -v28, v31, v30
	v_fmac_f32_e32 v31, v32, v29
	v_fma_f32 v28, -v28, v31, v30
	v_div_fmas_f32 v28, v28, v29, v31
	v_div_fixup_f32 v27, v28, v27, 2.0
	v_sub_f32_e32 v27, 1.0, v27
	v_add_f32_e32 v27, 1.0, v27
	v_mul_f32_e32 v26, v26, v27
	v_mul_f32_e32 v27, 0x3d372713, v22
	v_mul_f32_e32 v27, v27, v22
	v_fma_f32 v27, v27, v22, v22
	v_mul_f32_e32 v27, 0x3f4c422a, v27
	v_add_f32_e32 v27, v27, v27
	v_mul_f32_e32 v27, 0x3fb8aa3b, v27
	v_exp_f32_e32 v27, v27
	v_mul_f32_e32 v22, 0.5, v22
	v_add_f32_e32 v27, 1.0, v27
	v_div_scale_f32 v28, s[14:15], v27, v27, 2.0
	v_rcp_f32_e32 v29, v28
	s_nop 0
	v_fma_f32 v30, -v28, v29, 1.0
	v_fmac_f32_e32 v29, v30, v29
	v_div_scale_f32 v30, vcc, 2.0, v27, 2.0
	v_mul_f32_e32 v31, v30, v29
	v_fma_f32 v32, -v28, v31, v30
	v_fmac_f32_e32 v31, v32, v29
	v_fma_f32 v28, -v28, v31, v30
	v_div_fmas_f32 v28, v28, v29, v31
	v_div_fixup_f32 v27, v28, v27, 2.0
	v_sub_f32_e32 v27, 1.0, v27
	v_add_f32_e32 v27, 1.0, v27
	v_mul_f32_e32 v27, v22, v27
	v_lshlrev_b32_e32 v22, 16, v18
	v_mul_f32_e32 v28, 0x3d372713, v22
	v_mul_f32_e32 v28, v28, v22
	v_fma_f32 v28, v28, v22, v22
	v_mul_f32_e32 v28, 0x3f4c422a, v28
	v_add_f32_e32 v28, v28, v28
	v_mul_f32_e32 v28, 0x3fb8aa3b, v28
	v_exp_f32_e32 v28, v28
	v_mul_f32_e32 v22, 0.5, v22
	v_and_b32_e32 v18, 0xffff0000, v18
	v_cvt_pk_bf16_f32 v26, v26, v27
	v_add_f32_e32 v28, 1.0, v28
	v_div_scale_f32 v29, s[14:15], v28, v28, 2.0
	v_rcp_f32_e32 v30, v29
	s_nop 0
	v_fma_f32 v31, -v29, v30, 1.0
	v_fmac_f32_e32 v30, v31, v30
	v_div_scale_f32 v31, vcc, 2.0, v28, 2.0
	v_mul_f32_e32 v32, v31, v30
	v_fma_f32 v33, -v29, v32, v31
	v_fmac_f32_e32 v32, v33, v30
	v_fma_f32 v29, -v29, v32, v31
	v_div_fmas_f32 v29, v29, v30, v32
	v_div_fixup_f32 v28, v29, v28, 2.0
	v_sub_f32_e32 v28, 1.0, v28
	v_add_f32_e32 v28, 1.0, v28
	v_mul_f32_e32 v28, v22, v28
	v_mul_f32_e32 v22, 0x3d372713, v18
	v_mul_f32_e32 v22, v22, v18
	v_fma_f32 v22, v22, v18, v18
	v_mul_f32_e32 v22, 0x3f4c422a, v22
	v_add_f32_e32 v22, v22, v22
	v_mul_f32_e32 v22, 0x3fb8aa3b, v22
	v_exp_f32_e32 v22, v22
	v_mul_f32_e32 v18, 0.5, v18
	v_add_f32_e32 v22, 1.0, v22
	v_div_scale_f32 v29, s[14:15], v22, v22, 2.0
	v_rcp_f32_e32 v30, v29
	s_nop 0
	v_fma_f32 v31, -v29, v30, 1.0
	v_fmac_f32_e32 v30, v31, v30
	v_div_scale_f32 v31, vcc, 2.0, v22, 2.0
	v_mul_f32_e32 v32, v31, v30
	v_fma_f32 v33, -v29, v32, v31
	v_fmac_f32_e32 v32, v33, v30
	v_fma_f32 v29, -v29, v32, v31
	v_div_fmas_f32 v29, v29, v30, v32
	v_div_fixup_f32 v22, v29, v22, 2.0
	v_sub_f32_e32 v22, 1.0, v22
	v_add_f32_e32 v22, 1.0, v22
	v_mul_f32_e32 v29, v18, v22
	v_lshlrev_b32_e32 v18, 16, v23
	v_mul_f32_e32 v22, 0x3d372713, v18
	v_mul_f32_e32 v22, v22, v18
	v_fma_f32 v22, v22, v18, v18
	v_mul_f32_e32 v22, 0x3f4c422a, v22
	v_add_f32_e32 v22, v22, v22
	v_mul_f32_e32 v22, 0x3fb8aa3b, v22
	v_exp_f32_e32 v22, v22
	v_mul_f32_e32 v18, 0.5, v18
	v_add_f32_e32 v22, 1.0, v22
	v_div_scale_f32 v30, s[14:15], v22, v22, 2.0
	v_rcp_f32_e32 v31, v30
	s_nop 0
	v_fma_f32 v32, -v30, v31, 1.0
	v_fmac_f32_e32 v31, v32, v31
	v_div_scale_f32 v32, vcc, 2.0, v22, 2.0
	v_mul_f32_e32 v33, v32, v31
	v_fma_f32 v34, -v30, v33, v32
	v_fmac_f32_e32 v33, v34, v31
	v_fma_f32 v30, -v30, v33, v32
	v_div_fmas_f32 v30, v30, v31, v33
	v_div_fixup_f32 v22, v30, v22, 2.0
	v_sub_f32_e32 v22, 1.0, v22
	v_add_f32_e32 v22, 1.0, v22
	v_mul_f32_e32 v30, v18, v22
	v_and_b32_e32 v18, 0xffff0000, v23
	v_mul_f32_e32 v22, 0x3d372713, v18
	v_mul_f32_e32 v22, v22, v18
	v_fma_f32 v22, v22, v18, v18
	v_mul_f32_e32 v22, 0x3f4c422a, v22
	v_add_f32_e32 v22, v22, v22
	v_mul_f32_e32 v22, 0x3fb8aa3b, v22
	v_exp_f32_e32 v22, v22
	v_mul_f32_e32 v18, 0.5, v18
	v_add_f32_e32 v22, 1.0, v22
	v_div_scale_f32 v23, s[14:15], v22, v22, 2.0
	v_rcp_f32_e32 v31, v23
	s_nop 0
	v_fma_f32 v32, -v23, v31, 1.0
	v_fmac_f32_e32 v31, v32, v31
	v_div_scale_f32 v32, vcc, 2.0, v22, 2.0
	v_mul_f32_e32 v33, v32, v31
	v_fma_f32 v34, -v23, v33, v32
	v_fmac_f32_e32 v33, v34, v31
	v_fma_f32 v23, -v23, v33, v32
	v_div_fmas_f32 v23, v23, v31, v33
	v_div_fixup_f32 v22, v23, v22, 2.0
	v_sub_f32_e32 v22, 1.0, v22
	v_add_f32_e32 v22, 1.0, v22
	v_mul_f32_e32 v31, v18, v22
	v_lshlrev_b32_e32 v18, 16, v24
	v_mul_f32_e32 v22, 0x3d372713, v18
	v_mul_f32_e32 v22, v22, v18
	v_fma_f32 v22, v22, v18, v18
	v_mul_f32_e32 v22, 0x3f4c422a, v22
	v_add_f32_e32 v22, v22, v22
	v_mul_f32_e32 v22, 0x3fb8aa3b, v22
	v_exp_f32_e32 v22, v22
	v_mul_f32_e32 v18, 0.5, v18
	v_add_f32_e32 v22, 1.0, v22
	v_div_scale_f32 v23, s[14:15], v22, v22, 2.0
	v_rcp_f32_e32 v32, v23
	s_nop 0
	v_fma_f32 v33, -v23, v32, 1.0
	v_fmac_f32_e32 v32, v33, v32
	v_div_scale_f32 v33, vcc, 2.0, v22, 2.0
	v_mul_f32_e32 v34, v33, v32
	v_fma_f32 v35, -v23, v34, v33
	v_fmac_f32_e32 v34, v35, v32
	v_fma_f32 v23, -v23, v34, v33
	v_div_fmas_f32 v23, v23, v32, v34
	v_div_fixup_f32 v22, v23, v22, 2.0
	v_sub_f32_e32 v22, 1.0, v22
	v_add_f32_e32 v22, 1.0, v22
	v_mul_f32_e32 v32, v18, v22
	v_and_b32_e32 v18, 0xffff0000, v24
	v_mul_f32_e32 v22, 0x3d372713, v18
	v_mul_f32_e32 v22, v22, v18
	v_fma_f32 v22, v22, v18, v18
	v_mul_f32_e32 v22, 0x3f4c422a, v22
	v_add_f32_e32 v22, v22, v22
	v_mul_f32_e32 v22, 0x3fb8aa3b, v22
	v_exp_f32_e32 v22, v22
	v_mul_f32_e32 v18, 0.5, v18
	v_add_f32_e32 v22, 1.0, v22
	v_div_scale_f32 v23, s[14:15], v22, v22, 2.0
	v_rcp_f32_e32 v24, v23
	s_nop 0
	v_fma_f32 v33, -v23, v24, 1.0
	v_fmac_f32_e32 v24, v33, v24
	v_div_scale_f32 v33, vcc, 2.0, v22, 2.0
	v_mul_f32_e32 v34, v33, v24
	v_fma_f32 v35, -v23, v34, v33
	v_fmac_f32_e32 v34, v35, v24
	v_fma_f32 v23, -v23, v34, v33
	v_div_fmas_f32 v23, v23, v24, v34
	v_div_fixup_f32 v22, v23, v22, 2.0
	v_sub_f32_e32 v22, 1.0, v22
	v_add_f32_e32 v22, 1.0, v22
	v_mul_f32_e32 v24, v18, v22
	v_lshlrev_b32_e32 v18, 16, v25
	v_mul_f32_e32 v22, 0x3d372713, v18
	v_mul_f32_e32 v22, v22, v18
	v_fma_f32 v22, v22, v18, v18
	v_mul_f32_e32 v22, 0x3f4c422a, v22
	v_add_f32_e32 v22, v22, v22
	v_mul_f32_e32 v22, 0x3fb8aa3b, v22
	v_exp_f32_e32 v22, v22
	v_mul_f32_e32 v18, 0.5, v18
	v_add_f32_e32 v22, 1.0, v22
	v_div_scale_f32 v23, s[14:15], v22, v22, 2.0
	v_rcp_f32_e32 v33, v23
	s_nop 0
	v_fma_f32 v34, -v23, v33, 1.0
	v_fmac_f32_e32 v33, v34, v33
	v_div_scale_f32 v34, vcc, 2.0, v22, 2.0
	v_mul_f32_e32 v35, v34, v33
	v_fma_f32 v36, -v23, v35, v34
	v_fmac_f32_e32 v35, v36, v33
	v_fma_f32 v23, -v23, v35, v34
	v_div_fmas_f32 v23, v23, v33, v35
	v_div_fixup_f32 v22, v23, v22, 2.0
	v_sub_f32_e32 v22, 1.0, v22
	v_add_f32_e32 v22, 1.0, v22
	v_mul_f32_e32 v33, v18, v22
	v_and_b32_e32 v18, 0xffff0000, v25
	v_mul_f32_e32 v22, 0x3d372713, v18
	v_mul_f32_e32 v22, v22, v18
	v_fma_f32 v22, v22, v18, v18
	v_mul_f32_e32 v22, 0x3f4c422a, v22
	v_add_f32_e32 v22, v22, v22
	v_mul_f32_e32 v22, 0x3fb8aa3b, v22
	v_exp_f32_e32 v22, v22
	v_mul_f32_e32 v18, 0.5, v18
	v_add_f32_e32 v22, 1.0, v22
	v_div_scale_f32 v23, s[14:15], v22, v22, 2.0
	v_rcp_f32_e32 v25, v23
	s_nop 0
	v_fma_f32 v34, -v23, v25, 1.0
	v_fmac_f32_e32 v25, v34, v25
	v_div_scale_f32 v34, vcc, 2.0, v22, 2.0
	v_mul_f32_e32 v35, v34, v25
	v_fma_f32 v36, -v23, v35, v34
	v_fmac_f32_e32 v35, v36, v25
	v_fma_f32 v23, -v23, v35, v34
	v_div_fmas_f32 v23, v23, v25, v35
	v_div_fixup_f32 v22, v23, v22, 2.0
	v_sub_f32_e32 v22, 1.0, v22
	v_add_f32_e32 v22, 1.0, v22
	v_mul_f32_e32 v25, v18, v22
	v_and_b32_e32 v18, 0xffff0000, v19
	v_lshlrev_b32_e32 v19, 16, v19
	v_mul_f32_e32 v22, 0x3d372713, v19
	v_mul_f32_e32 v22, v22, v19
	v_mov_b32_e32 v23, v19
	v_fmac_f32_e32 v23, v22, v23
	v_mul_f32_e32 v22, 0x3f4c422a, v23
	v_add_f32_e32 v22, v22, v22
	v_mul_f32_e32 v22, 0x3fb8aa3b, v22
	v_exp_f32_e32 v23, v22
	v_mul_f32_e32 v22, 0x3d372713, v18
	v_mul_f32_e32 v22, v22, v18
	v_mov_b32_e32 v35, v18
	v_fmac_f32_e32 v35, v22, v35
	v_mul_f32_e32 v22, 0x3f4c422a, v35
	v_add_f32_e32 v22, v22, v22
	v_mul_f32_e32 v22, 0x3fb8aa3b, v22
	v_exp_f32_e32 v22, v22
	v_pk_mul_f32 v[18:19], v[18:19], 0.5 op_sel_hi:[1,0]
	v_mul_f32_e32 v34, v29, v29
	v_fmac_f32_e32 v34, v28, v28
	v_pk_add_f32 v[22:23], v[22:23], 1.0 op_sel_hi:[1,0]
	s_nop 0
	v_div_scale_f32 v35, s[14:15], v23, v23, 2.0
	v_rcp_f32_e32 v36, v35
	s_nop 0
	v_fma_f32 v37, -v35, v36, 1.0
	v_fmac_f32_e32 v36, v37, v36
	v_div_scale_f32 v37, vcc, 2.0, v23, 2.0
	v_mul_f32_e32 v38, v37, v36
	v_fma_f32 v39, -v35, v38, v37
	v_fmac_f32_e32 v38, v39, v36
	v_fma_f32 v35, -v35, v38, v37
	v_div_fmas_f32 v35, v35, v36, v38
	v_div_fixup_f32 v23, v35, v23, 2.0
	v_div_scale_f32 v35, s[14:15], v22, v22, 2.0
	v_rcp_f32_e32 v36, v35
	s_nop 0
	v_fma_f32 v37, -v35, v36, 1.0
	v_fmac_f32_e32 v36, v37, v36
	v_div_scale_f32 v37, vcc, 2.0, v22, 2.0
	v_mul_f32_e32 v38, v37, v36
	v_fma_f32 v39, -v35, v38, v37
	v_fmac_f32_e32 v38, v39, v36
	v_fma_f32 v35, -v35, v38, v37
	v_div_fmas_f32 v35, v35, v36, v38
	v_div_fixup_f32 v22, v35, v22, 2.0
	v_pk_add_f32 v[22:23], v[22:23], 1.0 op_sel_hi:[1,0] neg_lo:[1,0] neg_hi:[1,0]
	s_nop 0
	v_pk_add_f32 v[22:23], v[22:23], 1.0 op_sel_hi:[1,0]
	s_nop 0
	v_pk_mul_f32 v[18:19], v[18:19], v[22:23]
	s_nop 0
	v_pk_mul_f32 v[22:23], v[18:19], v[18:19]
	s_nop 0
	v_add_f32_e32 v23, v23, v34
	v_add_f32_e32 v36, v22, v23
	v_lshlrev_b32_e32 v23, 16, v20
	v_and_b32_e32 v22, 0xffff0000, v20
	v_mul_f32_e32 v20, 0x3d372713, v23
	v_mul_f32_e32 v20, v20, v23
	v_mov_b32_e32 v34, v23
	v_fmac_f32_e32 v34, v20, v34
	v_mul_f32_e32 v20, 0x3f4c422a, v34
	v_add_f32_e32 v20, v20, v20
	v_mul_f32_e32 v20, 0x3fb8aa3b, v20
	v_exp_f32_e32 v35, v20
	v_mul_f32_e32 v20, 0x3d372713, v22
	v_mul_f32_e32 v20, v20, v22
	v_mov_b32_e32 v34, v22
	v_fmac_f32_e32 v34, v20, v34
	v_mul_f32_e32 v20, 0x3f4c422a, v34
	v_add_f32_e32 v20, v20, v20
	v_mul_f32_e32 v20, 0x3fb8aa3b, v20
	v_exp_f32_e32 v34, v20
	v_pk_mul_f32 v[22:23], v[22:23], 0.5 op_sel_hi:[1,0]
	v_pk_add_f32 v[34:35], v[34:35], 1.0 op_sel_hi:[1,0]
	s_nop 0
	v_div_scale_f32 v20, s[14:15], v35, v35, 2.0
	v_rcp_f32_e32 v37, v20
	s_nop 0
	v_fma_f32 v38, -v20, v37, 1.0
	v_fmac_f32_e32 v37, v38, v37
	v_div_scale_f32 v38, vcc, 2.0, v35, 2.0
	v_mul_f32_e32 v39, v38, v37
	v_fma_f32 v40, -v20, v39, v38
	v_fmac_f32_e32 v39, v40, v37
	v_fma_f32 v20, -v20, v39, v38
	v_div_fmas_f32 v20, v20, v37, v39
	v_div_fixup_f32 v35, v20, v35, 2.0
	v_div_scale_f32 v20, s[14:15], v34, v34, 2.0
	v_rcp_f32_e32 v37, v20
	s_nop 0
	v_fma_f32 v38, -v20, v37, 1.0
	v_fmac_f32_e32 v37, v38, v37
	v_div_scale_f32 v38, vcc, 2.0, v34, 2.0
	v_mul_f32_e32 v39, v38, v37
	v_fma_f32 v40, -v20, v39, v38
	v_fmac_f32_e32 v39, v40, v37
	v_fma_f32 v20, -v20, v39, v38
	v_div_fmas_f32 v20, v20, v37, v39
	v_div_fixup_f32 v34, v20, v34, 2.0
	v_pk_add_f32 v[34:35], v[34:35], 1.0 op_sel_hi:[1,0] neg_lo:[1,0] neg_hi:[1,0]
	s_nop 0
	v_pk_add_f32 v[34:35], v[34:35], 1.0 op_sel_hi:[1,0]
	s_nop 0
	v_pk_mul_f32 v[22:23], v[22:23], v[34:35]
	s_nop 0
	v_pk_mul_f32 v[34:35], v[22:23], v[22:23]
	s_nop 0
	v_add_f32_e32 v20, v35, v36
	v_add_f32_e32 v36, v34, v20
	v_and_b32_e32 v20, 0xffff0000, v21
	v_lshlrev_b32_e32 v21, 16, v21
	v_mul_f32_e32 v34, 0x3d372713, v21
	v_mul_f32_e32 v34, v34, v21
	v_mov_b32_e32 v35, v21
	v_fmac_f32_e32 v35, v34, v35
	v_mul_f32_e32 v34, 0x3f4c422a, v35
	v_add_f32_e32 v34, v34, v34
	v_mul_f32_e32 v34, 0x3fb8aa3b, v34
	v_exp_f32_e32 v35, v34
	v_mul_f32_e32 v34, 0x3d372713, v20
	v_mul_f32_e32 v34, v34, v20
	v_mov_b32_e32 v37, v20
	v_fmac_f32_e32 v37, v34, v37
	v_mul_f32_e32 v34, 0x3f4c422a, v37
	v_add_f32_e32 v34, v34, v34
	v_mul_f32_e32 v34, 0x3fb8aa3b, v34
	v_exp_f32_e32 v34, v34
	v_pk_mul_f32 v[20:21], v[20:21], 0.5 op_sel_hi:[1,0]
	v_pk_add_f32 v[34:35], v[34:35], 1.0 op_sel_hi:[1,0]
	s_nop 0
	v_div_scale_f32 v37, s[14:15], v35, v35, 2.0
	v_rcp_f32_e32 v38, v37
	s_nop 0
	v_fma_f32 v39, -v37, v38, 1.0
	v_fmac_f32_e32 v38, v39, v38
	v_div_scale_f32 v39, vcc, 2.0, v35, 2.0
	v_mul_f32_e32 v40, v39, v38
	v_fma_f32 v41, -v37, v40, v39
	v_fmac_f32_e32 v40, v41, v38
	v_fma_f32 v37, -v37, v40, v39
	v_div_fmas_f32 v37, v37, v38, v40
	v_div_fixup_f32 v35, v37, v35, 2.0
	v_div_scale_f32 v37, s[14:15], v34, v34, 2.0
	v_rcp_f32_e32 v38, v37
	s_nop 0
	v_fma_f32 v39, -v37, v38, 1.0
	v_fmac_f32_e32 v38, v39, v38
	v_div_scale_f32 v39, vcc, 2.0, v34, 2.0
	v_mul_f32_e32 v40, v39, v38
	v_fma_f32 v41, -v37, v40, v39
	v_fmac_f32_e32 v40, v41, v38
	v_fma_f32 v37, -v37, v40, v39
	v_div_fmas_f32 v37, v37, v38, v40
	v_div_fixup_f32 v34, v37, v34, 2.0
	v_pk_add_f32 v[34:35], v[34:35], 1.0 op_sel_hi:[1,0] neg_lo:[1,0] neg_hi:[1,0]
	s_nop 0
	v_pk_add_f32 v[34:35], v[34:35], 1.0 op_sel_hi:[1,0]
	s_nop 0
	v_pk_mul_f32 v[34:35], v[20:21], v[34:35]
	s_nop 0
	v_pk_mul_f32 v[20:21], v[34:35], v[34:35]
	s_nop 0
	v_add_f32_e32 v21, v21, v36
	v_add_f32_e32 v20, v20, v21
	ds_bpermute_b32 v21, v106, v20
	s_waitcnt lgkmcnt(0)
	v_add_f32_e32 v20, v20, v21
	ds_bpermute_b32 v21, v107, v20
	s_waitcnt lgkmcnt(0)
	v_add_f32_e32 v20, v20, v21
	ds_bpermute_b32 v21, v108, v20
	s_waitcnt lgkmcnt(0)
	v_add_f32_e32 v20, v20, v21
	ds_bpermute_b32 v21, v109, v20
	s_waitcnt lgkmcnt(0)
	v_add_f32_e32 v20, v20, v21
	ds_bpermute_b32 v21, v110, v20
	s_waitcnt lgkmcnt(0)
	v_add_f32_e32 v20, v20, v21
	v_fmamk_f32 v20, v20, 0x3b800000, v243
	v_cmp_gt_f32_e32 vcc, s3, v20
	v_mul_f32_e32 v21, 0x4b800000, v20
	s_nop 0
	v_cndmask_b32_e32 v20, v20, v21, vcc
	v_rsq_f32_e32 v20, v20
	s_nop 0
	v_mul_f32_e32 v21, 0x45800000, v20
	v_cndmask_b32_e32 v36, v20, v21, vcc
	v_mul_f32_e32 v20, v28, v36
	v_mul_f32_e32 v21, v29, v36
	v_mul_f32_e32 v18, v18, v36
	v_mul_f32_e32 v20, v70, v20
	v_mul_f32_e32 v21, v71, v21
	v_mul_f32_e32 v19, v19, v36
	v_mul_f32_e32 v18, v73, v18
	v_cvt_pk_bf16_f32 v20, v20, v21
	v_cvt_pk_bf16_f32 v27, v30, v31
	v_mul_f32_e32 v19, v72, v19
	v_cvt_pk_bf16_f32 v21, v19, v18
	v_mul_f32_e32 v18, v23, v36
	v_mul_f32_e32 v18, v66, v18
	v_mul_f32_e32 v19, v22, v36
	v_cvt_pk_bf16_f32 v28, v32, v24
	v_mul_f32_e32 v19, v67, v19
	v_cvt_pk_bf16_f32 v22, v18, v19
	v_mul_f32_e32 v18, v35, v36
	v_mul_f32_e32 v18, v68, v18
	v_mul_f32_e32 v19, v34, v36
	v_cvt_pk_bf16_f32 v29, v33, v25
	v_mul_f32_e32 v19, v69, v19
	v_cvt_pk_bf16_f32 v23, v18, v19
	v_lshlrev_b32_e32 v18, 16, v14
	v_mul_f32_e32 v19, 0x3d372713, v18
	v_mul_f32_e32 v19, v19, v18
	v_fma_f32 v19, v19, v18, v18
	v_mul_f32_e32 v19, 0x3f4c422a, v19
	v_add_f32_e32 v19, v19, v19
	v_mul_f32_e32 v19, 0x3fb8aa3b, v19
	v_exp_f32_e32 v19, v19
	ds_write_b128 v111, v[26:29] offset:43520
	ds_write_b128 v112, v[20:23] offset:43520
	v_mul_f32_e32 v18, 0.5, v18
	v_and_b32_e32 v14, 0xffff0000, v14
	v_add_f32_e32 v19, 1.0, v19
	v_div_scale_f32 v20, s[14:15], v19, v19, 2.0
	v_rcp_f32_e32 v21, v20
	s_nop 0
	v_fma_f32 v22, -v20, v21, 1.0
	v_fmac_f32_e32 v21, v22, v21
	v_div_scale_f32 v22, vcc, 2.0, v19, 2.0
	v_mul_f32_e32 v23, v22, v21
	v_fma_f32 v24, -v20, v23, v22
	v_fmac_f32_e32 v23, v24, v21
	v_fma_f32 v20, -v20, v23, v22
	v_div_fmas_f32 v20, v20, v21, v23
	v_div_fixup_f32 v19, v20, v19, 2.0
	v_sub_f32_e32 v19, 1.0, v19
	v_add_f32_e32 v19, 1.0, v19
	v_mul_f32_e32 v18, v18, v19
	v_mul_f32_e32 v19, 0x3d372713, v14
	v_mul_f32_e32 v19, v19, v14
	v_fma_f32 v19, v19, v14, v14
	v_mul_f32_e32 v19, 0x3f4c422a, v19
	v_add_f32_e32 v19, v19, v19
	v_mul_f32_e32 v19, 0x3fb8aa3b, v19
	v_exp_f32_e32 v19, v19
	v_mul_f32_e32 v14, 0.5, v14
	v_add_f32_e32 v19, 1.0, v19
	v_div_scale_f32 v20, s[14:15], v19, v19, 2.0
	v_rcp_f32_e32 v21, v20
	s_nop 0
	v_fma_f32 v22, -v20, v21, 1.0
	v_fmac_f32_e32 v21, v22, v21
	v_div_scale_f32 v22, vcc, 2.0, v19, 2.0
	v_mul_f32_e32 v23, v22, v21
	v_fma_f32 v24, -v20, v23, v22
	v_fmac_f32_e32 v23, v24, v21
	v_fma_f32 v20, -v20, v23, v22
	v_div_fmas_f32 v20, v20, v21, v23
	v_div_fixup_f32 v19, v20, v19, 2.0
	v_sub_f32_e32 v19, 1.0, v19
	v_add_f32_e32 v19, 1.0, v19
	v_mul_f32_e32 v19, v14, v19
	v_lshlrev_b32_e32 v14, 16, v10
	v_mul_f32_e32 v20, 0x3d372713, v14
	v_mul_f32_e32 v20, v20, v14
	v_fma_f32 v20, v20, v14, v14
	v_mul_f32_e32 v20, 0x3f4c422a, v20
	v_add_f32_e32 v20, v20, v20
	v_mul_f32_e32 v20, 0x3fb8aa3b, v20
	v_exp_f32_e32 v20, v20
	v_mul_f32_e32 v14, 0.5, v14
	v_and_b32_e32 v10, 0xffff0000, v10
	v_cvt_pk_bf16_f32 v18, v18, v19
	v_add_f32_e32 v20, 1.0, v20
	v_div_scale_f32 v21, s[14:15], v20, v20, 2.0
	v_rcp_f32_e32 v22, v21
	s_nop 0
	v_fma_f32 v23, -v21, v22, 1.0
	v_fmac_f32_e32 v22, v23, v22
	v_div_scale_f32 v23, vcc, 2.0, v20, 2.0
	v_mul_f32_e32 v24, v23, v22
	v_fma_f32 v25, -v21, v24, v23
	v_fmac_f32_e32 v24, v25, v22
	v_fma_f32 v21, -v21, v24, v23
	v_div_fmas_f32 v21, v21, v22, v24
	v_div_fixup_f32 v20, v21, v20, 2.0
	v_sub_f32_e32 v20, 1.0, v20
	v_add_f32_e32 v20, 1.0, v20
	v_mul_f32_e32 v20, v14, v20
	v_mul_f32_e32 v14, 0x3d372713, v10
	v_mul_f32_e32 v14, v14, v10
	v_fma_f32 v14, v14, v10, v10
	v_mul_f32_e32 v14, 0x3f4c422a, v14
	v_add_f32_e32 v14, v14, v14
	v_mul_f32_e32 v14, 0x3fb8aa3b, v14
	v_exp_f32_e32 v14, v14
	v_mul_f32_e32 v10, 0.5, v10
	v_add_f32_e32 v14, 1.0, v14
	v_div_scale_f32 v21, s[14:15], v14, v14, 2.0
	v_rcp_f32_e32 v22, v21
	s_nop 0
	v_fma_f32 v23, -v21, v22, 1.0
	v_fmac_f32_e32 v22, v23, v22
	v_div_scale_f32 v23, vcc, 2.0, v14, 2.0
	v_mul_f32_e32 v24, v23, v22
	v_fma_f32 v25, -v21, v24, v23
	v_fmac_f32_e32 v24, v25, v22
	v_fma_f32 v21, -v21, v24, v23
	v_div_fmas_f32 v21, v21, v22, v24
	v_div_fixup_f32 v14, v21, v14, 2.0
	v_sub_f32_e32 v14, 1.0, v14
	v_add_f32_e32 v14, 1.0, v14
	v_mul_f32_e32 v21, v10, v14
	v_lshlrev_b32_e32 v10, 16, v15
	v_mul_f32_e32 v14, 0x3d372713, v10
	v_mul_f32_e32 v14, v14, v10
	v_fma_f32 v14, v14, v10, v10
	v_mul_f32_e32 v14, 0x3f4c422a, v14
	v_add_f32_e32 v14, v14, v14
	v_mul_f32_e32 v14, 0x3fb8aa3b, v14
	v_exp_f32_e32 v14, v14
	v_mul_f32_e32 v10, 0.5, v10
	v_add_f32_e32 v14, 1.0, v14
	v_div_scale_f32 v22, s[14:15], v14, v14, 2.0
	v_rcp_f32_e32 v23, v22
	s_nop 0
	v_fma_f32 v24, -v22, v23, 1.0
	v_fmac_f32_e32 v23, v24, v23
	v_div_scale_f32 v24, vcc, 2.0, v14, 2.0
	v_mul_f32_e32 v25, v24, v23
	v_fma_f32 v26, -v22, v25, v24
	v_fmac_f32_e32 v25, v26, v23
	v_fma_f32 v22, -v22, v25, v24
	v_div_fmas_f32 v22, v22, v23, v25
	v_div_fixup_f32 v14, v22, v14, 2.0
	v_sub_f32_e32 v14, 1.0, v14
	v_add_f32_e32 v14, 1.0, v14
	v_mul_f32_e32 v22, v10, v14
	v_and_b32_e32 v10, 0xffff0000, v15
	v_mul_f32_e32 v14, 0x3d372713, v10
	v_mul_f32_e32 v14, v14, v10
	v_fma_f32 v14, v14, v10, v10
	v_mul_f32_e32 v14, 0x3f4c422a, v14
	v_add_f32_e32 v14, v14, v14
	v_mul_f32_e32 v14, 0x3fb8aa3b, v14
	v_exp_f32_e32 v14, v14
	v_mul_f32_e32 v10, 0.5, v10
	v_add_f32_e32 v14, 1.0, v14
	v_div_scale_f32 v15, s[14:15], v14, v14, 2.0
	v_rcp_f32_e32 v23, v15
	s_nop 0
	v_fma_f32 v24, -v15, v23, 1.0
	v_fmac_f32_e32 v23, v24, v23
	v_div_scale_f32 v24, vcc, 2.0, v14, 2.0
	v_mul_f32_e32 v25, v24, v23
	v_fma_f32 v26, -v15, v25, v24
	v_fmac_f32_e32 v25, v26, v23
	v_fma_f32 v15, -v15, v25, v24
	v_div_fmas_f32 v15, v15, v23, v25
	v_div_fixup_f32 v14, v15, v14, 2.0
	v_sub_f32_e32 v14, 1.0, v14
	v_add_f32_e32 v14, 1.0, v14
	v_mul_f32_e32 v23, v10, v14
	v_lshlrev_b32_e32 v10, 16, v16
	v_mul_f32_e32 v14, 0x3d372713, v10
	v_mul_f32_e32 v14, v14, v10
	v_fma_f32 v14, v14, v10, v10
	v_mul_f32_e32 v14, 0x3f4c422a, v14
	v_add_f32_e32 v14, v14, v14
	v_mul_f32_e32 v14, 0x3fb8aa3b, v14
	v_exp_f32_e32 v14, v14
	v_mul_f32_e32 v10, 0.5, v10
	v_add_f32_e32 v14, 1.0, v14
	v_div_scale_f32 v15, s[14:15], v14, v14, 2.0
	v_rcp_f32_e32 v24, v15
	s_nop 0
	v_fma_f32 v25, -v15, v24, 1.0
	v_fmac_f32_e32 v24, v25, v24
	v_div_scale_f32 v25, vcc, 2.0, v14, 2.0
	v_mul_f32_e32 v26, v25, v24
	v_fma_f32 v27, -v15, v26, v25
	v_fmac_f32_e32 v26, v27, v24
	v_fma_f32 v15, -v15, v26, v25
	v_div_fmas_f32 v15, v15, v24, v26
	v_div_fixup_f32 v14, v15, v14, 2.0
	v_sub_f32_e32 v14, 1.0, v14
	v_add_f32_e32 v14, 1.0, v14
	v_mul_f32_e32 v24, v10, v14
	v_and_b32_e32 v10, 0xffff0000, v16
	v_mul_f32_e32 v14, 0x3d372713, v10
	v_mul_f32_e32 v14, v14, v10
	v_fma_f32 v14, v14, v10, v10
	v_mul_f32_e32 v14, 0x3f4c422a, v14
	v_add_f32_e32 v14, v14, v14
	v_mul_f32_e32 v14, 0x3fb8aa3b, v14
	v_exp_f32_e32 v14, v14
	v_mul_f32_e32 v10, 0.5, v10
	v_add_f32_e32 v14, 1.0, v14
	v_div_scale_f32 v15, s[14:15], v14, v14, 2.0
	v_rcp_f32_e32 v16, v15
	s_nop 0
	v_fma_f32 v25, -v15, v16, 1.0
	v_fmac_f32_e32 v16, v25, v16
	v_div_scale_f32 v25, vcc, 2.0, v14, 2.0
	v_mul_f32_e32 v26, v25, v16
	v_fma_f32 v27, -v15, v26, v25
	v_fmac_f32_e32 v26, v27, v16
	v_fma_f32 v15, -v15, v26, v25
	v_div_fmas_f32 v15, v15, v16, v26
	v_div_fixup_f32 v14, v15, v14, 2.0
	v_sub_f32_e32 v14, 1.0, v14
	v_add_f32_e32 v14, 1.0, v14
	v_mul_f32_e32 v16, v10, v14
	v_lshlrev_b32_e32 v10, 16, v17
	v_mul_f32_e32 v14, 0x3d372713, v10
	v_mul_f32_e32 v14, v14, v10
	v_fma_f32 v14, v14, v10, v10
	v_mul_f32_e32 v14, 0x3f4c422a, v14
	v_add_f32_e32 v14, v14, v14
	v_mul_f32_e32 v14, 0x3fb8aa3b, v14
	v_exp_f32_e32 v14, v14
	v_mul_f32_e32 v10, 0.5, v10
	v_add_f32_e32 v14, 1.0, v14
	v_div_scale_f32 v15, s[14:15], v14, v14, 2.0
	v_rcp_f32_e32 v25, v15
	s_nop 0
	v_fma_f32 v26, -v15, v25, 1.0
	v_fmac_f32_e32 v25, v26, v25
	v_div_scale_f32 v26, vcc, 2.0, v14, 2.0
	v_mul_f32_e32 v27, v26, v25
	v_fma_f32 v28, -v15, v27, v26
	v_fmac_f32_e32 v27, v28, v25
	v_fma_f32 v15, -v15, v27, v26
	v_div_fmas_f32 v15, v15, v25, v27
	v_div_fixup_f32 v14, v15, v14, 2.0
	v_sub_f32_e32 v14, 1.0, v14
	v_add_f32_e32 v14, 1.0, v14
	v_mul_f32_e32 v25, v10, v14
	v_and_b32_e32 v10, 0xffff0000, v17
	v_mul_f32_e32 v14, 0x3d372713, v10
	v_mul_f32_e32 v14, v14, v10
	v_fma_f32 v14, v14, v10, v10
	v_mul_f32_e32 v14, 0x3f4c422a, v14
	v_add_f32_e32 v14, v14, v14
	v_mul_f32_e32 v14, 0x3fb8aa3b, v14
	v_exp_f32_e32 v14, v14
	v_mul_f32_e32 v10, 0.5, v10
	v_add_f32_e32 v14, 1.0, v14
	v_div_scale_f32 v15, s[14:15], v14, v14, 2.0
	v_rcp_f32_e32 v17, v15
	s_nop 0
	v_fma_f32 v26, -v15, v17, 1.0
	v_fmac_f32_e32 v17, v26, v17
	v_div_scale_f32 v26, vcc, 2.0, v14, 2.0
	v_mul_f32_e32 v27, v26, v17
	v_fma_f32 v28, -v15, v27, v26
	v_fmac_f32_e32 v27, v28, v17
	v_fma_f32 v15, -v15, v27, v26
	v_div_fmas_f32 v15, v15, v17, v27
	v_div_fixup_f32 v14, v15, v14, 2.0
	v_sub_f32_e32 v14, 1.0, v14
	v_add_f32_e32 v14, 1.0, v14
	v_mul_f32_e32 v17, v10, v14
	v_and_b32_e32 v10, 0xffff0000, v11
	v_lshlrev_b32_e32 v11, 16, v11
	v_mul_f32_e32 v14, 0x3d372713, v11
	v_mul_f32_e32 v14, v14, v11
	v_mov_b32_e32 v15, v11
	v_fmac_f32_e32 v15, v14, v15
	v_mul_f32_e32 v14, 0x3f4c422a, v15
	v_add_f32_e32 v14, v14, v14
	v_mul_f32_e32 v14, 0x3fb8aa3b, v14
	v_exp_f32_e32 v15, v14
	v_mul_f32_e32 v14, 0x3d372713, v10
	v_mul_f32_e32 v14, v14, v10
	v_mov_b32_e32 v27, v10
	v_fmac_f32_e32 v27, v14, v27
	v_mul_f32_e32 v14, 0x3f4c422a, v27
	v_add_f32_e32 v14, v14, v14
	v_mul_f32_e32 v14, 0x3fb8aa3b, v14
	v_exp_f32_e32 v14, v14
	v_pk_mul_f32 v[10:11], v[10:11], 0.5 op_sel_hi:[1,0]
	v_mul_f32_e32 v26, v21, v21
	v_fmac_f32_e32 v26, v20, v20
	v_pk_add_f32 v[14:15], v[14:15], 1.0 op_sel_hi:[1,0]
	s_nop 0
	v_div_scale_f32 v27, s[14:15], v15, v15, 2.0
	v_rcp_f32_e32 v28, v27
	s_nop 0
	v_fma_f32 v29, -v27, v28, 1.0
	v_fmac_f32_e32 v28, v29, v28
	v_div_scale_f32 v29, vcc, 2.0, v15, 2.0
	v_mul_f32_e32 v30, v29, v28
	v_fma_f32 v31, -v27, v30, v29
	v_fmac_f32_e32 v30, v31, v28
	v_fma_f32 v27, -v27, v30, v29
	v_div_fmas_f32 v27, v27, v28, v30
	v_div_fixup_f32 v15, v27, v15, 2.0
	v_div_scale_f32 v27, s[14:15], v14, v14, 2.0
	v_rcp_f32_e32 v28, v27
	s_nop 0
	v_fma_f32 v29, -v27, v28, 1.0
	v_fmac_f32_e32 v28, v29, v28
	v_div_scale_f32 v29, vcc, 2.0, v14, 2.0
	v_mul_f32_e32 v30, v29, v28
	v_fma_f32 v31, -v27, v30, v29
	v_fmac_f32_e32 v30, v31, v28
	v_fma_f32 v27, -v27, v30, v29
	v_div_fmas_f32 v27, v27, v28, v30
	v_div_fixup_f32 v14, v27, v14, 2.0
	v_pk_add_f32 v[14:15], v[14:15], 1.0 op_sel_hi:[1,0] neg_lo:[1,0] neg_hi:[1,0]
	s_nop 0
	v_pk_add_f32 v[14:15], v[14:15], 1.0 op_sel_hi:[1,0]
	s_nop 0
	v_pk_mul_f32 v[10:11], v[10:11], v[14:15]
	s_nop 0
	v_pk_mul_f32 v[14:15], v[10:11], v[10:11]
	s_nop 0
	v_add_f32_e32 v15, v15, v26
	v_add_f32_e32 v28, v14, v15
	v_lshlrev_b32_e32 v15, 16, v12
	v_and_b32_e32 v14, 0xffff0000, v12
	v_mul_f32_e32 v12, 0x3d372713, v15
	v_mul_f32_e32 v12, v12, v15
	v_mov_b32_e32 v26, v15
	v_fmac_f32_e32 v26, v12, v26
	v_mul_f32_e32 v12, 0x3f4c422a, v26
	v_add_f32_e32 v12, v12, v12
	v_mul_f32_e32 v12, 0x3fb8aa3b, v12
	v_exp_f32_e32 v27, v12
	v_mul_f32_e32 v12, 0x3d372713, v14
	v_mul_f32_e32 v12, v12, v14
	v_mov_b32_e32 v26, v14
	v_fmac_f32_e32 v26, v12, v26
	v_mul_f32_e32 v12, 0x3f4c422a, v26
	v_add_f32_e32 v12, v12, v12
	v_mul_f32_e32 v12, 0x3fb8aa3b, v12
	v_exp_f32_e32 v26, v12
	v_pk_mul_f32 v[14:15], v[14:15], 0.5 op_sel_hi:[1,0]
	v_pk_add_f32 v[26:27], v[26:27], 1.0 op_sel_hi:[1,0]
	s_nop 0
	v_div_scale_f32 v12, s[14:15], v27, v27, 2.0
	v_rcp_f32_e32 v29, v12
	s_nop 0
	v_fma_f32 v30, -v12, v29, 1.0
	v_fmac_f32_e32 v29, v30, v29
	v_div_scale_f32 v30, vcc, 2.0, v27, 2.0
	v_mul_f32_e32 v31, v30, v29
	v_fma_f32 v32, -v12, v31, v30
	v_fmac_f32_e32 v31, v32, v29
	v_fma_f32 v12, -v12, v31, v30
	v_div_fmas_f32 v12, v12, v29, v31
	v_div_fixup_f32 v27, v12, v27, 2.0
	v_div_scale_f32 v12, s[14:15], v26, v26, 2.0
	v_rcp_f32_e32 v29, v12
	s_nop 0
	v_fma_f32 v30, -v12, v29, 1.0
	v_fmac_f32_e32 v29, v30, v29
	v_div_scale_f32 v30, vcc, 2.0, v26, 2.0
	v_mul_f32_e32 v31, v30, v29
	v_fma_f32 v32, -v12, v31, v30
	v_fmac_f32_e32 v31, v32, v29
	v_fma_f32 v12, -v12, v31, v30
	v_div_fmas_f32 v12, v12, v29, v31
	v_div_fixup_f32 v26, v12, v26, 2.0
	v_pk_add_f32 v[26:27], v[26:27], 1.0 op_sel_hi:[1,0] neg_lo:[1,0] neg_hi:[1,0]
	s_nop 0
	v_pk_add_f32 v[26:27], v[26:27], 1.0 op_sel_hi:[1,0]
	s_nop 0
	v_pk_mul_f32 v[14:15], v[14:15], v[26:27]
	s_nop 0
	v_pk_mul_f32 v[26:27], v[14:15], v[14:15]
	s_nop 0
	v_add_f32_e32 v12, v27, v28
	v_add_f32_e32 v28, v26, v12
	v_and_b32_e32 v12, 0xffff0000, v13
	v_lshlrev_b32_e32 v13, 16, v13
	v_mul_f32_e32 v26, 0x3d372713, v13
	v_mul_f32_e32 v26, v26, v13
	v_mov_b32_e32 v27, v13
	v_fmac_f32_e32 v27, v26, v27
	v_mul_f32_e32 v26, 0x3f4c422a, v27
	v_add_f32_e32 v26, v26, v26
	v_mul_f32_e32 v26, 0x3fb8aa3b, v26
	v_exp_f32_e32 v27, v26
	v_mul_f32_e32 v26, 0x3d372713, v12
	v_mul_f32_e32 v26, v26, v12
	v_mov_b32_e32 v29, v12
	v_fmac_f32_e32 v29, v26, v29
	v_mul_f32_e32 v26, 0x3f4c422a, v29
	v_add_f32_e32 v26, v26, v26
	v_mul_f32_e32 v26, 0x3fb8aa3b, v26
	v_exp_f32_e32 v26, v26
	v_pk_mul_f32 v[12:13], v[12:13], 0.5 op_sel_hi:[1,0]
	v_pk_add_f32 v[26:27], v[26:27], 1.0 op_sel_hi:[1,0]
	s_nop 0
	v_div_scale_f32 v29, s[14:15], v27, v27, 2.0
	v_rcp_f32_e32 v30, v29
	s_nop 0
	v_fma_f32 v31, -v29, v30, 1.0
	v_fmac_f32_e32 v30, v31, v30
	v_div_scale_f32 v31, vcc, 2.0, v27, 2.0
	v_mul_f32_e32 v32, v31, v30
	v_fma_f32 v33, -v29, v32, v31
	v_fmac_f32_e32 v32, v33, v30
	v_fma_f32 v29, -v29, v32, v31
	v_div_fmas_f32 v29, v29, v30, v32
	v_div_fixup_f32 v27, v29, v27, 2.0
	v_div_scale_f32 v29, s[14:15], v26, v26, 2.0
	v_rcp_f32_e32 v30, v29
	s_nop 0
	v_fma_f32 v31, -v29, v30, 1.0
	v_fmac_f32_e32 v30, v31, v30
	v_div_scale_f32 v31, vcc, 2.0, v26, 2.0
	v_mul_f32_e32 v32, v31, v30
	v_fma_f32 v33, -v29, v32, v31
	v_fmac_f32_e32 v32, v33, v30
	v_fma_f32 v29, -v29, v32, v31
	v_div_fmas_f32 v29, v29, v30, v32
	v_div_fixup_f32 v26, v29, v26, 2.0
	v_pk_add_f32 v[26:27], v[26:27], 1.0 op_sel_hi:[1,0] neg_lo:[1,0] neg_hi:[1,0]
	s_nop 0
	v_pk_add_f32 v[26:27], v[26:27], 1.0 op_sel_hi:[1,0]
	s_nop 0
	v_pk_mul_f32 v[26:27], v[12:13], v[26:27]
	s_nop 0
	v_pk_mul_f32 v[12:13], v[26:27], v[26:27]
	s_nop 0
	v_add_f32_e32 v13, v13, v28
	v_add_f32_e32 v12, v12, v13
	ds_bpermute_b32 v13, v106, v12
	s_waitcnt lgkmcnt(0)
	v_add_f32_e32 v12, v12, v13
	ds_bpermute_b32 v13, v107, v12
	s_waitcnt lgkmcnt(0)
	v_add_f32_e32 v12, v12, v13
	ds_bpermute_b32 v13, v108, v12
	s_waitcnt lgkmcnt(0)
	v_add_f32_e32 v12, v12, v13
	ds_bpermute_b32 v13, v109, v12
	s_waitcnt lgkmcnt(0)
	v_add_f32_e32 v12, v12, v13
	ds_bpermute_b32 v13, v110, v12
	s_waitcnt lgkmcnt(0)
	v_add_f32_e32 v12, v12, v13
	v_fmamk_f32 v12, v12, 0x3b800000, v243
	v_cmp_gt_f32_e32 vcc, s3, v12
	v_mul_f32_e32 v13, 0x4b800000, v12
	s_nop 0
	v_cndmask_b32_e32 v12, v12, v13, vcc
	v_rsq_f32_e32 v12, v12
	s_nop 0
	v_mul_f32_e32 v13, 0x45800000, v12
	v_cndmask_b32_e32 v28, v12, v13, vcc
	v_mul_f32_e32 v12, v20, v28
	v_mul_f32_e32 v13, v21, v28
	v_mul_f32_e32 v10, v10, v28
	v_mul_f32_e32 v12, v70, v12
	v_mul_f32_e32 v13, v71, v13
	v_mul_f32_e32 v11, v11, v28
	v_mul_f32_e32 v10, v73, v10
	v_cvt_pk_bf16_f32 v12, v12, v13
	v_cvt_pk_bf16_f32 v19, v22, v23
	v_mul_f32_e32 v11, v72, v11
	v_cvt_pk_bf16_f32 v13, v11, v10
	v_mul_f32_e32 v10, v15, v28
	v_mul_f32_e32 v10, v66, v10
	v_mul_f32_e32 v11, v14, v28
	v_cvt_pk_bf16_f32 v20, v24, v16
	v_mul_f32_e32 v11, v67, v11
	v_cvt_pk_bf16_f32 v14, v10, v11
	v_mul_f32_e32 v10, v27, v28
	v_mul_f32_e32 v10, v68, v10
	v_mul_f32_e32 v11, v26, v28
	v_cvt_pk_bf16_f32 v21, v25, v17
	v_mul_f32_e32 v11, v69, v11
	v_cvt_pk_bf16_f32 v15, v10, v11
	v_lshlrev_b32_e32 v10, 16, v6
	v_mul_f32_e32 v11, 0x3d372713, v10
	v_mul_f32_e32 v11, v11, v10
	v_fma_f32 v11, v11, v10, v10
	v_mul_f32_e32 v11, 0x3f4c422a, v11
	v_add_f32_e32 v11, v11, v11
	v_mul_f32_e32 v11, 0x3fb8aa3b, v11
	v_exp_f32_e32 v11, v11
	ds_write_b128 v111, v[18:21] offset:52224
	ds_write_b128 v112, v[12:15] offset:52224
	v_mul_f32_e32 v10, 0.5, v10
	v_and_b32_e32 v6, 0xffff0000, v6
	v_add_f32_e32 v11, 1.0, v11
	v_div_scale_f32 v12, s[14:15], v11, v11, 2.0
	v_rcp_f32_e32 v13, v12
	s_nop 0
	v_fma_f32 v14, -v12, v13, 1.0
	v_fmac_f32_e32 v13, v14, v13
	v_div_scale_f32 v14, vcc, 2.0, v11, 2.0
	v_mul_f32_e32 v15, v14, v13
	v_fma_f32 v16, -v12, v15, v14
	v_fmac_f32_e32 v15, v16, v13
	v_fma_f32 v12, -v12, v15, v14
	v_div_fmas_f32 v12, v12, v13, v15
	v_div_fixup_f32 v11, v12, v11, 2.0
	v_sub_f32_e32 v11, 1.0, v11
	v_add_f32_e32 v11, 1.0, v11
	v_mul_f32_e32 v10, v10, v11
	v_mul_f32_e32 v11, 0x3d372713, v6
	v_mul_f32_e32 v11, v11, v6
	v_fma_f32 v11, v11, v6, v6
	v_mul_f32_e32 v11, 0x3f4c422a, v11
	v_add_f32_e32 v11, v11, v11
	v_mul_f32_e32 v11, 0x3fb8aa3b, v11
	v_exp_f32_e32 v11, v11
	v_mul_f32_e32 v6, 0.5, v6
	v_add_f32_e32 v11, 1.0, v11
	v_div_scale_f32 v12, s[14:15], v11, v11, 2.0
	v_rcp_f32_e32 v13, v12
	s_nop 0
	v_fma_f32 v14, -v12, v13, 1.0
	v_fmac_f32_e32 v13, v14, v13
	v_div_scale_f32 v14, vcc, 2.0, v11, 2.0
	v_mul_f32_e32 v15, v14, v13
	v_fma_f32 v16, -v12, v15, v14
	v_fmac_f32_e32 v15, v16, v13
	v_fma_f32 v12, -v12, v15, v14
	v_div_fmas_f32 v12, v12, v13, v15
	v_div_fixup_f32 v11, v12, v11, 2.0
	v_sub_f32_e32 v11, 1.0, v11
	v_add_f32_e32 v11, 1.0, v11
	v_mul_f32_e32 v11, v6, v11
	v_lshlrev_b32_e32 v6, 16, v2
	v_mul_f32_e32 v12, 0x3d372713, v6
	v_mul_f32_e32 v12, v12, v6
	v_fma_f32 v12, v12, v6, v6
	v_mul_f32_e32 v12, 0x3f4c422a, v12
	v_add_f32_e32 v12, v12, v12
	v_mul_f32_e32 v12, 0x3fb8aa3b, v12
	v_exp_f32_e32 v12, v12
	v_mul_f32_e32 v6, 0.5, v6
	v_and_b32_e32 v2, 0xffff0000, v2
	v_cvt_pk_bf16_f32 v10, v10, v11
	v_add_f32_e32 v12, 1.0, v12
	v_div_scale_f32 v13, s[14:15], v12, v12, 2.0
	v_rcp_f32_e32 v14, v13
	s_nop 0
	v_fma_f32 v15, -v13, v14, 1.0
	v_fmac_f32_e32 v14, v15, v14
	v_div_scale_f32 v15, vcc, 2.0, v12, 2.0
	v_mul_f32_e32 v16, v15, v14
	v_fma_f32 v17, -v13, v16, v15
	v_fmac_f32_e32 v16, v17, v14
	v_fma_f32 v13, -v13, v16, v15
	v_div_fmas_f32 v13, v13, v14, v16
	v_div_fixup_f32 v12, v13, v12, 2.0
	v_sub_f32_e32 v12, 1.0, v12
	v_add_f32_e32 v12, 1.0, v12
	v_mul_f32_e32 v12, v6, v12
	v_mul_f32_e32 v6, 0x3d372713, v2
	v_mul_f32_e32 v6, v6, v2
	v_fma_f32 v6, v6, v2, v2
	v_mul_f32_e32 v6, 0x3f4c422a, v6
	v_add_f32_e32 v6, v6, v6
	v_mul_f32_e32 v6, 0x3fb8aa3b, v6
	v_exp_f32_e32 v6, v6
	v_mul_f32_e32 v2, 0.5, v2
	v_add_f32_e32 v6, 1.0, v6
	v_div_scale_f32 v13, s[14:15], v6, v6, 2.0
	v_rcp_f32_e32 v14, v13
	s_nop 0
	v_fma_f32 v15, -v13, v14, 1.0
	v_fmac_f32_e32 v14, v15, v14
	v_div_scale_f32 v15, vcc, 2.0, v6, 2.0
	v_mul_f32_e32 v16, v15, v14
	v_fma_f32 v17, -v13, v16, v15
	v_fmac_f32_e32 v16, v17, v14
	v_fma_f32 v13, -v13, v16, v15
	v_div_fmas_f32 v13, v13, v14, v16
	v_div_fixup_f32 v6, v13, v6, 2.0
	v_sub_f32_e32 v6, 1.0, v6
	v_add_f32_e32 v6, 1.0, v6
	v_mul_f32_e32 v13, v2, v6
	v_lshlrev_b32_e32 v2, 16, v7
	v_mul_f32_e32 v6, 0x3d372713, v2
	v_mul_f32_e32 v6, v6, v2
	v_fma_f32 v6, v6, v2, v2
	v_mul_f32_e32 v6, 0x3f4c422a, v6
	v_add_f32_e32 v6, v6, v6
	v_mul_f32_e32 v6, 0x3fb8aa3b, v6
	v_exp_f32_e32 v6, v6
	v_mul_f32_e32 v2, 0.5, v2
	v_add_f32_e32 v6, 1.0, v6
	v_div_scale_f32 v14, s[14:15], v6, v6, 2.0
	v_rcp_f32_e32 v15, v14
	s_nop 0
	v_fma_f32 v16, -v14, v15, 1.0
	v_fmac_f32_e32 v15, v16, v15
	v_div_scale_f32 v16, vcc, 2.0, v6, 2.0
	v_mul_f32_e32 v17, v16, v15
	v_fma_f32 v18, -v14, v17, v16
	v_fmac_f32_e32 v17, v18, v15
	v_fma_f32 v14, -v14, v17, v16
	v_div_fmas_f32 v14, v14, v15, v17
	v_div_fixup_f32 v6, v14, v6, 2.0
	v_sub_f32_e32 v6, 1.0, v6
	v_add_f32_e32 v6, 1.0, v6
	v_mul_f32_e32 v14, v2, v6
	v_and_b32_e32 v2, 0xffff0000, v7
	v_mul_f32_e32 v6, 0x3d372713, v2
	v_mul_f32_e32 v6, v6, v2
	v_fma_f32 v6, v6, v2, v2
	v_mul_f32_e32 v6, 0x3f4c422a, v6
	v_add_f32_e32 v6, v6, v6
	v_mul_f32_e32 v6, 0x3fb8aa3b, v6
	v_exp_f32_e32 v6, v6
	v_mul_f32_e32 v2, 0.5, v2
	v_add_f32_e32 v6, 1.0, v6
	v_div_scale_f32 v7, s[14:15], v6, v6, 2.0
	v_rcp_f32_e32 v15, v7
	s_nop 0
	v_fma_f32 v16, -v7, v15, 1.0
	v_fmac_f32_e32 v15, v16, v15
	v_div_scale_f32 v16, vcc, 2.0, v6, 2.0
	v_mul_f32_e32 v17, v16, v15
	v_fma_f32 v18, -v7, v17, v16
	v_fmac_f32_e32 v17, v18, v15
	v_fma_f32 v7, -v7, v17, v16
	v_div_fmas_f32 v7, v7, v15, v17
	v_div_fixup_f32 v6, v7, v6, 2.0
	v_sub_f32_e32 v6, 1.0, v6
	v_add_f32_e32 v6, 1.0, v6
	v_mul_f32_e32 v15, v2, v6
	v_lshlrev_b32_e32 v2, 16, v8
	v_mul_f32_e32 v6, 0x3d372713, v2
	v_mul_f32_e32 v6, v6, v2
	v_fma_f32 v6, v6, v2, v2
	v_mul_f32_e32 v6, 0x3f4c422a, v6
	v_add_f32_e32 v6, v6, v6
	v_mul_f32_e32 v6, 0x3fb8aa3b, v6
	v_exp_f32_e32 v6, v6
	v_mul_f32_e32 v2, 0.5, v2
	v_add_f32_e32 v6, 1.0, v6
	v_div_scale_f32 v7, s[14:15], v6, v6, 2.0
	v_rcp_f32_e32 v16, v7
	s_nop 0
	v_fma_f32 v17, -v7, v16, 1.0
	v_fmac_f32_e32 v16, v17, v16
	v_div_scale_f32 v17, vcc, 2.0, v6, 2.0
	v_mul_f32_e32 v18, v17, v16
	v_fma_f32 v19, -v7, v18, v17
	v_fmac_f32_e32 v18, v19, v16
	v_fma_f32 v7, -v7, v18, v17
	v_div_fmas_f32 v7, v7, v16, v18
	v_div_fixup_f32 v6, v7, v6, 2.0
	v_sub_f32_e32 v6, 1.0, v6
	v_add_f32_e32 v6, 1.0, v6
	v_mul_f32_e32 v16, v2, v6
	v_and_b32_e32 v2, 0xffff0000, v8
	v_mul_f32_e32 v6, 0x3d372713, v2
	v_mul_f32_e32 v6, v6, v2
	v_fma_f32 v6, v6, v2, v2
	v_mul_f32_e32 v6, 0x3f4c422a, v6
	v_add_f32_e32 v6, v6, v6
	v_mul_f32_e32 v6, 0x3fb8aa3b, v6
	v_exp_f32_e32 v6, v6
	v_mul_f32_e32 v2, 0.5, v2
	v_add_f32_e32 v6, 1.0, v6
	v_div_scale_f32 v7, s[14:15], v6, v6, 2.0
	v_rcp_f32_e32 v8, v7
	s_nop 0
	v_fma_f32 v17, -v7, v8, 1.0
	v_fmac_f32_e32 v8, v17, v8
	v_div_scale_f32 v17, vcc, 2.0, v6, 2.0
	v_mul_f32_e32 v18, v17, v8
	v_fma_f32 v19, -v7, v18, v17
	v_fmac_f32_e32 v18, v19, v8
	v_fma_f32 v7, -v7, v18, v17
	v_div_fmas_f32 v7, v7, v8, v18
	v_div_fixup_f32 v6, v7, v6, 2.0
	v_sub_f32_e32 v6, 1.0, v6
	v_add_f32_e32 v6, 1.0, v6
	v_mul_f32_e32 v8, v2, v6
	v_lshlrev_b32_e32 v2, 16, v9
	v_mul_f32_e32 v6, 0x3d372713, v2
	v_mul_f32_e32 v6, v6, v2
	v_fma_f32 v6, v6, v2, v2
	v_mul_f32_e32 v6, 0x3f4c422a, v6
	v_add_f32_e32 v6, v6, v6
	v_mul_f32_e32 v6, 0x3fb8aa3b, v6
	v_exp_f32_e32 v6, v6
	v_mul_f32_e32 v2, 0.5, v2
	v_add_f32_e32 v6, 1.0, v6
	v_div_scale_f32 v7, s[14:15], v6, v6, 2.0
	v_rcp_f32_e32 v17, v7
	s_nop 0
	v_fma_f32 v18, -v7, v17, 1.0
	v_fmac_f32_e32 v17, v18, v17
	v_div_scale_f32 v18, vcc, 2.0, v6, 2.0
	v_mul_f32_e32 v19, v18, v17
	v_fma_f32 v20, -v7, v19, v18
	v_fmac_f32_e32 v19, v20, v17
	v_fma_f32 v7, -v7, v19, v18
	v_div_fmas_f32 v7, v7, v17, v19
	v_div_fixup_f32 v6, v7, v6, 2.0
	v_sub_f32_e32 v6, 1.0, v6
	v_add_f32_e32 v6, 1.0, v6
	v_mul_f32_e32 v17, v2, v6
	v_and_b32_e32 v2, 0xffff0000, v9
	v_mul_f32_e32 v6, 0x3d372713, v2
	v_mul_f32_e32 v6, v6, v2
	v_fma_f32 v6, v6, v2, v2
	v_mul_f32_e32 v6, 0x3f4c422a, v6
	v_add_f32_e32 v6, v6, v6
	v_mul_f32_e32 v6, 0x3fb8aa3b, v6
	v_exp_f32_e32 v6, v6
	v_mul_f32_e32 v2, 0.5, v2
	v_add_f32_e32 v6, 1.0, v6
	v_div_scale_f32 v7, s[14:15], v6, v6, 2.0
	v_rcp_f32_e32 v9, v7
	s_nop 0
	v_fma_f32 v18, -v7, v9, 1.0
	v_fmac_f32_e32 v9, v18, v9
	v_div_scale_f32 v18, vcc, 2.0, v6, 2.0
	v_mul_f32_e32 v19, v18, v9
	v_fma_f32 v20, -v7, v19, v18
	v_fmac_f32_e32 v19, v20, v9
	v_fma_f32 v7, -v7, v19, v18
	v_div_fmas_f32 v7, v7, v9, v19
	v_div_fixup_f32 v6, v7, v6, 2.0
	v_sub_f32_e32 v6, 1.0, v6
	v_add_f32_e32 v6, 1.0, v6
	v_mul_f32_e32 v9, v2, v6
	v_and_b32_e32 v2, 0xffff0000, v3
	v_lshlrev_b32_e32 v3, 16, v3
	v_mul_f32_e32 v6, 0x3d372713, v3
	v_mul_f32_e32 v6, v6, v3
	v_mov_b32_e32 v7, v3
	v_fmac_f32_e32 v7, v6, v7
	v_mul_f32_e32 v6, 0x3f4c422a, v7
	v_add_f32_e32 v6, v6, v6
	v_mul_f32_e32 v6, 0x3fb8aa3b, v6
	v_exp_f32_e32 v7, v6
	v_mul_f32_e32 v6, 0x3d372713, v2
	v_mul_f32_e32 v6, v6, v2
	v_mov_b32_e32 v19, v2
	v_fmac_f32_e32 v19, v6, v19
	v_mul_f32_e32 v6, 0x3f4c422a, v19
	v_add_f32_e32 v6, v6, v6
	v_mul_f32_e32 v6, 0x3fb8aa3b, v6
	v_exp_f32_e32 v6, v6
	v_pk_mul_f32 v[2:3], v[2:3], 0.5 op_sel_hi:[1,0]
	v_mul_f32_e32 v18, v13, v13
	v_fmac_f32_e32 v18, v12, v12
	v_pk_add_f32 v[6:7], v[6:7], 1.0 op_sel_hi:[1,0]
	s_nop 0
	v_div_scale_f32 v19, s[14:15], v7, v7, 2.0
	v_rcp_f32_e32 v20, v19
	s_nop 0
	v_fma_f32 v21, -v19, v20, 1.0
	v_fmac_f32_e32 v20, v21, v20
	v_div_scale_f32 v21, vcc, 2.0, v7, 2.0
	v_mul_f32_e32 v22, v21, v20
	v_fma_f32 v23, -v19, v22, v21
	v_fmac_f32_e32 v22, v23, v20
	v_fma_f32 v19, -v19, v22, v21
	v_div_fmas_f32 v19, v19, v20, v22
	v_div_fixup_f32 v7, v19, v7, 2.0
	v_div_scale_f32 v19, s[14:15], v6, v6, 2.0
	v_rcp_f32_e32 v20, v19
	s_nop 0
	v_fma_f32 v21, -v19, v20, 1.0
	v_fmac_f32_e32 v20, v21, v20
	v_div_scale_f32 v21, vcc, 2.0, v6, 2.0
	v_mul_f32_e32 v22, v21, v20
	v_fma_f32 v23, -v19, v22, v21
	v_fmac_f32_e32 v22, v23, v20
	v_fma_f32 v19, -v19, v22, v21
	v_div_fmas_f32 v19, v19, v20, v22
	v_div_fixup_f32 v6, v19, v6, 2.0
	v_pk_add_f32 v[6:7], v[6:7], 1.0 op_sel_hi:[1,0] neg_lo:[1,0] neg_hi:[1,0]
	s_nop 0
	v_pk_add_f32 v[6:7], v[6:7], 1.0 op_sel_hi:[1,0]
	s_nop 0
	v_pk_mul_f32 v[2:3], v[2:3], v[6:7]
	s_nop 0
	v_pk_mul_f32 v[6:7], v[2:3], v[2:3]
	s_nop 0
	v_add_f32_e32 v7, v7, v18
	v_add_f32_e32 v20, v6, v7
	v_lshlrev_b32_e32 v7, 16, v4
	v_and_b32_e32 v6, 0xffff0000, v4
	v_mul_f32_e32 v4, 0x3d372713, v7
	v_mul_f32_e32 v4, v4, v7
	v_mov_b32_e32 v18, v7
	v_fmac_f32_e32 v18, v4, v18
	v_mul_f32_e32 v4, 0x3f4c422a, v18
	v_add_f32_e32 v4, v4, v4
	v_mul_f32_e32 v4, 0x3fb8aa3b, v4
	v_exp_f32_e32 v19, v4
	v_mul_f32_e32 v4, 0x3d372713, v6
	v_mul_f32_e32 v4, v4, v6
	v_mov_b32_e32 v18, v6
	v_fmac_f32_e32 v18, v4, v18
	v_mul_f32_e32 v4, 0x3f4c422a, v18
	v_add_f32_e32 v4, v4, v4
	v_mul_f32_e32 v4, 0x3fb8aa3b, v4
	v_exp_f32_e32 v18, v4
	v_pk_mul_f32 v[6:7], v[6:7], 0.5 op_sel_hi:[1,0]
	v_pk_add_f32 v[18:19], v[18:19], 1.0 op_sel_hi:[1,0]
	s_nop 0
	v_div_scale_f32 v4, s[14:15], v19, v19, 2.0
	v_rcp_f32_e32 v21, v4
	s_nop 0
	v_fma_f32 v22, -v4, v21, 1.0
	v_fmac_f32_e32 v21, v22, v21
	v_div_scale_f32 v22, vcc, 2.0, v19, 2.0
	v_mul_f32_e32 v23, v22, v21
	v_fma_f32 v24, -v4, v23, v22
	v_fmac_f32_e32 v23, v24, v21
	v_fma_f32 v4, -v4, v23, v22
	v_div_fmas_f32 v4, v4, v21, v23
	v_div_fixup_f32 v19, v4, v19, 2.0
	v_div_scale_f32 v4, s[14:15], v18, v18, 2.0
	v_rcp_f32_e32 v21, v4
	s_nop 0
	v_fma_f32 v22, -v4, v21, 1.0
	v_fmac_f32_e32 v21, v22, v21
	v_div_scale_f32 v22, vcc, 2.0, v18, 2.0
	v_mul_f32_e32 v23, v22, v21
	v_fma_f32 v24, -v4, v23, v22
	v_fmac_f32_e32 v23, v24, v21
	v_fma_f32 v4, -v4, v23, v22
	v_div_fmas_f32 v4, v4, v21, v23
	v_div_fixup_f32 v18, v4, v18, 2.0
	v_pk_add_f32 v[18:19], v[18:19], 1.0 op_sel_hi:[1,0] neg_lo:[1,0] neg_hi:[1,0]
	s_nop 0
	v_pk_add_f32 v[18:19], v[18:19], 1.0 op_sel_hi:[1,0]
	s_nop 0
	v_pk_mul_f32 v[6:7], v[6:7], v[18:19]
	s_nop 0
	v_pk_mul_f32 v[18:19], v[6:7], v[6:7]
	s_nop 0
	v_add_f32_e32 v4, v19, v20
	v_add_f32_e32 v20, v18, v4
	v_and_b32_e32 v4, 0xffff0000, v5
	v_lshlrev_b32_e32 v5, 16, v5
	v_mul_f32_e32 v18, 0x3d372713, v5
	v_mul_f32_e32 v18, v18, v5
	v_mov_b32_e32 v19, v5
	v_fmac_f32_e32 v19, v18, v19
	v_mul_f32_e32 v18, 0x3f4c422a, v19
	v_add_f32_e32 v18, v18, v18
	v_mul_f32_e32 v18, 0x3fb8aa3b, v18
	v_exp_f32_e32 v19, v18
	v_mul_f32_e32 v18, 0x3d372713, v4
	v_mul_f32_e32 v18, v18, v4
	v_mov_b32_e32 v21, v4
	v_fmac_f32_e32 v21, v18, v21
	v_mul_f32_e32 v18, 0x3f4c422a, v21
	v_add_f32_e32 v18, v18, v18
	v_mul_f32_e32 v18, 0x3fb8aa3b, v18
	v_exp_f32_e32 v18, v18
	v_pk_mul_f32 v[4:5], v[4:5], 0.5 op_sel_hi:[1,0]
	v_pk_add_f32 v[18:19], v[18:19], 1.0 op_sel_hi:[1,0]
	s_nop 0
	v_div_scale_f32 v21, s[14:15], v19, v19, 2.0
	v_rcp_f32_e32 v22, v21
	s_nop 0
	v_fma_f32 v23, -v21, v22, 1.0
	v_fmac_f32_e32 v22, v23, v22
	v_div_scale_f32 v23, vcc, 2.0, v19, 2.0
	v_mul_f32_e32 v24, v23, v22
	v_fma_f32 v25, -v21, v24, v23
	v_fmac_f32_e32 v24, v25, v22
	v_fma_f32 v21, -v21, v24, v23
	v_div_fmas_f32 v21, v21, v22, v24
	v_div_fixup_f32 v19, v21, v19, 2.0
	v_div_scale_f32 v21, s[14:15], v18, v18, 2.0
	v_rcp_f32_e32 v22, v21
	s_nop 0
	v_fma_f32 v23, -v21, v22, 1.0
	v_fmac_f32_e32 v22, v23, v22
	v_div_scale_f32 v23, vcc, 2.0, v18, 2.0
	v_mul_f32_e32 v24, v23, v22
	v_fma_f32 v25, -v21, v24, v23
	v_fmac_f32_e32 v24, v25, v22
	v_fma_f32 v21, -v21, v24, v23
	v_div_fmas_f32 v21, v21, v22, v24
	v_div_fixup_f32 v18, v21, v18, 2.0
	v_pk_add_f32 v[18:19], v[18:19], 1.0 op_sel_hi:[1,0] neg_lo:[1,0] neg_hi:[1,0]
	s_nop 0
	v_pk_add_f32 v[18:19], v[18:19], 1.0 op_sel_hi:[1,0]
	s_nop 0
	v_pk_mul_f32 v[18:19], v[4:5], v[18:19]
	s_nop 0
	v_pk_mul_f32 v[4:5], v[18:19], v[18:19]
	s_nop 0
	v_add_f32_e32 v5, v5, v20
	v_add_f32_e32 v4, v4, v5
	ds_bpermute_b32 v5, v106, v4
	s_waitcnt lgkmcnt(0)
	v_add_f32_e32 v4, v4, v5
	ds_bpermute_b32 v5, v107, v4
	s_waitcnt lgkmcnt(0)
	v_add_f32_e32 v4, v4, v5
	ds_bpermute_b32 v5, v108, v4
	s_waitcnt lgkmcnt(0)
	v_add_f32_e32 v4, v4, v5
	ds_bpermute_b32 v5, v109, v4
	s_waitcnt lgkmcnt(0)
	v_add_f32_e32 v4, v4, v5
	ds_bpermute_b32 v5, v110, v4
	s_waitcnt lgkmcnt(0)
	v_add_f32_e32 v4, v4, v5
	v_fmamk_f32 v4, v4, 0x3b800000, v243
	v_cmp_gt_f32_e32 vcc, s3, v4
	v_mul_f32_e32 v5, 0x4b800000, v4
	s_nop 0
	v_cndmask_b32_e32 v4, v4, v5, vcc
	v_rsq_f32_e32 v4, v4
	s_nop 0
	v_mul_f32_e32 v5, 0x45800000, v4
	v_cndmask_b32_e32 v20, v4, v5, vcc
	v_mul_f32_e32 v4, v12, v20
	v_mul_f32_e32 v5, v13, v20
	v_mul_f32_e32 v2, v2, v20
	v_mul_f32_e32 v4, v70, v4
	v_mul_f32_e32 v5, v71, v5
	v_mul_f32_e32 v3, v3, v20
	v_mul_f32_e32 v2, v73, v2
	v_cvt_pk_bf16_f32 v4, v4, v5
	v_cvt_pk_bf16_f32 v11, v14, v15
	v_mul_f32_e32 v3, v72, v3
	v_cvt_pk_bf16_f32 v5, v3, v2
	v_mul_f32_e32 v2, v7, v20
	v_mul_f32_e32 v2, v66, v2
	v_mul_f32_e32 v3, v6, v20
	v_cvt_pk_bf16_f32 v12, v16, v8
	v_mul_f32_e32 v3, v67, v3
	v_cvt_pk_bf16_f32 v6, v2, v3
	v_mul_f32_e32 v2, v19, v20
	v_mul_f32_e32 v2, v68, v2
	v_mul_f32_e32 v3, v18, v20
	v_cvt_pk_bf16_f32 v13, v17, v9
	v_mul_f32_e32 v3, v69, v3
	v_cvt_pk_bf16_f32 v7, v2, v3
	v_lshl_add_u64 v[200:201], v[98:99], 0, v[0:1]
	v_lshl_add_u64 v[202:203], v[100:101], 0, v[0:1]
	v_lshl_add_u64 v[200:201], s[4:5], 0, v[200:201]
	v_lshl_add_u64 v[202:203], s[4:5], 0, v[202:203]
	global_load_dwordx4 v[136:139], v[200:201], off
	global_load_dwordx4 v[140:143], v[202:203], off
	global_load_dwordx4 v[144:147], v[200:201], off offset:32
	global_load_dwordx4 v[148:151], v[202:203], off offset:32
	global_load_dwordx4 v[152:155], v[200:201], off offset:64
	global_load_dwordx4 v[156:159], v[202:203], off offset:64
	global_load_dwordx4 v[160:163], v[200:201], off offset:96
	global_load_dwordx4 v[164:167], v[202:203], off offset:96
	global_load_dwordx4 v[168:171], v[200:201], off offset:128
	global_load_dwordx4 v[172:175], v[202:203], off offset:128
	global_load_dwordx4 v[176:179], v[200:201], off offset:160
	global_load_dwordx4 v[180:183], v[202:203], off offset:160
	global_load_dwordx4 v[184:187], v[200:201], off offset:192
	global_load_dwordx4 v[188:191], v[202:203], off offset:192
	global_load_dwordx4 v[192:195], v[200:201], off offset:224
	global_load_dwordx4 v[196:199], v[202:203], off offset:224
	v_mov_b32_e32 v2, 0
	ds_write_b128 v111, v[10:13] offset:60928
	ds_write_b128 v112, v[4:7] offset:60928
	v_mov_b32_e32 v3, v2
	v_mov_b32_e32 v4, v2
	v_mov_b32_e32 v5, v2
	v_mov_b32_e32 v6, v2
	v_mov_b32_e32 v7, v2
	v_mov_b32_e32 v8, v2
	v_mov_b32_e32 v9, v2
	v_mov_b32_e32 v10, v2
	v_mov_b32_e32 v11, v2
	v_mov_b32_e32 v12, v2
	v_mov_b32_e32 v13, v2
	v_mov_b32_e32 v14, v2
	v_mov_b32_e32 v15, v2
	v_mov_b32_e32 v16, v2
	v_mov_b32_e32 v17, v2
	v_mov_b32_e32 v18, v2
	v_mov_b32_e32 v19, v2
	v_mov_b32_e32 v20, v2
	v_mov_b32_e32 v21, v2
	v_mov_b32_e32 v22, v2
	v_mov_b32_e32 v23, v2
	v_mov_b32_e32 v24, v2
	v_mov_b32_e32 v25, v2
	v_mov_b32_e32 v26, v2
	v_mov_b32_e32 v27, v2
	v_mov_b32_e32 v28, v2
	v_mov_b32_e32 v29, v2
	v_mov_b32_e32 v30, v2
	v_mov_b32_e32 v31, v2
	v_mov_b32_e32 v32, v2
	v_mov_b32_e32 v33, v2
	v_mov_b32_e32 v34, v2
	v_mov_b32_e32 v35, v2
	v_mov_b32_e32 v36, v2
	v_mov_b32_e32 v37, v2
	v_mov_b32_e32 v38, v2
	v_mov_b32_e32 v39, v2
	v_mov_b32_e32 v40, v2
	v_mov_b32_e32 v41, v2
	v_mov_b32_e32 v42, v2
	v_mov_b32_e32 v43, v2
	v_mov_b32_e32 v44, v2
	v_mov_b32_e32 v45, v2
	v_mov_b32_e32 v46, v2
	v_mov_b32_e32 v47, v2
	v_mov_b32_e32 v48, v2
	v_mov_b32_e32 v49, v2
	v_mov_b32_e32 v50, v2
	v_mov_b32_e32 v51, v2
	v_mov_b32_e32 v52, v2
	v_mov_b32_e32 v53, v2
	v_mov_b32_e32 v54, v2
	v_mov_b32_e32 v55, v2
	v_mov_b32_e32 v56, v2
	v_mov_b32_e32 v57, v2
	v_mov_b32_e32 v58, v2
	v_mov_b32_e32 v59, v2
	v_mov_b32_e32 v60, v2
	v_mov_b32_e32 v61, v2
	v_mov_b32_e32 v62, v2
	v_mov_b32_e32 v63, v2
	v_mov_b32_e32 v64, v2
	v_mov_b32_e32 v65, v2
	s_waitcnt lgkmcnt(0)
	s_barrier
.LBB0_278:
	s_waitcnt vmcnt(0)
	s_nop 0
	v_add_u32_e32 v115, s5, v114
	v_add_u32_e32 v124, 0x11000, v115
	v_add_u32_e32 v126, 0x11880, v115
	v_add_u32_e32 v128, 0x11040, v115
	v_add_u32_e32 v130, 0x118c0, v115
	ds_read_b64_tr_b16 v[124:125], v124
	ds_read_b64_tr_b16 v[126:127], v126
	ds_read_b64_tr_b16 v[128:129], v128
	ds_read_b64_tr_b16 v[130:131], v130
	s_addk_i32 s5, 0x4400
	s_waitcnt lgkmcnt(2)
	v_mfma_f32_32x32x16_bf16 v[50:65], v[124:127], v[136:139], v[50:65]
	s_waitcnt lgkmcnt(0)
	v_mfma_f32_32x32x16_bf16 v[34:49], v[128:131], v[136:139], v[34:49]
	v_mfma_f32_32x32x16_bf16 v[18:33], v[124:127], v[140:143], v[18:33]
	v_add_u32_e32 v124, 0x13200, v115
	v_add_u32_e32 v126, 0x13a80, v115
	v_mfma_f32_32x32x16_bf16 v[2:17], v[128:131], v[140:143], v[2:17]
	v_add_u32_e32 v128, 0x13240, v115
	ds_read_b64_tr_b16 v[124:125], v124
	ds_read_b64_tr_b16 v[126:127], v126
	v_add_u32_e32 v115, 0x13ac0, v115
	ds_read_b64_tr_b16 v[128:129], v128
	ds_read_b64_tr_b16 v[130:131], v115
	s_waitcnt lgkmcnt(2)
	v_mfma_f32_32x32x16_bf16 v[50:65], v[124:127], v[144:147], v[50:65]
	s_waitcnt lgkmcnt(0)
	v_mfma_f32_32x32x16_bf16 v[34:49], v[128:131], v[144:147], v[34:49]
	v_mfma_f32_32x32x16_bf16 v[18:33], v[124:127], v[148:151], v[18:33]
	v_mfma_f32_32x32x16_bf16 v[2:17], v[128:131], v[148:151], v[2:17]
	s_nop 0
	v_add_u32_e32 v115, s5, v114
	v_add_u32_e32 v124, 0x11000, v115
	v_add_u32_e32 v126, 0x11880, v115
	v_add_u32_e32 v128, 0x11040, v115
	v_add_u32_e32 v130, 0x118c0, v115
	ds_read_b64_tr_b16 v[124:125], v124
	ds_read_b64_tr_b16 v[126:127], v126
	ds_read_b64_tr_b16 v[128:129], v128
	ds_read_b64_tr_b16 v[130:131], v130
	s_addk_i32 s5, 0x4400
	s_waitcnt lgkmcnt(2)
	v_mfma_f32_32x32x16_bf16 v[50:65], v[124:127], v[152:155], v[50:65]
	s_waitcnt lgkmcnt(0)
	v_mfma_f32_32x32x16_bf16 v[34:49], v[128:131], v[152:155], v[34:49]
	v_mfma_f32_32x32x16_bf16 v[18:33], v[124:127], v[156:159], v[18:33]
	v_add_u32_e32 v124, 0x13200, v115
	v_add_u32_e32 v126, 0x13a80, v115
	v_mfma_f32_32x32x16_bf16 v[2:17], v[128:131], v[156:159], v[2:17]
	v_add_u32_e32 v128, 0x13240, v115
	ds_read_b64_tr_b16 v[124:125], v124
	ds_read_b64_tr_b16 v[126:127], v126
	v_add_u32_e32 v115, 0x13ac0, v115
	ds_read_b64_tr_b16 v[128:129], v128
	ds_read_b64_tr_b16 v[130:131], v115
	s_waitcnt lgkmcnt(2)
	v_mfma_f32_32x32x16_bf16 v[50:65], v[124:127], v[160:163], v[50:65]
	s_waitcnt lgkmcnt(0)
	v_mfma_f32_32x32x16_bf16 v[34:49], v[128:131], v[160:163], v[34:49]
	v_mfma_f32_32x32x16_bf16 v[18:33], v[124:127], v[164:167], v[18:33]
	v_mfma_f32_32x32x16_bf16 v[2:17], v[128:131], v[164:167], v[2:17]
	s_nop 0
	v_add_u32_e32 v115, s5, v114
	v_add_u32_e32 v124, 0x11000, v115
	v_add_u32_e32 v126, 0x11880, v115
	v_add_u32_e32 v128, 0x11040, v115
	v_add_u32_e32 v130, 0x118c0, v115
	ds_read_b64_tr_b16 v[124:125], v124
	ds_read_b64_tr_b16 v[126:127], v126
	ds_read_b64_tr_b16 v[128:129], v128
	ds_read_b64_tr_b16 v[130:131], v130
	s_addk_i32 s5, 0x4400
	s_waitcnt lgkmcnt(2)
	v_mfma_f32_32x32x16_bf16 v[50:65], v[124:127], v[168:171], v[50:65]
	s_waitcnt lgkmcnt(0)
	v_mfma_f32_32x32x16_bf16 v[34:49], v[128:131], v[168:171], v[34:49]
	v_mfma_f32_32x32x16_bf16 v[18:33], v[124:127], v[172:175], v[18:33]
	v_add_u32_e32 v124, 0x13200, v115
	v_add_u32_e32 v126, 0x13a80, v115
	v_mfma_f32_32x32x16_bf16 v[2:17], v[128:131], v[172:175], v[2:17]
	v_add_u32_e32 v128, 0x13240, v115
	ds_read_b64_tr_b16 v[124:125], v124
	ds_read_b64_tr_b16 v[126:127], v126
	v_add_u32_e32 v115, 0x13ac0, v115
	ds_read_b64_tr_b16 v[128:129], v128
	ds_read_b64_tr_b16 v[130:131], v115
	s_waitcnt lgkmcnt(2)
	v_mfma_f32_32x32x16_bf16 v[50:65], v[124:127], v[176:179], v[50:65]
	s_waitcnt lgkmcnt(0)
	v_mfma_f32_32x32x16_bf16 v[34:49], v[128:131], v[176:179], v[34:49]
	v_mfma_f32_32x32x16_bf16 v[18:33], v[124:127], v[180:183], v[18:33]
	v_mfma_f32_32x32x16_bf16 v[2:17], v[128:131], v[180:183], v[2:17]
	s_nop 0
	v_add_u32_e32 v115, s5, v114
	v_add_u32_e32 v124, 0x11000, v115
	v_add_u32_e32 v126, 0x11880, v115
	v_add_u32_e32 v128, 0x11040, v115
	v_add_u32_e32 v130, 0x118c0, v115
	ds_read_b64_tr_b16 v[124:125], v124
	ds_read_b64_tr_b16 v[126:127], v126
	ds_read_b64_tr_b16 v[128:129], v128
	ds_read_b64_tr_b16 v[130:131], v130
	s_addk_i32 s5, 0x4400
	s_waitcnt lgkmcnt(2)
	v_mfma_f32_32x32x16_bf16 v[50:65], v[124:127], v[184:187], v[50:65]
	s_waitcnt lgkmcnt(0)
	v_mfma_f32_32x32x16_bf16 v[34:49], v[128:131], v[184:187], v[34:49]
	v_mfma_f32_32x32x16_bf16 v[18:33], v[124:127], v[188:191], v[18:33]
	v_add_u32_e32 v124, 0x13200, v115
	v_add_u32_e32 v126, 0x13a80, v115
	v_mfma_f32_32x32x16_bf16 v[2:17], v[128:131], v[188:191], v[2:17]
	v_add_u32_e32 v128, 0x13240, v115
	ds_read_b64_tr_b16 v[124:125], v124
	ds_read_b64_tr_b16 v[126:127], v126
	v_add_u32_e32 v115, 0x13ac0, v115
	ds_read_b64_tr_b16 v[128:129], v128
	ds_read_b64_tr_b16 v[130:131], v115
	s_waitcnt lgkmcnt(2)
	v_mfma_f32_32x32x16_bf16 v[50:65], v[124:127], v[192:195], v[50:65]
	s_waitcnt lgkmcnt(0)
	v_mfma_f32_32x32x16_bf16 v[34:49], v[128:131], v[192:195], v[34:49]
	v_mfma_f32_32x32x16_bf16 v[18:33], v[124:127], v[196:199], v[18:33]
	v_mfma_f32_32x32x16_bf16 v[2:17], v[128:131], v[196:199], v[2:17]
	global_load_dword v100, v[74:75], off
	ds_read_b64 v[116:117], v113
	v_or_b32_e32 v98, s11, v103
	v_ashrrev_i32_e32 v99, 31, v98
	v_lshlrev_b64 v[98:99], 11, v[98:99]
	v_lshl_add_u64 v[98:99], s[28:29], 0, v[98:99]
	s_waitcnt lgkmcnt(0)
	v_lshlrev_b32_e32 v101, 16, v116
	s_mov_b64 s[14:15], 0xcb00200
	v_lshl_add_u64 v[98:99], v[98:99], 0, s[14:15]
	s_mov_b32 s5, s54
	s_waitcnt vmcnt(0)
	v_add_f32_e32 v50, v50, v100
	v_mul_f32_e32 v50, v50, v101
	v_add_f32_e32 v51, v51, v100
	v_and_b32_e32 v101, 0xffff0000, v116
	v_mul_f32_e32 v51, v51, v101
	v_cvt_pk_bf16_f32 v50, v50, v51
	v_add_f32_e32 v51, v52, v100
	v_lshlrev_b32_e32 v52, 16, v117
	v_mul_f32_e32 v51, v51, v52
	v_add_f32_e32 v52, v53, v100
	v_and_b32_e32 v53, 0xffff0000, v117
	v_mul_f32_e32 v52, v52, v53
	v_cvt_pk_bf16_f32 v51, v51, v52
	v_lshl_add_u64 v[52:53], v[98:99], 0, v[82:83]
	global_store_dwordx2 v[52:53], v[50:51], off
	ds_read_b64 v[50:51], v113 offset:16
	v_add_f32_e32 v52, v54, v100
	v_add_f32_e32 v34, v34, v100
	v_add_f32_e32 v35, v35, v100
	s_waitcnt lgkmcnt(0)
	v_lshlrev_b32_e32 v53, 16, v50
	v_mul_f32_e32 v52, v52, v53
	v_add_f32_e32 v53, v55, v100
	v_and_b32_e32 v50, 0xffff0000, v50
	v_mul_f32_e32 v50, v53, v50
	v_cvt_pk_bf16_f32 v50, v52, v50
	v_add_f32_e32 v52, v56, v100
	v_lshlrev_b32_e32 v53, 16, v51
	v_mul_f32_e32 v52, v52, v53
	v_add_f32_e32 v53, v57, v100
	v_and_b32_e32 v51, 0xffff0000, v51
	v_mul_f32_e32 v51, v53, v51
	v_cvt_pk_bf16_f32 v51, v52, v51
	v_lshl_add_u64 v[52:53], v[98:99], 0, v[84:85]
	global_store_dwordx2 v[52:53], v[50:51], off
	ds_read_b64 v[50:51], v113 offset:32
	v_add_f32_e32 v52, v58, v100
	s_waitcnt lgkmcnt(0)
	v_lshlrev_b32_e32 v53, 16, v50
	v_mul_f32_e32 v52, v52, v53
	v_add_f32_e32 v53, v59, v100
	v_and_b32_e32 v50, 0xffff0000, v50
	v_mul_f32_e32 v50, v53, v50
	v_cvt_pk_bf16_f32 v50, v52, v50
	v_add_f32_e32 v52, v60, v100
	v_lshlrev_b32_e32 v53, 16, v51
	v_mul_f32_e32 v52, v52, v53
	v_add_f32_e32 v53, v61, v100
	v_and_b32_e32 v51, 0xffff0000, v51
	v_mul_f32_e32 v51, v53, v51
	v_cvt_pk_bf16_f32 v51, v52, v51
	v_lshl_add_u64 v[52:53], v[98:99], 0, v[86:87]
	global_store_dwordx2 v[52:53], v[50:51], off
	ds_read_b64 v[50:51], v113 offset:48
	v_add_f32_e32 v52, v62, v100
	s_waitcnt lgkmcnt(0)
	v_lshlrev_b32_e32 v53, 16, v50
	v_mul_f32_e32 v52, v52, v53
	v_add_f32_e32 v53, v63, v100
	v_and_b32_e32 v50, 0xffff0000, v50
	v_mul_f32_e32 v50, v53, v50
	v_cvt_pk_bf16_f32 v50, v52, v50
	v_add_f32_e32 v52, v64, v100
	v_lshlrev_b32_e32 v53, 16, v51
	v_mul_f32_e32 v52, v52, v53
	v_add_f32_e32 v53, v65, v100
	v_and_b32_e32 v51, 0xffff0000, v51
	v_mul_f32_e32 v51, v53, v51
	v_cvt_pk_bf16_f32 v51, v52, v51
	v_lshl_add_u64 v[52:53], v[98:99], 0, v[88:89]
	global_store_dwordx2 v[52:53], v[50:51], off
	ds_read_b64 v[50:51], v113 offset:64
	s_waitcnt lgkmcnt(0)
	v_lshlrev_b32_e32 v52, 16, v50
	v_and_b32_e32 v50, 0xffff0000, v50
	v_mul_f32_e32 v34, v34, v52
	v_mul_f32_e32 v35, v35, v50
	v_cvt_pk_bf16_f32 v34, v34, v35
	v_add_f32_e32 v35, v36, v100
	v_lshlrev_b32_e32 v36, 16, v51
	v_mul_f32_e32 v35, v35, v36
	v_add_f32_e32 v36, v37, v100
	v_and_b32_e32 v37, 0xffff0000, v51
	v_mul_f32_e32 v36, v36, v37
	v_cvt_pk_bf16_f32 v35, v35, v36
	v_lshl_add_u64 v[36:37], v[98:99], 0, v[90:91]
	global_store_dwordx2 v[36:37], v[34:35], off
	ds_read_b64 v[34:35], v113 offset:80
	v_add_f32_e32 v36, v38, v100
	s_waitcnt lgkmcnt(0)
	v_lshlrev_b32_e32 v37, 16, v34
	v_mul_f32_e32 v36, v36, v37
	v_add_f32_e32 v37, v39, v100
	v_and_b32_e32 v34, 0xffff0000, v34
	v_mul_f32_e32 v34, v37, v34
	v_cvt_pk_bf16_f32 v34, v36, v34
	v_add_f32_e32 v36, v40, v100
	v_lshlrev_b32_e32 v37, 16, v35
	v_mul_f32_e32 v36, v36, v37
	v_add_f32_e32 v37, v41, v100
	v_and_b32_e32 v35, 0xffff0000, v35
	v_mul_f32_e32 v35, v37, v35
	v_cvt_pk_bf16_f32 v35, v36, v35
	v_lshl_add_u64 v[36:37], v[98:99], 0, v[92:93]
	global_store_dwordx2 v[36:37], v[34:35], off
	ds_read_b64 v[34:35], v113 offset:96
	v_add_f32_e32 v36, v42, v100
	s_waitcnt lgkmcnt(0)
	v_lshlrev_b32_e32 v37, 16, v34
	v_mul_f32_e32 v36, v36, v37
	v_add_f32_e32 v37, v43, v100
	v_and_b32_e32 v34, 0xffff0000, v34
	v_mul_f32_e32 v34, v37, v34
	v_cvt_pk_bf16_f32 v34, v36, v34
	v_add_f32_e32 v36, v44, v100
	v_lshlrev_b32_e32 v37, 16, v35
	v_mul_f32_e32 v36, v36, v37
	v_add_f32_e32 v37, v45, v100
	v_and_b32_e32 v35, 0xffff0000, v35
	v_mul_f32_e32 v35, v37, v35
	v_cvt_pk_bf16_f32 v35, v36, v35
	v_lshl_add_u64 v[36:37], v[98:99], 0, v[94:95]
	global_store_dwordx2 v[36:37], v[34:35], off
	ds_read_b64 v[34:35], v113 offset:112
	v_add_f32_e32 v36, v46, v100
	s_waitcnt lgkmcnt(0)
	v_lshlrev_b32_e32 v37, 16, v34
	v_mul_f32_e32 v36, v36, v37
	v_add_f32_e32 v37, v47, v100
	v_and_b32_e32 v34, 0xffff0000, v34
	v_mul_f32_e32 v34, v37, v34
	v_cvt_pk_bf16_f32 v34, v36, v34
	v_add_f32_e32 v36, v48, v100
	v_lshlrev_b32_e32 v37, 16, v35
	v_mul_f32_e32 v36, v36, v37
	v_add_f32_e32 v37, v49, v100
	v_and_b32_e32 v35, 0xffff0000, v35
	v_mul_f32_e32 v35, v37, v35
	v_cvt_pk_bf16_f32 v35, v36, v35
	v_lshl_add_u64 v[36:37], v[98:99], 0, v[96:97]
	global_store_dwordx2 v[36:37], v[34:35], off
	global_load_dword v36, v[74:75], off offset:128
	ds_read_b64 v[38:39], v105
	v_or_b32_e32 v34, s11, v104
	v_ashrrev_i32_e32 v35, 31, v34
	v_lshlrev_b64 v[34:35], 11, v[34:35]
	v_lshl_add_u64 v[34:35], s[28:29], 0, v[34:35]
	s_waitcnt lgkmcnt(0)
	v_lshlrev_b32_e32 v37, 16, v38
	v_lshl_add_u64 v[34:35], v[34:35], 0, s[14:15]
	s_waitcnt vmcnt(0)
	v_add_f32_e32 v18, v18, v36
	v_mul_f32_e32 v18, v18, v37
	v_add_f32_e32 v19, v19, v36
	v_and_b32_e32 v37, 0xffff0000, v38
	v_mul_f32_e32 v19, v19, v37
	v_cvt_pk_bf16_f32 v18, v18, v19
	v_add_f32_e32 v19, v20, v36
	v_lshlrev_b32_e32 v20, 16, v39
	v_mul_f32_e32 v19, v19, v20
	v_add_f32_e32 v20, v21, v36
	v_and_b32_e32 v21, 0xffff0000, v39
	v_mul_f32_e32 v20, v20, v21
	v_cvt_pk_bf16_f32 v19, v19, v20
	v_lshl_add_u64 v[20:21], v[34:35], 0, v[82:83]
	global_store_dwordx2 v[20:21], v[18:19], off
	ds_read_b64 v[18:19], v105 offset:16
	v_add_f32_e32 v20, v22, v36
	v_add_f32_e32 v2, v2, v36
	v_add_f32_e32 v3, v3, v36
	s_waitcnt lgkmcnt(0)
	v_lshlrev_b32_e32 v21, 16, v18
	v_mul_f32_e32 v20, v20, v21
	v_add_f32_e32 v21, v23, v36
	v_and_b32_e32 v18, 0xffff0000, v18
	v_mul_f32_e32 v18, v21, v18
	v_cvt_pk_bf16_f32 v18, v20, v18
	v_add_f32_e32 v20, v24, v36
	v_lshlrev_b32_e32 v21, 16, v19
	v_mul_f32_e32 v20, v20, v21
	v_add_f32_e32 v21, v25, v36
	v_and_b32_e32 v19, 0xffff0000, v19
	v_mul_f32_e32 v19, v21, v19
	v_cvt_pk_bf16_f32 v19, v20, v19
	v_lshl_add_u64 v[20:21], v[34:35], 0, v[84:85]
	global_store_dwordx2 v[20:21], v[18:19], off
	ds_read_b64 v[18:19], v105 offset:32
	v_add_f32_e32 v20, v26, v36
	s_waitcnt lgkmcnt(0)
	v_lshlrev_b32_e32 v21, 16, v18
	v_mul_f32_e32 v20, v20, v21
	v_add_f32_e32 v21, v27, v36
	v_and_b32_e32 v18, 0xffff0000, v18
	v_mul_f32_e32 v18, v21, v18
	v_cvt_pk_bf16_f32 v18, v20, v18
	v_add_f32_e32 v20, v28, v36
	v_lshlrev_b32_e32 v21, 16, v19
	v_mul_f32_e32 v20, v20, v21
	v_add_f32_e32 v21, v29, v36
	v_and_b32_e32 v19, 0xffff0000, v19
	v_mul_f32_e32 v19, v21, v19
	v_cvt_pk_bf16_f32 v19, v20, v19
	v_lshl_add_u64 v[20:21], v[34:35], 0, v[86:87]
	global_store_dwordx2 v[20:21], v[18:19], off
	ds_read_b64 v[18:19], v105 offset:48
	v_add_f32_e32 v20, v30, v36
	s_waitcnt lgkmcnt(0)
	v_lshlrev_b32_e32 v21, 16, v18
	v_mul_f32_e32 v20, v20, v21
	v_add_f32_e32 v21, v31, v36
	v_and_b32_e32 v18, 0xffff0000, v18
	v_mul_f32_e32 v18, v21, v18
	v_cvt_pk_bf16_f32 v18, v20, v18
	v_add_f32_e32 v20, v32, v36
	v_lshlrev_b32_e32 v21, 16, v19
	v_mul_f32_e32 v20, v20, v21
	v_add_f32_e32 v21, v33, v36
	v_and_b32_e32 v19, 0xffff0000, v19
	v_mul_f32_e32 v19, v21, v19
	v_cvt_pk_bf16_f32 v19, v20, v19
	v_lshl_add_u64 v[20:21], v[34:35], 0, v[88:89]
	global_store_dwordx2 v[20:21], v[18:19], off
	ds_read_b64 v[18:19], v105 offset:64
	s_waitcnt lgkmcnt(0)
	v_lshlrev_b32_e32 v20, 16, v18
	v_and_b32_e32 v18, 0xffff0000, v18
	v_mul_f32_e32 v2, v2, v20
	v_mul_f32_e32 v3, v3, v18
	v_cvt_pk_bf16_f32 v2, v2, v3
	v_add_f32_e32 v3, v4, v36
	v_lshlrev_b32_e32 v4, 16, v19
	v_mul_f32_e32 v3, v3, v4
	v_add_f32_e32 v4, v5, v36
	v_and_b32_e32 v5, 0xffff0000, v19
	v_mul_f32_e32 v4, v4, v5
	v_cvt_pk_bf16_f32 v3, v3, v4
	v_lshl_add_u64 v[4:5], v[34:35], 0, v[90:91]
	global_store_dwordx2 v[4:5], v[2:3], off
	ds_read_b64 v[2:3], v105 offset:80
	v_add_f32_e32 v4, v6, v36
	s_waitcnt lgkmcnt(0)
	v_lshlrev_b32_e32 v5, 16, v2
	v_mul_f32_e32 v4, v4, v5
	v_add_f32_e32 v5, v7, v36
	v_and_b32_e32 v2, 0xffff0000, v2
	v_mul_f32_e32 v2, v5, v2
	v_cvt_pk_bf16_f32 v2, v4, v2
	v_add_f32_e32 v4, v8, v36
	v_lshlrev_b32_e32 v5, 16, v3
	v_mul_f32_e32 v4, v4, v5
	v_add_f32_e32 v5, v9, v36
	v_and_b32_e32 v3, 0xffff0000, v3
	v_mul_f32_e32 v3, v5, v3
	v_cvt_pk_bf16_f32 v3, v4, v3
	v_lshl_add_u64 v[4:5], v[34:35], 0, v[92:93]
	global_store_dwordx2 v[4:5], v[2:3], off
	ds_read_b64 v[2:3], v105 offset:96
	v_add_f32_e32 v4, v10, v36
	s_waitcnt lgkmcnt(0)
	v_lshlrev_b32_e32 v5, 16, v2
	v_mul_f32_e32 v4, v4, v5
	v_add_f32_e32 v5, v11, v36
	v_and_b32_e32 v2, 0xffff0000, v2
	v_mul_f32_e32 v2, v5, v2
	v_cvt_pk_bf16_f32 v2, v4, v2
	v_add_f32_e32 v4, v12, v36
	v_lshlrev_b32_e32 v5, 16, v3
	v_mul_f32_e32 v4, v4, v5
	v_add_f32_e32 v5, v13, v36
	v_and_b32_e32 v3, 0xffff0000, v3
	v_mul_f32_e32 v3, v5, v3
	v_cvt_pk_bf16_f32 v3, v4, v3
	v_lshl_add_u64 v[4:5], v[34:35], 0, v[94:95]
	global_store_dwordx2 v[4:5], v[2:3], off
	ds_read_b64 v[2:3], v105 offset:112
	v_add_f32_e32 v4, v14, v36
	s_waitcnt lgkmcnt(0)
	v_lshlrev_b32_e32 v5, 16, v2
	v_mul_f32_e32 v4, v4, v5
	v_add_f32_e32 v5, v15, v36
	v_and_b32_e32 v2, 0xffff0000, v2
	v_mul_f32_e32 v2, v5, v2
	v_cvt_pk_bf16_f32 v2, v4, v2
	v_add_f32_e32 v4, v16, v36
	v_lshlrev_b32_e32 v5, 16, v3
	v_mul_f32_e32 v4, v4, v5
	v_add_f32_e32 v5, v17, v36
	v_and_b32_e32 v3, 0xffff0000, v3
	v_mul_f32_e32 v3, v5, v3
	v_cvt_pk_bf16_f32 v3, v4, v3
	v_lshl_add_u64 v[4:5], v[34:35], 0, v[96:97]
	global_store_dwordx2 v[4:5], v[2:3], off
	s_barrier
	s_add_i32 s10, s5, s10
	s_cmpk_lt_i32 s10, 0xc0
	s_cbranch_scc1 .LBB0_277
